# GEMM K-loop headers aligned to 64 B on top of MMA-path cleanup
# speedup vs baseline: 1.0151x; 1.0063x over previous
.LBB0_265:
	s_ashr_i32 s45, s44, 31
	ds_read_b128 v[2:5], v150
	ds_read_b128 v[6:9], v150 offset:1024
	ds_read_b128 v[10:13], v150 offset:2048
	ds_read_b128 v[14:17], v150 offset:3072
	ds_read_b128 v[18:21], v151
	ds_read_b128 v[22:25], v151 offset:1024
	ds_read_b128 v[26:29], v151 offset:2048
	ds_read_b128 v[30:33], v151 offset:3072
	s_lshl_b64 s[46:47], s[44:45], 21
	s_add_u32 s46, s26, s46
	s_addc_u32 s47, s27, s47
	s_and_b64 s[48:49], s[4:5], exec
	s_cselect_b32 s45, s47, s55
	s_cselect_b32 s73, s46, s54
	s_ashr_i32 s43, s42, 31
	s_lshl_b64 s[48:49], s[42:43], 21
	s_add_u32 s48, s24, s48
	s_addc_u32 s49, s25, s49
	s_and_b64 s[56:57], s[4:5], exec
	s_cselect_b32 s43, s49, s53
	s_cselect_b32 s74, s48, s52
	s_add_u32 s56, s54, 0x100080
	s_addc_u32 s57, s55, 0
	s_add_i32 s75, s51, 0xc000
	v_lshl_add_u64 v[66:67], s[56:57], 0, v[130:131]
	s_mov_b32 m0, s75
	s_add_i32 s76, s51, 0xe000
	ds_read_b128 v[34:37], v152
	ds_read_b128 v[38:41], v152 offset:1024
	ds_read_b128 v[42:45], v152 offset:2048
	ds_read_b128 v[46:49], v152 offset:3072
	ds_read_b128 v[50:53], v152 offset:4096
	ds_read_b128 v[54:57], v152 offset:5120
	ds_read_b128 v[58:61], v152 offset:6144
	ds_read_b128 v[62:65], v152 offset:7168
	global_load_lds_dwordx4 v[66:67], off
	v_lshl_add_u64 v[66:67], s[56:57], 0, v[134:135]
	s_mov_b32 m0, s76
	s_nop 0
	global_load_lds_dwordx4 v[66:67], off
	s_waitcnt vmcnt(24)
	s_waitcnt lgkmcnt(0)
	s_setprio 1
	s_barrier
	v_mfma_f32_16x16x32_bf16 v[90:93], v[2:5], v[58:61], 0
	v_mfma_f32_16x16x32_bf16 v[66:69], v[2:5], v[34:37], 0
	v_mfma_f32_16x16x32_bf16 v[70:73], v[10:13], v[34:37], 0
	v_mfma_f32_16x16x32_bf16 v[74:77], v[2:5], v[42:45], 0
	v_mfma_f32_16x16x32_bf16 v[78:81], v[10:13], v[42:45], 0
	v_mfma_f32_16x16x32_bf16 v[82:85], v[2:5], v[50:53], 0
	v_mfma_f32_16x16x32_bf16 v[86:89], v[10:13], v[50:53], 0
	v_mfma_f32_16x16x32_bf16 v[94:97], v[6:9], v[62:65], v[90:93]
	v_mfma_f32_16x16x32_bf16 v[90:93], v[10:13], v[58:61], 0
	v_mfma_f32_16x16x32_bf16 v[66:69], v[6:9], v[38:41], v[66:69]
	v_mfma_f32_16x16x32_bf16 v[126:129], v[14:17], v[38:41], v[70:73]
	v_mfma_f32_16x16x32_bf16 v[74:77], v[6:9], v[46:49], v[74:77]
	v_mfma_f32_16x16x32_bf16 v[78:81], v[14:17], v[46:49], v[78:81]
	v_mfma_f32_16x16x32_bf16 v[82:85], v[6:9], v[54:57], v[82:85]
	v_mfma_f32_16x16x32_bf16 v[86:89], v[14:17], v[54:57], v[86:89]
	v_mfma_f32_16x16x32_bf16 v[102:105], v[14:17], v[62:65], v[90:93]
	v_mfma_f32_16x16x32_bf16 v[90:93], v[18:21], v[34:37], 0
	v_mfma_f32_16x16x32_bf16 v[34:37], v[26:29], v[34:37], 0
	v_mfma_f32_16x16x32_bf16 v[110:113], v[22:25], v[38:41], v[90:93]
	v_mfma_f32_16x16x32_bf16 v[34:37], v[30:33], v[38:41], v[34:37]
	v_mfma_f32_16x16x32_bf16 v[38:41], v[18:21], v[42:45], 0
	v_mfma_f32_16x16x32_bf16 v[42:45], v[26:29], v[42:45], 0
	v_mfma_f32_16x16x32_bf16 v[38:41], v[22:25], v[46:49], v[38:41]
	v_mfma_f32_16x16x32_bf16 v[42:45], v[30:33], v[46:49], v[42:45]
	v_mfma_f32_16x16x32_bf16 v[46:49], v[18:21], v[50:53], 0
	v_mfma_f32_16x16x32_bf16 v[50:53], v[26:29], v[50:53], 0
	v_mfma_f32_16x16x32_bf16 v[46:49], v[22:25], v[54:57], v[46:49]
	v_mfma_f32_16x16x32_bf16 v[54:57], v[30:33], v[54:57], v[50:53]
	v_mfma_f32_16x16x32_bf16 v[50:53], v[18:21], v[58:61], 0
	v_mfma_f32_16x16x32_bf16 v[154:157], v[22:25], v[62:65], v[50:53]
	v_mfma_f32_16x16x32_bf16 v[50:53], v[26:29], v[58:61], 0
	v_mfma_f32_16x16x32_bf16 v[158:161], v[30:33], v[62:65], v[50:53]
	s_setprio 0
	s_barrier
	s_add_i32 s77, s66, s58
	v_lshl_add_u64 v[142:143], s[52:53], 0, v[132:133]
	s_add_i32 s78, s77, 0x2000
	v_lshl_add_u64 v[122:123], v[142:143], 0, s[16:17]
	s_mov_b32 m0, s77
	v_lshl_add_u64 v[144:145], s[52:53], 0, v[136:137]
	s_add_u32 s56, s52, 0x100100
	ds_read_b128 v[50:53], v152 offset:16384
	ds_read_b128 v[58:61], v152 offset:17408
	ds_read_b128 v[62:65], v152 offset:18432
	ds_read_b128 v[90:93], v152 offset:19456
	ds_read_b128 v[98:101], v152 offset:20480
	ds_read_b128 v[106:109], v152 offset:21504
	ds_read_b128 v[114:117], v152 offset:22528
	ds_read_b128 v[118:121], v152 offset:23552
	global_load_lds_dwordx4 v[122:123], off
	v_lshl_add_u64 v[122:123], v[144:145], 0, s[16:17]
	s_mov_b32 m0, s78
	s_addc_u32 s57, s53, 0
	s_add_i32 s79, s67, s58
	global_load_lds_dwordx4 v[122:123], off
	v_lshl_add_u64 v[122:123], s[56:57], 0, v[132:133]
	s_mov_b32 m0, s79
	s_add_i32 s80, s79, 0x2000
	global_load_lds_dwordx4 v[122:123], off
	v_lshl_add_u64 v[122:123], s[56:57], 0, v[136:137]
	s_mov_b32 m0, s80
	v_lshl_add_u64 v[148:149], s[54:55], 0, v[130:131]
	global_load_lds_dwordx4 v[122:123], off
	v_lshl_add_u64 v[122:123], v[148:149], 0, s[16:17]
	s_mov_b32 m0, s51
	v_lshl_add_u64 v[70:71], s[54:55], 0, v[134:135]
	global_load_lds_dwordx4 v[122:123], off
	v_lshl_add_u64 v[72:73], v[70:71], 0, s[16:17]
	s_mov_b32 m0, s59
	s_nop 0
	global_load_lds_dwordx4 v[72:73], off
	s_waitcnt vmcnt(24)
	s_waitcnt lgkmcnt(0)
	s_setprio 1
	s_barrier
	v_mfma_f32_16x16x32_bf16 v[122:125], v[2:5], v[50:53], 0
	v_mfma_f32_16x16x32_bf16 v[162:165], v[6:9], v[58:61], v[122:125]
	v_mfma_f32_16x16x32_bf16 v[122:125], v[10:13], v[50:53], 0
	v_mfma_f32_16x16x32_bf16 v[166:169], v[14:17], v[58:61], v[122:125]
	v_mfma_f32_16x16x32_bf16 v[122:125], v[2:5], v[62:65], 0
	v_mfma_f32_16x16x32_bf16 v[170:173], v[6:9], v[90:93], v[122:125]
	v_mfma_f32_16x16x32_bf16 v[122:125], v[10:13], v[62:65], 0
	v_mfma_f32_16x16x32_bf16 v[174:177], v[14:17], v[90:93], v[122:125]
	v_mfma_f32_16x16x32_bf16 v[122:125], v[2:5], v[98:101], 0
	v_mfma_f32_16x16x32_bf16 v[2:5], v[2:5], v[114:117], 0
	v_mfma_f32_16x16x32_bf16 v[178:181], v[6:9], v[106:109], v[122:125]
	v_mfma_f32_16x16x32_bf16 v[2:5], v[6:9], v[118:121], v[2:5]
	v_mfma_f32_16x16x32_bf16 v[6:9], v[10:13], v[114:117], 0
	v_mfma_f32_16x16x32_bf16 v[122:125], v[10:13], v[98:101], 0
	v_mfma_f32_16x16x32_bf16 v[6:9], v[14:17], v[118:121], v[6:9]
	v_mfma_f32_16x16x32_bf16 v[182:185], v[14:17], v[106:109], v[122:125]
	v_mfma_f32_16x16x32_bf16 v[14:17], v[26:29], v[50:53], 0
	v_mfma_f32_16x16x32_bf16 v[186:189], v[30:33], v[58:61], v[14:17]
	v_mfma_f32_16x16x32_bf16 v[14:17], v[18:21], v[62:65], 0
	v_mfma_f32_16x16x32_bf16 v[190:193], v[22:25], v[90:93], v[14:17]
	v_mfma_f32_16x16x32_bf16 v[14:17], v[26:29], v[62:65], 0
	v_mfma_f32_16x16x32_bf16 v[194:197], v[30:33], v[90:93], v[14:17]
	v_mfma_f32_16x16x32_bf16 v[14:17], v[18:21], v[98:101], 0
	v_mfma_f32_16x16x32_bf16 v[198:201], v[22:25], v[106:109], v[14:17]
	v_mfma_f32_16x16x32_bf16 v[14:17], v[26:29], v[98:101], 0
	v_mfma_f32_16x16x32_bf16 v[10:13], v[18:21], v[50:53], 0
	v_mfma_f32_16x16x32_bf16 v[202:205], v[30:33], v[106:109], v[14:17]
	v_mfma_f32_16x16x32_bf16 v[14:17], v[18:21], v[114:117], 0
	v_mfma_f32_16x16x32_bf16 v[10:13], v[22:25], v[58:61], v[10:13]
	v_mfma_f32_16x16x32_bf16 v[206:209], v[22:25], v[118:121], v[14:17]
	v_mfma_f32_16x16x32_bf16 v[14:17], v[26:29], v[114:117], 0
	v_mfma_f32_16x16x32_bf16 v[210:213], v[30:33], v[118:121], v[14:17]
	s_setprio 0
	s_barrier
	s_add_i32 s81, 0, 0x18000
	s_add_i32 s83, 0, 0x1c000
	v_add_u32_e32 v146, s81, v153
	v_add_u32_e32 v147, s83, v153
	s_nop 0
	ds_read_b128 v[14:17], v146
	ds_read_b128 v[18:21], v146 offset:1024
	ds_read_b128 v[26:29], v146 offset:2048
	ds_read_b128 v[214:217], v146 offset:3072
	ds_read_b128 v[218:221], v147
	ds_read_b128 v[222:225], v147 offset:1024
	ds_read_b128 v[226:229], v147 offset:2048
	ds_read_b128 v[230:233], v147 offset:3072
	s_add_u32 s56, s54, 0x100100
	s_addc_u32 s57, s55, 0
	s_mov_b32 m0, s60
	v_lshl_add_u64 v[50:51], s[56:57], 0, v[130:131]
	ds_read_b128 v[22:25], v152 offset:32768
	ds_read_b128 v[30:33], v152 offset:33792
	ds_read_b128 v[62:65], v152 offset:34816
	ds_read_b128 v[234:237], v152 offset:35840
	ds_read_b128 v[238:241], v152 offset:36864
	ds_read_b128 v[242:245], v152 offset:37888
	ds_read_b128 v[246:249], v152 offset:38912
	ds_read_b128 v[250:253], v152 offset:39936
	global_load_lds_dwordx4 v[50:51], off
	v_lshl_add_u64 v[50:51], s[56:57], 0, v[134:135]
	s_mov_b32 m0, s61
	s_nop 0
	global_load_lds_dwordx4 v[50:51], off
	s_waitcnt vmcnt(8)
	s_waitcnt lgkmcnt(0)
	s_setprio 1
	s_barrier
	v_mfma_f32_16x16x32_bf16 v[50:53], v[14:17], v[22:25], v[66:69]
	v_mfma_f32_16x16x32_bf16 v[122:125], v[18:21], v[30:33], v[50:53]
	v_mfma_f32_16x16x32_bf16 v[50:53], v[26:29], v[22:25], v[126:129]
	v_mfma_f32_16x16x32_bf16 v[114:117], v[214:217], v[30:33], v[50:53]
	v_mfma_f32_16x16x32_bf16 v[50:53], v[14:17], v[62:65], v[74:77]
	v_mfma_f32_16x16x32_bf16 v[106:109], v[18:21], v[234:237], v[50:53]
	v_mfma_f32_16x16x32_bf16 v[50:53], v[26:29], v[62:65], v[78:81]
	v_mfma_f32_16x16x32_bf16 v[98:101], v[214:217], v[234:237], v[50:53]
	v_mfma_f32_16x16x32_bf16 v[50:53], v[14:17], v[238:241], v[82:85]
	v_mfma_f32_16x16x32_bf16 v[90:93], v[18:21], v[242:245], v[50:53]
	v_mfma_f32_16x16x32_bf16 v[50:53], v[26:29], v[238:241], v[86:89]
	v_mfma_f32_16x16x32_bf16 v[82:85], v[214:217], v[242:245], v[50:53]
	v_mfma_f32_16x16x32_bf16 v[50:53], v[14:17], v[246:249], v[94:97]
	v_mfma_f32_16x16x32_bf16 v[58:61], v[18:21], v[250:253], v[50:53]
	v_mfma_f32_16x16x32_bf16 v[50:53], v[26:29], v[246:249], v[102:105]
	v_mfma_f32_16x16x32_bf16 v[50:53], v[214:217], v[250:253], v[50:53]
	v_mfma_f32_16x16x32_bf16 v[66:69], v[218:221], v[22:25], v[110:113]
	v_mfma_f32_16x16x32_bf16 v[22:25], v[226:229], v[22:25], v[34:37]
	v_mfma_f32_16x16x32_bf16 v[118:121], v[230:233], v[30:33], v[22:25]
	v_mfma_f32_16x16x32_bf16 v[22:25], v[218:221], v[62:65], v[38:41]
	v_mfma_f32_16x16x32_bf16 v[110:113], v[222:225], v[234:237], v[22:25]
	v_mfma_f32_16x16x32_bf16 v[22:25], v[226:229], v[62:65], v[42:45]
	v_mfma_f32_16x16x32_bf16 v[102:105], v[230:233], v[234:237], v[22:25]
	v_mfma_f32_16x16x32_bf16 v[22:25], v[218:221], v[238:241], v[46:49]
	v_mfma_f32_16x16x32_bf16 v[94:97], v[222:225], v[242:245], v[22:25]
	v_mfma_f32_16x16x32_bf16 v[22:25], v[226:229], v[238:241], v[54:57]
	v_mfma_f32_16x16x32_bf16 v[86:89], v[230:233], v[242:245], v[22:25]
	v_mfma_f32_16x16x32_bf16 v[22:25], v[218:221], v[246:249], v[154:157]
	v_mfma_f32_16x16x32_bf16 v[62:65], v[222:225], v[250:253], v[22:25]
	v_mfma_f32_16x16x32_bf16 v[22:25], v[226:229], v[246:249], v[158:161]
	v_mfma_f32_16x16x32_bf16 v[126:129], v[222:225], v[30:33], v[66:69]
	v_mfma_f32_16x16x32_bf16 v[54:57], v[230:233], v[250:253], v[22:25]
	s_setprio 0
	s_barrier
	s_add_i32 s81, s81, s58
	s_add_i32 s82, s81, 0x2000
	s_nop 1
	v_lshl_add_u64 v[22:23], v[142:143], 0, s[30:31]
	s_mov_b32 m0, s81
	s_add_u32 s56, s52, 0x100180
	ds_read_b128 v[34:37], v152 offset:49152
	ds_read_b128 v[42:45], v152 offset:50176
	ds_read_b128 v[154:157], v152 offset:51200
	ds_read_b128 v[158:161], v152 offset:52224
	ds_read_b128 v[234:237], v152 offset:53248
	ds_read_b128 v[238:241], v152 offset:54272
	ds_read_b128 v[242:245], v152 offset:55296
	ds_read_b128 v[246:249], v152 offset:56320
	global_load_lds_dwordx4 v[22:23], off
	v_lshl_add_u64 v[22:23], v[144:145], 0, s[30:31]
	s_mov_b32 m0, s82
	s_addc_u32 s57, s53, 0
	s_add_i32 s83, s83, s58
	global_load_lds_dwordx4 v[22:23], off
	v_lshl_add_u64 v[22:23], s[56:57], 0, v[132:133]
	s_mov_b32 m0, s83
	s_add_i32 s84, s83, 0x2000
	global_load_lds_dwordx4 v[22:23], off
	v_lshl_add_u64 v[22:23], s[56:57], 0, v[136:137]
	s_mov_b32 m0, s84
	s_nop 0
	global_load_lds_dwordx4 v[22:23], off
	v_lshl_add_u64 v[22:23], v[148:149], 0, s[30:31]
	s_mov_b32 m0, s63
	s_nop 0
	global_load_lds_dwordx4 v[22:23], off
	v_lshl_add_u64 v[22:23], v[70:71], 0, s[30:31]
	s_mov_b32 m0, s64
	s_nop 0
	global_load_lds_dwordx4 v[22:23], off
	s_waitcnt vmcnt(8)
	s_waitcnt lgkmcnt(0)
	s_setprio 1
	s_barrier
	v_mfma_f32_16x16x32_bf16 v[22:25], v[14:17], v[34:37], v[162:165]
	v_mfma_f32_16x16x32_bf16 v[78:81], v[18:21], v[42:45], v[22:25]
	v_mfma_f32_16x16x32_bf16 v[22:25], v[26:29], v[34:37], v[166:169]
	v_mfma_f32_16x16x32_bf16 v[70:73], v[214:217], v[42:45], v[22:25]
	v_mfma_f32_16x16x32_bf16 v[22:25], v[14:17], v[154:157], v[170:173]
	v_mfma_f32_16x16x32_bf16 v[46:49], v[18:21], v[158:161], v[22:25]
	v_mfma_f32_16x16x32_bf16 v[22:25], v[26:29], v[154:157], v[174:177]
	v_mfma_f32_16x16x32_bf16 v[38:41], v[214:217], v[158:161], v[22:25]
	v_mfma_f32_16x16x32_bf16 v[22:25], v[14:17], v[234:237], v[178:181]
	v_mfma_f32_16x16x32_bf16 v[2:5], v[14:17], v[242:245], v[2:5]
	v_mfma_f32_16x16x32_bf16 v[30:33], v[18:21], v[238:241], v[22:25]
	v_mfma_f32_16x16x32_bf16 v[22:25], v[26:29], v[234:237], v[182:185]
	v_mfma_f32_16x16x32_bf16 v[14:17], v[18:21], v[246:249], v[2:5]
	v_mfma_f32_16x16x32_bf16 v[2:5], v[26:29], v[242:245], v[6:9]
	v_mfma_f32_16x16x32_bf16 v[22:25], v[214:217], v[238:241], v[22:25]
	v_mfma_f32_16x16x32_bf16 v[6:9], v[214:217], v[246:249], v[2:5]
	v_mfma_f32_16x16x32_bf16 v[2:5], v[218:221], v[34:37], v[10:13]
	v_mfma_f32_16x16x32_bf16 v[74:77], v[222:225], v[42:45], v[2:5]
	v_mfma_f32_16x16x32_bf16 v[2:5], v[226:229], v[34:37], v[186:189]
	v_mfma_f32_16x16x32_bf16 v[66:69], v[230:233], v[42:45], v[2:5]
	v_mfma_f32_16x16x32_bf16 v[2:5], v[218:221], v[154:157], v[190:193]
	v_mfma_f32_16x16x32_bf16 v[42:45], v[222:225], v[158:161], v[2:5]
	v_mfma_f32_16x16x32_bf16 v[2:5], v[226:229], v[154:157], v[194:197]
	v_mfma_f32_16x16x32_bf16 v[34:37], v[230:233], v[158:161], v[2:5]
	v_mfma_f32_16x16x32_bf16 v[2:5], v[218:221], v[234:237], v[198:201]
	v_mfma_f32_16x16x32_bf16 v[26:29], v[222:225], v[238:241], v[2:5]
	v_mfma_f32_16x16x32_bf16 v[2:5], v[226:229], v[234:237], v[202:205]
	v_mfma_f32_16x16x32_bf16 v[18:21], v[230:233], v[238:241], v[2:5]
	v_mfma_f32_16x16x32_bf16 v[2:5], v[218:221], v[242:245], v[206:209]
	v_mfma_f32_16x16x32_bf16 v[10:13], v[222:225], v[246:249], v[2:5]
	v_mfma_f32_16x16x32_bf16 v[2:5], v[226:229], v[242:245], v[210:213]
	v_mfma_f32_16x16x32_bf16 v[2:5], v[230:233], v[246:249], v[2:5]
	s_setprio 0
	s_barrier
	s_add_u32 s85, s52, 0x200
	s_addc_u32 s86, s53, 0
	s_add_u32 s52, s54, 0x100180
	s_addc_u32 s53, s55, 0
	s_mov_b32 s87, 0
	.p2align	6

.LBB0_281:
	s_ashr_i32 s49, s48, 31
	ds_read_b128 v[2:5], v188
	ds_read_b128 v[6:9], v188 offset:1024
	ds_read_b128 v[10:13], v188 offset:2048
	ds_read_b128 v[14:17], v188 offset:3072
	ds_read_b128 v[18:21], v189
	ds_read_b128 v[22:25], v189 offset:1024
	ds_read_b128 v[26:29], v189 offset:2048
	ds_read_b128 v[30:33], v189 offset:3072
	s_lshl_b64 s[8:9], s[48:49], 20
	s_add_u32 s50, s20, s8
	s_addc_u32 s51, s21, s9
	s_and_b64 s[8:9], s[4:5], exec
	s_cselect_b32 s49, s51, s59
	s_cselect_b32 s73, s50, s58
	s_ashr_i32 s47, s46, 31
	s_lshl_b64 s[8:9], s[46:47], 20
	s_add_u32 s52, s19, s8
	s_addc_u32 s53, s24, s9
	s_and_b64 s[8:9], s[4:5], exec
	s_cselect_b32 s47, s53, s57
	s_cselect_b32 s74, s52, s56
	s_add_u32 s8, s58, 0x80080
	s_addc_u32 s9, s59, 0
	s_add_i32 s75, s37, 0xc000
	v_lshl_add_u64 v[34:35], s[8:9], 0, v[168:169]
	s_mov_b32 m0, s75
	s_add_i32 s76, s37, 0xe000
	ds_read_b128 v[38:41], v190
	ds_read_b128 v[42:45], v190 offset:1024
	ds_read_b128 v[46:49], v190 offset:2048
	ds_read_b128 v[50:53], v190 offset:3072
	ds_read_b128 v[54:57], v190 offset:4096
	ds_read_b128 v[58:61], v190 offset:5120
	ds_read_b128 v[62:65], v190 offset:6144
	ds_read_b128 v[66:69], v190 offset:7168
	global_load_lds_dwordx4 v[34:35], off
	v_lshl_add_u64 v[34:35], s[8:9], 0, v[164:165]
	s_mov_b32 m0, s76
	s_nop 0
	global_load_lds_dwordx4 v[34:35], off
	s_waitcnt vmcnt(24)
	s_waitcnt lgkmcnt(0)
	s_setprio 1
	s_barrier
	s_mov_b32 s8, 0
	s_mov_b32 s10, s8
	s_mov_b32 s11, s8
	s_mov_b32 s9, s8
	v_mov_b64_e32 v[36:37], s[10:11]
	v_mov_b64_e32 v[160:161], s[10:11]
	v_mov_b64_e32 v[156:157], s[10:11]
	v_mov_b64_e32 v[144:145], s[10:11]
	v_mov_b64_e32 v[140:141], s[10:11]
	v_mov_b64_e32 v[128:129], s[10:11]
	v_mov_b64_e32 v[120:121], s[10:11]
	v_mov_b64_e32 v[92:93], s[10:11]
	v_mov_b64_e32 v[84:85], s[10:11]
	v_mov_b64_e32 v[34:35], s[8:9]
	v_mov_b64_e32 v[158:159], s[8:9]
	v_mov_b64_e32 v[154:155], s[8:9]
	v_mov_b64_e32 v[142:143], s[8:9]
	v_mov_b64_e32 v[138:139], s[8:9]
	v_mov_b64_e32 v[126:127], s[8:9]
	v_mov_b64_e32 v[118:119], s[8:9]
	v_mov_b64_e32 v[90:91], s[8:9]
	v_mov_b64_e32 v[82:83], s[8:9]
	s_waitcnt lgkmcnt(0)
	v_mfma_f32_16x16x128_f8f6f4 v[158:161], v[2:9], v[38:45], v[158:161]
	v_mfma_f32_16x16x128_f8f6f4 v[154:157], v[10:17], v[38:45], v[154:157]
	v_mfma_f32_16x16x128_f8f6f4 v[142:145], v[2:9], v[46:53], v[142:145]
	v_mfma_f32_16x16x128_f8f6f4 v[138:141], v[10:17], v[46:53], v[138:141]
	v_mfma_f32_16x16x128_f8f6f4 v[126:129], v[2:9], v[54:61], v[126:129]
	v_mfma_f32_16x16x128_f8f6f4 v[118:121], v[10:17], v[54:61], v[118:121]
	v_mfma_f32_16x16x128_f8f6f4 v[90:93], v[2:9], v[62:69], v[90:93]
	v_mfma_f32_16x16x128_f8f6f4 v[82:85], v[10:17], v[62:69], v[82:85]
	v_mov_b64_e32 v[152:153], s[10:11]
	v_mov_b64_e32 v[148:149], s[10:11]
	v_mov_b64_e32 v[136:137], s[10:11]
	v_mov_b64_e32 v[132:133], s[10:11]
	v_mov_b64_e32 v[112:113], s[10:11]
	v_mov_b64_e32 v[108:109], s[10:11]
	v_mov_b64_e32 v[80:81], s[10:11]
	v_mov_b64_e32 v[76:77], s[10:11]
	v_mov_b64_e32 v[150:151], s[8:9]
	v_mov_b64_e32 v[146:147], s[8:9]
	v_mov_b64_e32 v[134:135], s[8:9]
	v_mov_b64_e32 v[130:131], s[8:9]
	v_mov_b64_e32 v[110:111], s[8:9]
	v_mov_b64_e32 v[106:107], s[8:9]
	v_mov_b64_e32 v[78:79], s[8:9]
	v_mov_b64_e32 v[74:75], s[8:9]
	v_mfma_f32_16x16x128_f8f6f4 v[150:153], v[18:25], v[38:45], v[150:153]
	v_mfma_f32_16x16x128_f8f6f4 v[146:149], v[26:33], v[38:45], v[146:149]
	v_mfma_f32_16x16x128_f8f6f4 v[134:137], v[18:25], v[46:53], v[134:137]
	v_mfma_f32_16x16x128_f8f6f4 v[130:133], v[26:33], v[46:53], v[130:133]
	v_mfma_f32_16x16x128_f8f6f4 v[110:113], v[18:25], v[54:61], v[110:113]
	v_mfma_f32_16x16x128_f8f6f4 v[106:109], v[26:33], v[54:61], v[106:109]
	v_mfma_f32_16x16x128_f8f6f4 v[78:81], v[18:25], v[62:69], v[78:81]
	v_mfma_f32_16x16x128_f8f6f4 v[74:77], v[26:33], v[62:69], v[74:77]
	s_setprio 0
	s_barrier
	s_add_i32 s9, s66, s25
	v_lshl_add_u64 v[178:179], s[56:57], 0, v[166:167]
	s_add_i32 s77, s9, 0x2000
	v_lshl_add_u64 v[38:39], v[178:179], 0, s[30:31]
	s_mov_b32 m0, s9
	v_lshl_add_u64 v[180:181], s[56:57], 0, v[162:163]
	s_add_u32 s10, s56, 0x80100
	ds_read_b128 v[50:53], v190 offset:16384
	ds_read_b128 v[54:57], v190 offset:17408
	ds_read_b128 v[192:195], v190 offset:18432
	ds_read_b128 v[196:199], v190 offset:19456
	ds_read_b128 v[200:203], v190 offset:20480
	ds_read_b128 v[204:207], v190 offset:21504
	ds_read_b128 v[208:211], v190 offset:22528
	ds_read_b128 v[212:215], v190 offset:23552
	global_load_lds_dwordx4 v[38:39], off
	v_lshl_add_u64 v[38:39], v[180:181], 0, s[30:31]
	s_mov_b32 m0, s77
	s_addc_u32 s11, s57, 0
	s_add_i32 s78, s67, s25
	global_load_lds_dwordx4 v[38:39], off
	v_lshl_add_u64 v[38:39], s[10:11], 0, v[166:167]
	s_mov_b32 m0, s78
	s_add_i32 s79, s78, 0x2000
	global_load_lds_dwordx4 v[38:39], off
	v_lshl_add_u64 v[38:39], s[10:11], 0, v[162:163]
	s_mov_b32 m0, s79
	v_lshl_add_u64 v[182:183], s[58:59], 0, v[168:169]
	global_load_lds_dwordx4 v[38:39], off
	v_lshl_add_u64 v[38:39], v[182:183], 0, s[30:31]
	s_mov_b32 m0, s37
	v_lshl_add_u64 v[184:185], s[58:59], 0, v[164:165]
	global_load_lds_dwordx4 v[38:39], off
	v_lshl_add_u64 v[38:39], v[184:185], 0, s[30:31]
	s_mov_b32 m0, s55
	s_nop 0
	global_load_lds_dwordx4 v[38:39], off
	s_waitcnt vmcnt(24)
	s_waitcnt lgkmcnt(0)
	s_setprio 1
	s_barrier
	v_mov_b64_e32 v[124:125], v[36:37]
	v_mov_b64_e32 v[116:117], v[36:37]
	v_mov_b64_e32 v[96:97], v[36:37]
	v_mov_b64_e32 v[88:89], v[36:37]
	v_mov_b64_e32 v[64:65], v[36:37]
	v_mov_b64_e32 v[60:61], v[36:37]
	v_mov_b64_e32 v[48:49], v[36:37]
	v_mov_b64_e32 v[44:45], v[36:37]
	v_mov_b64_e32 v[122:123], v[34:35]
	v_mov_b64_e32 v[114:115], v[34:35]
	v_mov_b64_e32 v[94:95], v[34:35]
	v_mov_b64_e32 v[86:87], v[34:35]
	v_mov_b64_e32 v[62:63], v[34:35]
	v_mov_b64_e32 v[58:59], v[34:35]
	v_mov_b64_e32 v[46:47], v[34:35]
	v_mov_b64_e32 v[42:43], v[34:35]
	s_waitcnt lgkmcnt(0)
	v_mfma_f32_16x16x128_f8f6f4 v[122:125], v[2:9], v[50:57], v[122:125]
	v_mfma_f32_16x16x128_f8f6f4 v[114:117], v[10:17], v[50:57], v[114:117]
	v_mfma_f32_16x16x128_f8f6f4 v[94:97], v[2:9], v[192:199], v[94:97]
	v_mfma_f32_16x16x128_f8f6f4 v[86:89], v[10:17], v[192:199], v[86:89]
	v_mfma_f32_16x16x128_f8f6f4 v[62:65], v[2:9], v[200:207], v[62:65]
	v_mfma_f32_16x16x128_f8f6f4 v[58:61], v[10:17], v[200:207], v[58:61]
	v_mfma_f32_16x16x128_f8f6f4 v[46:49], v[2:9], v[208:215], v[46:49]
	v_mfma_f32_16x16x128_f8f6f4 v[42:45], v[10:17], v[208:215], v[42:45]
	v_mov_b64_e32 v[104:105], v[36:37]
	v_mov_b64_e32 v[100:101], v[36:37]
	v_mov_b64_e32 v[102:103], v[34:35]
	v_mov_b64_e32 v[98:99], v[34:35]
	v_mfma_f32_16x16x128_f8f6f4 v[102:105], v[18:25], v[50:57], v[102:105]
	v_mfma_f32_16x16x128_f8f6f4 v[98:101], v[26:33], v[50:57], v[98:101]
	v_mov_b64_e32 v[72:73], v[36:37]
	v_mov_b64_e32 v[68:69], v[36:37]
	v_mov_b64_e32 v[56:57], v[36:37]
	v_mov_b64_e32 v[52:53], v[36:37]
	v_mov_b64_e32 v[40:41], v[36:37]
	v_mov_b64_e32 v[70:71], v[34:35]
	v_mov_b64_e32 v[66:67], v[34:35]
	v_mov_b64_e32 v[54:55], v[34:35]
	v_mov_b64_e32 v[50:51], v[34:35]
	v_mov_b64_e32 v[38:39], v[34:35]
	v_mfma_f32_16x16x128_f8f6f4 v[70:73], v[18:25], v[192:199], v[70:73]
	v_mfma_f32_16x16x128_f8f6f4 v[66:69], v[26:33], v[192:199], v[66:69]
	v_mfma_f32_16x16x128_f8f6f4 v[54:57], v[18:25], v[200:207], v[54:57]
	v_mfma_f32_16x16x128_f8f6f4 v[50:53], v[26:33], v[200:207], v[50:53]
	v_mfma_f32_16x16x128_f8f6f4 v[38:41], v[18:25], v[208:215], v[38:41]
	v_mfma_f32_16x16x128_f8f6f4 v[34:37], v[26:33], v[208:215], v[34:37]
	s_setprio 0
	s_barrier
	s_add_i32 s80, 0, 0x18000
	s_add_i32 s82, 0, 0x1c000
	v_add_u32_e32 v191, s80, v186
	v_add_u32_e32 v192, s82, v186
	ds_read_b128 v[18:21], v191
	ds_read_b128 v[22:25], v191 offset:1024
	ds_read_b128 v[26:29], v191 offset:2048
	ds_read_b128 v[30:33], v191 offset:3072
	ds_read_b128 v[2:5], v192
	ds_read_b128 v[6:9], v192 offset:1024
	ds_read_b128 v[10:13], v192 offset:2048
	ds_read_b128 v[14:17], v192 offset:3072
	s_add_u32 s10, s58, 0x80100
	s_addc_u32 s11, s59, 0
	s_mov_b32 m0, s60
	v_lshl_add_u64 v[226:227], s[10:11], 0, v[168:169]
	ds_read_b128 v[194:197], v190 offset:32768
	ds_read_b128 v[198:201], v190 offset:33792
	ds_read_b128 v[202:205], v190 offset:34816
	ds_read_b128 v[206:209], v190 offset:35840
	ds_read_b128 v[210:213], v190 offset:36864
	ds_read_b128 v[214:217], v190 offset:37888
	ds_read_b128 v[218:221], v190 offset:38912
	ds_read_b128 v[222:225], v190 offset:39936
	global_load_lds_dwordx4 v[226:227], off
	v_lshl_add_u64 v[226:227], s[10:11], 0, v[164:165]
	s_mov_b32 m0, s61
	s_nop 0
	global_load_lds_dwordx4 v[226:227], off
	s_waitcnt vmcnt(8)
	s_waitcnt lgkmcnt(0)
	s_setprio 1
	s_barrier
	v_mfma_f32_16x16x128_f8f6f4 v[158:161], v[18:25], v[194:201], v[158:161]
	v_mfma_f32_16x16x128_f8f6f4 v[154:157], v[26:33], v[194:201], v[154:157]
	v_mfma_f32_16x16x128_f8f6f4 v[142:145], v[18:25], v[202:209], v[142:145]
	v_mfma_f32_16x16x128_f8f6f4 v[138:141], v[26:33], v[202:209], v[138:141]
	v_mfma_f32_16x16x128_f8f6f4 v[126:129], v[18:25], v[210:217], v[126:129]
	v_mfma_f32_16x16x128_f8f6f4 v[118:121], v[26:33], v[210:217], v[118:121]
	v_mfma_f32_16x16x128_f8f6f4 v[90:93], v[18:25], v[218:225], v[90:93]
	v_mfma_f32_16x16x128_f8f6f4 v[82:85], v[26:33], v[218:225], v[82:85]
	v_mfma_f32_16x16x128_f8f6f4 v[150:153], v[2:9], v[194:201], v[150:153]
	v_mfma_f32_16x16x128_f8f6f4 v[146:149], v[10:17], v[194:201], v[146:149]
	v_mfma_f32_16x16x128_f8f6f4 v[134:137], v[2:9], v[202:209], v[134:137]
	v_mfma_f32_16x16x128_f8f6f4 v[130:133], v[10:17], v[202:209], v[130:133]
	v_mfma_f32_16x16x128_f8f6f4 v[110:113], v[2:9], v[210:217], v[110:113]
	v_mfma_f32_16x16x128_f8f6f4 v[106:109], v[10:17], v[210:217], v[106:109]
	v_mfma_f32_16x16x128_f8f6f4 v[78:81], v[2:9], v[218:225], v[78:81]
	v_mfma_f32_16x16x128_f8f6f4 v[74:77], v[10:17], v[218:225], v[74:77]
	s_setprio 0
	s_barrier
	s_add_i32 s80, s80, s25
	s_add_i32 s81, s80, 0x2000
	v_lshl_add_u64 v[178:179], v[178:179], 0, s[34:35]
	s_mov_b32 m0, s80
	s_add_u32 s10, s56, 0x80180
	ds_read_b128 v[194:197], v190 offset:49152
	ds_read_b128 v[198:201], v190 offset:50176
	ds_read_b128 v[202:205], v190 offset:51200
	ds_read_b128 v[206:209], v190 offset:52224
	ds_read_b128 v[210:213], v190 offset:53248
	ds_read_b128 v[214:217], v190 offset:54272
	ds_read_b128 v[218:221], v190 offset:55296
	ds_read_b128 v[222:225], v190 offset:56320
	global_load_lds_dwordx4 v[178:179], off
	v_lshl_add_u64 v[178:179], v[180:181], 0, s[34:35]
	s_mov_b32 m0, s81
	s_addc_u32 s11, s57, 0
	s_add_i32 s82, s82, s25
	global_load_lds_dwordx4 v[178:179], off
	v_lshl_add_u64 v[178:179], s[10:11], 0, v[166:167]
	s_mov_b32 m0, s82
	s_add_i32 s83, s82, 0x2000
	global_load_lds_dwordx4 v[178:179], off
	v_lshl_add_u64 v[178:179], s[10:11], 0, v[162:163]
	s_mov_b32 m0, s83
	s_nop 0
	global_load_lds_dwordx4 v[178:179], off
	v_lshl_add_u64 v[178:179], v[182:183], 0, s[34:35]
	s_mov_b32 m0, s63
	s_nop 0
	global_load_lds_dwordx4 v[178:179], off
	v_lshl_add_u64 v[178:179], v[184:185], 0, s[34:35]
	s_mov_b32 m0, s64
	s_nop 0
	global_load_lds_dwordx4 v[178:179], off
	s_waitcnt vmcnt(8)
	s_waitcnt lgkmcnt(0)
	s_setprio 1
	s_barrier
	v_mfma_f32_16x16x128_f8f6f4 v[122:125], v[18:25], v[194:201], v[122:125]
	v_mfma_f32_16x16x128_f8f6f4 v[114:117], v[26:33], v[194:201], v[114:117]
	v_mfma_f32_16x16x128_f8f6f4 v[94:97], v[18:25], v[202:209], v[94:97]
	v_mfma_f32_16x16x128_f8f6f4 v[86:89], v[26:33], v[202:209], v[86:89]
	v_mfma_f32_16x16x128_f8f6f4 v[62:65], v[18:25], v[210:217], v[62:65]
	v_mfma_f32_16x16x128_f8f6f4 v[58:61], v[26:33], v[210:217], v[58:61]
	v_mfma_f32_16x16x128_f8f6f4 v[46:49], v[18:25], v[218:225], v[46:49]
	v_mfma_f32_16x16x128_f8f6f4 v[42:45], v[26:33], v[218:225], v[42:45]
	v_mfma_f32_16x16x128_f8f6f4 v[102:105], v[2:9], v[194:201], v[102:105]
	v_mfma_f32_16x16x128_f8f6f4 v[98:101], v[10:17], v[194:201], v[98:101]
	v_mfma_f32_16x16x128_f8f6f4 v[70:73], v[2:9], v[202:209], v[70:73]
	v_mfma_f32_16x16x128_f8f6f4 v[66:69], v[10:17], v[202:209], v[66:69]
	v_mfma_f32_16x16x128_f8f6f4 v[54:57], v[2:9], v[210:217], v[54:57]
	v_mfma_f32_16x16x128_f8f6f4 v[50:53], v[10:17], v[210:217], v[50:53]
	v_mfma_f32_16x16x128_f8f6f4 v[38:41], v[2:9], v[218:225], v[38:41]
	v_mfma_f32_16x16x128_f8f6f4 v[34:37], v[10:17], v[218:225], v[34:37]
	s_setprio 0
	s_barrier
	s_add_u32 s10, s58, 0x80180
	s_addc_u32 s11, s59, 0
	s_add_u32 s84, s56, 0x200
	s_addc_u32 s85, s57, 0
	.p2align	6

.LBB0_305:
	s_ashr_i32 s45, s44, 31
	ds_read_b128 v[2:5], v150
	ds_read_b128 v[6:9], v150 offset:1024
	ds_read_b128 v[10:13], v150 offset:2048
	ds_read_b128 v[14:17], v150 offset:3072
	ds_read_b128 v[18:21], v151
	ds_read_b128 v[22:25], v151 offset:1024
	ds_read_b128 v[26:29], v151 offset:2048
	ds_read_b128 v[30:33], v151 offset:3072
	s_lshl_b64 s[46:47], s[44:45], 21
	s_add_u32 s46, s24, s46
	s_addc_u32 s47, s25, s47
	s_and_b64 s[48:49], s[4:5], exec
	s_cselect_b32 s45, s47, s55
	s_cselect_b32 s73, s46, s54
	s_ashr_i32 s43, s42, 31
	s_lshl_b64 s[48:49], s[42:43], 21
	s_add_u32 s48, s26, s48
	s_addc_u32 s49, s27, s49
	s_and_b64 s[56:57], s[4:5], exec
	s_cselect_b32 s43, s49, s53
	s_cselect_b32 s74, s48, s52
	s_add_u32 s56, s54, 0x100080
	s_addc_u32 s57, s55, 0
	s_add_i32 s75, s51, 0xc000
	v_lshl_add_u64 v[66:67], s[56:57], 0, v[130:131]
	s_mov_b32 m0, s75
	s_add_i32 s76, s51, 0xe000
	ds_read_b128 v[34:37], v152
	ds_read_b128 v[38:41], v152 offset:1024
	ds_read_b128 v[42:45], v152 offset:2048
	ds_read_b128 v[46:49], v152 offset:3072
	ds_read_b128 v[50:53], v152 offset:4096
	ds_read_b128 v[54:57], v152 offset:5120
	ds_read_b128 v[58:61], v152 offset:6144
	ds_read_b128 v[62:65], v152 offset:7168
	global_load_lds_dwordx4 v[66:67], off
	v_lshl_add_u64 v[66:67], s[56:57], 0, v[134:135]
	s_mov_b32 m0, s76
	s_nop 0
	global_load_lds_dwordx4 v[66:67], off
	s_waitcnt vmcnt(24)
	s_waitcnt lgkmcnt(0)
	s_setprio 1
	s_barrier
	v_mfma_f32_16x16x32_bf16 v[90:93], v[2:5], v[58:61], 0
	v_mfma_f32_16x16x32_bf16 v[66:69], v[2:5], v[34:37], 0
	v_mfma_f32_16x16x32_bf16 v[70:73], v[10:13], v[34:37], 0
	v_mfma_f32_16x16x32_bf16 v[74:77], v[2:5], v[42:45], 0
	v_mfma_f32_16x16x32_bf16 v[78:81], v[10:13], v[42:45], 0
	v_mfma_f32_16x16x32_bf16 v[82:85], v[2:5], v[50:53], 0
	v_mfma_f32_16x16x32_bf16 v[86:89], v[10:13], v[50:53], 0
	v_mfma_f32_16x16x32_bf16 v[94:97], v[6:9], v[62:65], v[90:93]
	v_mfma_f32_16x16x32_bf16 v[90:93], v[10:13], v[58:61], 0
	v_mfma_f32_16x16x32_bf16 v[66:69], v[6:9], v[38:41], v[66:69]
	v_mfma_f32_16x16x32_bf16 v[126:129], v[14:17], v[38:41], v[70:73]
	v_mfma_f32_16x16x32_bf16 v[74:77], v[6:9], v[46:49], v[74:77]
	v_mfma_f32_16x16x32_bf16 v[78:81], v[14:17], v[46:49], v[78:81]
	v_mfma_f32_16x16x32_bf16 v[82:85], v[6:9], v[54:57], v[82:85]
	v_mfma_f32_16x16x32_bf16 v[86:89], v[14:17], v[54:57], v[86:89]
	v_mfma_f32_16x16x32_bf16 v[102:105], v[14:17], v[62:65], v[90:93]
	v_mfma_f32_16x16x32_bf16 v[90:93], v[18:21], v[34:37], 0
	v_mfma_f32_16x16x32_bf16 v[34:37], v[26:29], v[34:37], 0
	v_mfma_f32_16x16x32_bf16 v[110:113], v[22:25], v[38:41], v[90:93]
	v_mfma_f32_16x16x32_bf16 v[34:37], v[30:33], v[38:41], v[34:37]
	v_mfma_f32_16x16x32_bf16 v[38:41], v[18:21], v[42:45], 0
	v_mfma_f32_16x16x32_bf16 v[42:45], v[26:29], v[42:45], 0
	v_mfma_f32_16x16x32_bf16 v[38:41], v[22:25], v[46:49], v[38:41]
	v_mfma_f32_16x16x32_bf16 v[42:45], v[30:33], v[46:49], v[42:45]
	v_mfma_f32_16x16x32_bf16 v[46:49], v[18:21], v[50:53], 0
	v_mfma_f32_16x16x32_bf16 v[50:53], v[26:29], v[50:53], 0
	v_mfma_f32_16x16x32_bf16 v[46:49], v[22:25], v[54:57], v[46:49]
	v_mfma_f32_16x16x32_bf16 v[54:57], v[30:33], v[54:57], v[50:53]
	v_mfma_f32_16x16x32_bf16 v[50:53], v[18:21], v[58:61], 0
	v_mfma_f32_16x16x32_bf16 v[154:157], v[22:25], v[62:65], v[50:53]
	v_mfma_f32_16x16x32_bf16 v[50:53], v[26:29], v[58:61], 0
	v_mfma_f32_16x16x32_bf16 v[158:161], v[30:33], v[62:65], v[50:53]
	s_setprio 0
	s_barrier
	s_add_i32 s77, s66, s58
	v_lshl_add_u64 v[142:143], s[52:53], 0, v[132:133]
	s_add_i32 s78, s77, 0x2000
	v_lshl_add_u64 v[122:123], v[142:143], 0, s[30:31]
	s_mov_b32 m0, s77
	v_lshl_add_u64 v[144:145], s[52:53], 0, v[136:137]
	s_add_u32 s56, s52, 0x100100
	ds_read_b128 v[50:53], v152 offset:16384
	ds_read_b128 v[58:61], v152 offset:17408
	ds_read_b128 v[62:65], v152 offset:18432
	ds_read_b128 v[90:93], v152 offset:19456
	ds_read_b128 v[98:101], v152 offset:20480
	ds_read_b128 v[106:109], v152 offset:21504
	ds_read_b128 v[114:117], v152 offset:22528
	ds_read_b128 v[118:121], v152 offset:23552
	global_load_lds_dwordx4 v[122:123], off
	v_lshl_add_u64 v[122:123], v[144:145], 0, s[30:31]
	s_mov_b32 m0, s78
	s_addc_u32 s57, s53, 0
	s_add_i32 s79, s67, s58
	global_load_lds_dwordx4 v[122:123], off
	v_lshl_add_u64 v[122:123], s[56:57], 0, v[132:133]
	s_mov_b32 m0, s79
	s_add_i32 s80, s79, 0x2000
	global_load_lds_dwordx4 v[122:123], off
	v_lshl_add_u64 v[122:123], s[56:57], 0, v[136:137]
	s_mov_b32 m0, s80
	v_lshl_add_u64 v[148:149], s[54:55], 0, v[130:131]
	global_load_lds_dwordx4 v[122:123], off
	v_lshl_add_u64 v[122:123], v[148:149], 0, s[30:31]
	s_mov_b32 m0, s51
	v_lshl_add_u64 v[70:71], s[54:55], 0, v[134:135]
	global_load_lds_dwordx4 v[122:123], off
	v_lshl_add_u64 v[72:73], v[70:71], 0, s[30:31]
	s_mov_b32 m0, s59
	s_nop 0
	global_load_lds_dwordx4 v[72:73], off
	s_waitcnt vmcnt(24)
	s_waitcnt lgkmcnt(0)
	s_setprio 1
	s_barrier
	v_mfma_f32_16x16x32_bf16 v[122:125], v[2:5], v[50:53], 0
	v_mfma_f32_16x16x32_bf16 v[162:165], v[6:9], v[58:61], v[122:125]
	v_mfma_f32_16x16x32_bf16 v[122:125], v[10:13], v[50:53], 0
	v_mfma_f32_16x16x32_bf16 v[166:169], v[14:17], v[58:61], v[122:125]
	v_mfma_f32_16x16x32_bf16 v[122:125], v[2:5], v[62:65], 0
	v_mfma_f32_16x16x32_bf16 v[170:173], v[6:9], v[90:93], v[122:125]
	v_mfma_f32_16x16x32_bf16 v[122:125], v[10:13], v[62:65], 0
	v_mfma_f32_16x16x32_bf16 v[174:177], v[14:17], v[90:93], v[122:125]
	v_mfma_f32_16x16x32_bf16 v[122:125], v[2:5], v[98:101], 0
	v_mfma_f32_16x16x32_bf16 v[2:5], v[2:5], v[114:117], 0
	v_mfma_f32_16x16x32_bf16 v[178:181], v[6:9], v[106:109], v[122:125]
	v_mfma_f32_16x16x32_bf16 v[2:5], v[6:9], v[118:121], v[2:5]
	v_mfma_f32_16x16x32_bf16 v[6:9], v[10:13], v[114:117], 0
	v_mfma_f32_16x16x32_bf16 v[122:125], v[10:13], v[98:101], 0
	v_mfma_f32_16x16x32_bf16 v[6:9], v[14:17], v[118:121], v[6:9]
	v_mfma_f32_16x16x32_bf16 v[182:185], v[14:17], v[106:109], v[122:125]
	v_mfma_f32_16x16x32_bf16 v[14:17], v[26:29], v[50:53], 0
	v_mfma_f32_16x16x32_bf16 v[186:189], v[30:33], v[58:61], v[14:17]
	v_mfma_f32_16x16x32_bf16 v[14:17], v[18:21], v[62:65], 0
	v_mfma_f32_16x16x32_bf16 v[190:193], v[22:25], v[90:93], v[14:17]
	v_mfma_f32_16x16x32_bf16 v[14:17], v[26:29], v[62:65], 0
	v_mfma_f32_16x16x32_bf16 v[194:197], v[30:33], v[90:93], v[14:17]
	v_mfma_f32_16x16x32_bf16 v[14:17], v[18:21], v[98:101], 0
	v_mfma_f32_16x16x32_bf16 v[198:201], v[22:25], v[106:109], v[14:17]
	v_mfma_f32_16x16x32_bf16 v[14:17], v[26:29], v[98:101], 0
	v_mfma_f32_16x16x32_bf16 v[10:13], v[18:21], v[50:53], 0
	v_mfma_f32_16x16x32_bf16 v[202:205], v[30:33], v[106:109], v[14:17]
	v_mfma_f32_16x16x32_bf16 v[14:17], v[18:21], v[114:117], 0
	v_mfma_f32_16x16x32_bf16 v[10:13], v[22:25], v[58:61], v[10:13]
	v_mfma_f32_16x16x32_bf16 v[206:209], v[22:25], v[118:121], v[14:17]
	v_mfma_f32_16x16x32_bf16 v[14:17], v[26:29], v[114:117], 0
	v_mfma_f32_16x16x32_bf16 v[210:213], v[30:33], v[118:121], v[14:17]
	s_setprio 0
	s_barrier
	s_add_i32 s81, 0, 0x18000
	s_add_i32 s83, 0, 0x1c000
	v_add_u32_e32 v146, s81, v153
	v_add_u32_e32 v147, s83, v153
	s_nop 0
	ds_read_b128 v[14:17], v146
	ds_read_b128 v[18:21], v146 offset:1024
	ds_read_b128 v[26:29], v146 offset:2048
	ds_read_b128 v[214:217], v146 offset:3072
	ds_read_b128 v[218:221], v147
	ds_read_b128 v[222:225], v147 offset:1024
	ds_read_b128 v[226:229], v147 offset:2048
	ds_read_b128 v[230:233], v147 offset:3072
	s_add_u32 s56, s54, 0x100100
	s_addc_u32 s57, s55, 0
	s_mov_b32 m0, s60
	v_lshl_add_u64 v[50:51], s[56:57], 0, v[130:131]
	ds_read_b128 v[22:25], v152 offset:32768
	ds_read_b128 v[30:33], v152 offset:33792
	ds_read_b128 v[62:65], v152 offset:34816
	ds_read_b128 v[234:237], v152 offset:35840
	ds_read_b128 v[238:241], v152 offset:36864
	ds_read_b128 v[242:245], v152 offset:37888
	ds_read_b128 v[246:249], v152 offset:38912
	ds_read_b128 v[250:253], v152 offset:39936
	global_load_lds_dwordx4 v[50:51], off
	v_lshl_add_u64 v[50:51], s[56:57], 0, v[134:135]
	s_mov_b32 m0, s61
	s_nop 0
	global_load_lds_dwordx4 v[50:51], off
	s_waitcnt vmcnt(8)
	s_waitcnt lgkmcnt(0)
	s_setprio 1
	s_barrier
	v_mfma_f32_16x16x32_bf16 v[50:53], v[14:17], v[22:25], v[66:69]
	v_mfma_f32_16x16x32_bf16 v[122:125], v[18:21], v[30:33], v[50:53]
	v_mfma_f32_16x16x32_bf16 v[50:53], v[26:29], v[22:25], v[126:129]
	v_mfma_f32_16x16x32_bf16 v[114:117], v[214:217], v[30:33], v[50:53]
	v_mfma_f32_16x16x32_bf16 v[50:53], v[14:17], v[62:65], v[74:77]
	v_mfma_f32_16x16x32_bf16 v[106:109], v[18:21], v[234:237], v[50:53]
	v_mfma_f32_16x16x32_bf16 v[50:53], v[26:29], v[62:65], v[78:81]
	v_mfma_f32_16x16x32_bf16 v[98:101], v[214:217], v[234:237], v[50:53]
	v_mfma_f32_16x16x32_bf16 v[50:53], v[14:17], v[238:241], v[82:85]
	v_mfma_f32_16x16x32_bf16 v[90:93], v[18:21], v[242:245], v[50:53]
	v_mfma_f32_16x16x32_bf16 v[50:53], v[26:29], v[238:241], v[86:89]
	v_mfma_f32_16x16x32_bf16 v[82:85], v[214:217], v[242:245], v[50:53]
	v_mfma_f32_16x16x32_bf16 v[50:53], v[14:17], v[246:249], v[94:97]
	v_mfma_f32_16x16x32_bf16 v[58:61], v[18:21], v[250:253], v[50:53]
	v_mfma_f32_16x16x32_bf16 v[50:53], v[26:29], v[246:249], v[102:105]
	v_mfma_f32_16x16x32_bf16 v[50:53], v[214:217], v[250:253], v[50:53]
	v_mfma_f32_16x16x32_bf16 v[66:69], v[218:221], v[22:25], v[110:113]
	v_mfma_f32_16x16x32_bf16 v[22:25], v[226:229], v[22:25], v[34:37]
	v_mfma_f32_16x16x32_bf16 v[118:121], v[230:233], v[30:33], v[22:25]
	v_mfma_f32_16x16x32_bf16 v[22:25], v[218:221], v[62:65], v[38:41]
	v_mfma_f32_16x16x32_bf16 v[110:113], v[222:225], v[234:237], v[22:25]
	v_mfma_f32_16x16x32_bf16 v[22:25], v[226:229], v[62:65], v[42:45]
	v_mfma_f32_16x16x32_bf16 v[102:105], v[230:233], v[234:237], v[22:25]
	v_mfma_f32_16x16x32_bf16 v[22:25], v[218:221], v[238:241], v[46:49]
	v_mfma_f32_16x16x32_bf16 v[94:97], v[222:225], v[242:245], v[22:25]
	v_mfma_f32_16x16x32_bf16 v[22:25], v[226:229], v[238:241], v[54:57]
	v_mfma_f32_16x16x32_bf16 v[86:89], v[230:233], v[242:245], v[22:25]
	v_mfma_f32_16x16x32_bf16 v[22:25], v[218:221], v[246:249], v[154:157]
	v_mfma_f32_16x16x32_bf16 v[62:65], v[222:225], v[250:253], v[22:25]
	v_mfma_f32_16x16x32_bf16 v[22:25], v[226:229], v[246:249], v[158:161]
	v_mfma_f32_16x16x32_bf16 v[126:129], v[222:225], v[30:33], v[66:69]
	v_mfma_f32_16x16x32_bf16 v[54:57], v[230:233], v[250:253], v[22:25]
	s_setprio 0
	s_barrier
	s_add_i32 s81, s81, s58
	s_add_i32 s82, s81, 0x2000
	s_nop 1
	v_lshl_add_u64 v[22:23], v[142:143], 0, s[34:35]
	s_mov_b32 m0, s81
	s_add_u32 s56, s52, 0x100180
	ds_read_b128 v[34:37], v152 offset:49152
	ds_read_b128 v[42:45], v152 offset:50176
	ds_read_b128 v[154:157], v152 offset:51200
	ds_read_b128 v[158:161], v152 offset:52224
	ds_read_b128 v[234:237], v152 offset:53248
	ds_read_b128 v[238:241], v152 offset:54272
	ds_read_b128 v[242:245], v152 offset:55296
	ds_read_b128 v[246:249], v152 offset:56320
	global_load_lds_dwordx4 v[22:23], off
	v_lshl_add_u64 v[22:23], v[144:145], 0, s[34:35]
	s_mov_b32 m0, s82
	s_addc_u32 s57, s53, 0
	s_add_i32 s83, s83, s58
	global_load_lds_dwordx4 v[22:23], off
	v_lshl_add_u64 v[22:23], s[56:57], 0, v[132:133]
	s_mov_b32 m0, s83
	s_add_i32 s84, s83, 0x2000
	global_load_lds_dwordx4 v[22:23], off
	v_lshl_add_u64 v[22:23], s[56:57], 0, v[136:137]
	s_mov_b32 m0, s84
	s_nop 0
	global_load_lds_dwordx4 v[22:23], off
	v_lshl_add_u64 v[22:23], v[148:149], 0, s[34:35]
	s_mov_b32 m0, s63
	s_nop 0
	global_load_lds_dwordx4 v[22:23], off
	v_lshl_add_u64 v[22:23], v[70:71], 0, s[34:35]
	s_mov_b32 m0, s64
	s_nop 0
	global_load_lds_dwordx4 v[22:23], off
	s_waitcnt vmcnt(8)
	s_waitcnt lgkmcnt(0)
	s_setprio 1
	s_barrier
	v_mfma_f32_16x16x32_bf16 v[22:25], v[14:17], v[34:37], v[162:165]
	v_mfma_f32_16x16x32_bf16 v[78:81], v[18:21], v[42:45], v[22:25]
	v_mfma_f32_16x16x32_bf16 v[22:25], v[26:29], v[34:37], v[166:169]
	v_mfma_f32_16x16x32_bf16 v[70:73], v[214:217], v[42:45], v[22:25]
	v_mfma_f32_16x16x32_bf16 v[22:25], v[14:17], v[154:157], v[170:173]
	v_mfma_f32_16x16x32_bf16 v[46:49], v[18:21], v[158:161], v[22:25]
	v_mfma_f32_16x16x32_bf16 v[22:25], v[26:29], v[154:157], v[174:177]
	v_mfma_f32_16x16x32_bf16 v[38:41], v[214:217], v[158:161], v[22:25]
	v_mfma_f32_16x16x32_bf16 v[22:25], v[14:17], v[234:237], v[178:181]
	v_mfma_f32_16x16x32_bf16 v[2:5], v[14:17], v[242:245], v[2:5]
	v_mfma_f32_16x16x32_bf16 v[30:33], v[18:21], v[238:241], v[22:25]
	v_mfma_f32_16x16x32_bf16 v[22:25], v[26:29], v[234:237], v[182:185]
	v_mfma_f32_16x16x32_bf16 v[14:17], v[18:21], v[246:249], v[2:5]
	v_mfma_f32_16x16x32_bf16 v[2:5], v[26:29], v[242:245], v[6:9]
	v_mfma_f32_16x16x32_bf16 v[22:25], v[214:217], v[238:241], v[22:25]
	v_mfma_f32_16x16x32_bf16 v[6:9], v[214:217], v[246:249], v[2:5]
	v_mfma_f32_16x16x32_bf16 v[2:5], v[218:221], v[34:37], v[10:13]
	v_mfma_f32_16x16x32_bf16 v[74:77], v[222:225], v[42:45], v[2:5]
	v_mfma_f32_16x16x32_bf16 v[2:5], v[226:229], v[34:37], v[186:189]
	v_mfma_f32_16x16x32_bf16 v[66:69], v[230:233], v[42:45], v[2:5]
	v_mfma_f32_16x16x32_bf16 v[2:5], v[218:221], v[154:157], v[190:193]
	v_mfma_f32_16x16x32_bf16 v[42:45], v[222:225], v[158:161], v[2:5]
	v_mfma_f32_16x16x32_bf16 v[2:5], v[226:229], v[154:157], v[194:197]
	v_mfma_f32_16x16x32_bf16 v[34:37], v[230:233], v[158:161], v[2:5]
	v_mfma_f32_16x16x32_bf16 v[2:5], v[218:221], v[234:237], v[198:201]
	v_mfma_f32_16x16x32_bf16 v[26:29], v[222:225], v[238:241], v[2:5]
	v_mfma_f32_16x16x32_bf16 v[2:5], v[226:229], v[234:237], v[202:205]
	v_mfma_f32_16x16x32_bf16 v[18:21], v[230:233], v[238:241], v[2:5]
	v_mfma_f32_16x16x32_bf16 v[2:5], v[218:221], v[242:245], v[206:209]
	v_mfma_f32_16x16x32_bf16 v[10:13], v[222:225], v[246:249], v[2:5]
	v_mfma_f32_16x16x32_bf16 v[2:5], v[226:229], v[242:245], v[210:213]
	v_mfma_f32_16x16x32_bf16 v[2:5], v[230:233], v[246:249], v[2:5]
	s_setprio 0
	s_barrier
	s_add_u32 s85, s52, 0x200
	s_addc_u32 s86, s53, 0
	s_add_u32 s52, s54, 0x100180
	s_addc_u32 s53, s55, 0
	s_mov_b32 s87, 0
	.p2align	6

.LBB0_746:
	s_ashr_i32 s45, s44, 31
	ds_read_b128 v[2:5], v150
	ds_read_b128 v[6:9], v150 offset:1024
	ds_read_b128 v[10:13], v150 offset:2048
	ds_read_b128 v[14:17], v150 offset:3072
	ds_read_b128 v[18:21], v151
	ds_read_b128 v[22:25], v151 offset:1024
	ds_read_b128 v[26:29], v151 offset:2048
	ds_read_b128 v[30:33], v151 offset:3072
	s_lshl_b64 s[46:47], s[44:45], 20
	s_add_u32 s46, s24, s46
	s_addc_u32 s47, s25, s47
	s_and_b64 s[48:49], s[4:5], exec
	s_cselect_b32 s45, s47, s55
	s_cselect_b32 s75, s46, s54
	s_ashr_i32 s43, s42, 31
	s_lshl_b64 s[48:49], s[42:43], 20
	s_add_u32 s48, s58, s48
	s_addc_u32 s49, s59, s49
	s_and_b64 s[56:57], s[4:5], exec
	s_cselect_b32 s43, s49, s53
	s_cselect_b32 s76, s48, s52
	s_add_u32 s56, s54, 0x80080
	s_addc_u32 s57, s55, 0
	s_add_i32 s77, s51, 0xc000
	v_lshl_add_u64 v[66:67], s[56:57], 0, v[130:131]
	s_mov_b32 m0, s77
	s_add_i32 s78, s51, 0xe000
	ds_read_b128 v[34:37], v152
	ds_read_b128 v[38:41], v152 offset:1024
	ds_read_b128 v[42:45], v152 offset:2048
	ds_read_b128 v[46:49], v152 offset:3072
	ds_read_b128 v[50:53], v152 offset:4096
	ds_read_b128 v[54:57], v152 offset:5120
	ds_read_b128 v[58:61], v152 offset:6144
	ds_read_b128 v[62:65], v152 offset:7168
	global_load_lds_dwordx4 v[66:67], off
	v_lshl_add_u64 v[66:67], s[56:57], 0, v[134:135]
	s_mov_b32 m0, s78
	s_nop 0
	global_load_lds_dwordx4 v[66:67], off
	s_waitcnt vmcnt(24)
	s_waitcnt lgkmcnt(0)
	s_setprio 1
	s_barrier
	v_mfma_f32_16x16x32_bf16 v[90:93], v[2:5], v[58:61], 0
	v_mfma_f32_16x16x32_bf16 v[66:69], v[2:5], v[34:37], 0
	v_mfma_f32_16x16x32_bf16 v[70:73], v[10:13], v[34:37], 0
	v_mfma_f32_16x16x32_bf16 v[74:77], v[2:5], v[42:45], 0
	v_mfma_f32_16x16x32_bf16 v[78:81], v[10:13], v[42:45], 0
	v_mfma_f32_16x16x32_bf16 v[82:85], v[2:5], v[50:53], 0
	v_mfma_f32_16x16x32_bf16 v[86:89], v[10:13], v[50:53], 0
	v_mfma_f32_16x16x32_bf16 v[94:97], v[6:9], v[62:65], v[90:93]
	v_mfma_f32_16x16x32_bf16 v[90:93], v[10:13], v[58:61], 0
	v_mfma_f32_16x16x32_bf16 v[66:69], v[6:9], v[38:41], v[66:69]
	v_mfma_f32_16x16x32_bf16 v[126:129], v[14:17], v[38:41], v[70:73]
	v_mfma_f32_16x16x32_bf16 v[74:77], v[6:9], v[46:49], v[74:77]
	v_mfma_f32_16x16x32_bf16 v[78:81], v[14:17], v[46:49], v[78:81]
	v_mfma_f32_16x16x32_bf16 v[82:85], v[6:9], v[54:57], v[82:85]
	v_mfma_f32_16x16x32_bf16 v[86:89], v[14:17], v[54:57], v[86:89]
	v_mfma_f32_16x16x32_bf16 v[102:105], v[14:17], v[62:65], v[90:93]
	v_mfma_f32_16x16x32_bf16 v[90:93], v[18:21], v[34:37], 0
	v_mfma_f32_16x16x32_bf16 v[34:37], v[26:29], v[34:37], 0
	v_mfma_f32_16x16x32_bf16 v[110:113], v[22:25], v[38:41], v[90:93]
	v_mfma_f32_16x16x32_bf16 v[34:37], v[30:33], v[38:41], v[34:37]
	v_mfma_f32_16x16x32_bf16 v[38:41], v[18:21], v[42:45], 0
	v_mfma_f32_16x16x32_bf16 v[42:45], v[26:29], v[42:45], 0
	v_mfma_f32_16x16x32_bf16 v[38:41], v[22:25], v[46:49], v[38:41]
	v_mfma_f32_16x16x32_bf16 v[42:45], v[30:33], v[46:49], v[42:45]
	v_mfma_f32_16x16x32_bf16 v[46:49], v[18:21], v[50:53], 0
	v_mfma_f32_16x16x32_bf16 v[50:53], v[26:29], v[50:53], 0
	v_mfma_f32_16x16x32_bf16 v[46:49], v[22:25], v[54:57], v[46:49]
	v_mfma_f32_16x16x32_bf16 v[54:57], v[30:33], v[54:57], v[50:53]
	v_mfma_f32_16x16x32_bf16 v[50:53], v[18:21], v[58:61], 0
	v_mfma_f32_16x16x32_bf16 v[154:157], v[22:25], v[62:65], v[50:53]
	v_mfma_f32_16x16x32_bf16 v[50:53], v[26:29], v[58:61], 0
	v_mfma_f32_16x16x32_bf16 v[158:161], v[30:33], v[62:65], v[50:53]
	s_setprio 0
	s_barrier
	s_add_i32 s79, s68, s60
	v_lshl_add_u64 v[142:143], s[52:53], 0, v[132:133]
	s_add_i32 s80, s79, 0x2000
	v_lshl_add_u64 v[122:123], v[142:143], 0, s[16:17]
	s_mov_b32 m0, s79
	v_lshl_add_u64 v[144:145], s[52:53], 0, v[136:137]
	s_add_u32 s56, s52, 0x80100
	ds_read_b128 v[50:53], v152 offset:16384
	ds_read_b128 v[58:61], v152 offset:17408
	ds_read_b128 v[62:65], v152 offset:18432
	ds_read_b128 v[90:93], v152 offset:19456
	ds_read_b128 v[98:101], v152 offset:20480
	ds_read_b128 v[106:109], v152 offset:21504
	ds_read_b128 v[114:117], v152 offset:22528
	ds_read_b128 v[118:121], v152 offset:23552
	global_load_lds_dwordx4 v[122:123], off
	v_lshl_add_u64 v[122:123], v[144:145], 0, s[16:17]
	s_mov_b32 m0, s80
	s_addc_u32 s57, s53, 0
	s_add_i32 s81, s69, s60
	global_load_lds_dwordx4 v[122:123], off
	v_lshl_add_u64 v[122:123], s[56:57], 0, v[132:133]
	s_mov_b32 m0, s81
	s_add_i32 s82, s81, 0x2000
	global_load_lds_dwordx4 v[122:123], off
	v_lshl_add_u64 v[122:123], s[56:57], 0, v[136:137]
	s_mov_b32 m0, s82
	v_lshl_add_u64 v[148:149], s[54:55], 0, v[130:131]
	global_load_lds_dwordx4 v[122:123], off
	v_lshl_add_u64 v[122:123], v[148:149], 0, s[16:17]
	s_mov_b32 m0, s51
	v_lshl_add_u64 v[70:71], s[54:55], 0, v[134:135]
	global_load_lds_dwordx4 v[122:123], off
	v_lshl_add_u64 v[72:73], v[70:71], 0, s[16:17]
	s_mov_b32 m0, s61
	s_nop 0
	global_load_lds_dwordx4 v[72:73], off
	s_waitcnt vmcnt(24)
	s_waitcnt lgkmcnt(0)
	s_setprio 1
	s_barrier
	v_mfma_f32_16x16x32_bf16 v[122:125], v[2:5], v[50:53], 0
	v_mfma_f32_16x16x32_bf16 v[162:165], v[6:9], v[58:61], v[122:125]
	v_mfma_f32_16x16x32_bf16 v[122:125], v[10:13], v[50:53], 0
	v_mfma_f32_16x16x32_bf16 v[166:169], v[14:17], v[58:61], v[122:125]
	v_mfma_f32_16x16x32_bf16 v[122:125], v[2:5], v[62:65], 0
	v_mfma_f32_16x16x32_bf16 v[170:173], v[6:9], v[90:93], v[122:125]
	v_mfma_f32_16x16x32_bf16 v[122:125], v[10:13], v[62:65], 0
	v_mfma_f32_16x16x32_bf16 v[174:177], v[14:17], v[90:93], v[122:125]
	v_mfma_f32_16x16x32_bf16 v[122:125], v[2:5], v[98:101], 0
	v_mfma_f32_16x16x32_bf16 v[2:5], v[2:5], v[114:117], 0
	v_mfma_f32_16x16x32_bf16 v[178:181], v[6:9], v[106:109], v[122:125]
	v_mfma_f32_16x16x32_bf16 v[2:5], v[6:9], v[118:121], v[2:5]
	v_mfma_f32_16x16x32_bf16 v[6:9], v[10:13], v[114:117], 0
	v_mfma_f32_16x16x32_bf16 v[122:125], v[10:13], v[98:101], 0
	v_mfma_f32_16x16x32_bf16 v[6:9], v[14:17], v[118:121], v[6:9]
	v_mfma_f32_16x16x32_bf16 v[182:185], v[14:17], v[106:109], v[122:125]
	v_mfma_f32_16x16x32_bf16 v[14:17], v[26:29], v[50:53], 0
	v_mfma_f32_16x16x32_bf16 v[186:189], v[30:33], v[58:61], v[14:17]
	v_mfma_f32_16x16x32_bf16 v[14:17], v[18:21], v[62:65], 0
	v_mfma_f32_16x16x32_bf16 v[190:193], v[22:25], v[90:93], v[14:17]
	v_mfma_f32_16x16x32_bf16 v[14:17], v[26:29], v[62:65], 0
	v_mfma_f32_16x16x32_bf16 v[194:197], v[30:33], v[90:93], v[14:17]
	v_mfma_f32_16x16x32_bf16 v[14:17], v[18:21], v[98:101], 0
	v_mfma_f32_16x16x32_bf16 v[198:201], v[22:25], v[106:109], v[14:17]
	v_mfma_f32_16x16x32_bf16 v[14:17], v[26:29], v[98:101], 0
	v_mfma_f32_16x16x32_bf16 v[10:13], v[18:21], v[50:53], 0
	v_mfma_f32_16x16x32_bf16 v[202:205], v[30:33], v[106:109], v[14:17]
	v_mfma_f32_16x16x32_bf16 v[14:17], v[18:21], v[114:117], 0
	v_mfma_f32_16x16x32_bf16 v[10:13], v[22:25], v[58:61], v[10:13]
	v_mfma_f32_16x16x32_bf16 v[206:209], v[22:25], v[118:121], v[14:17]
	v_mfma_f32_16x16x32_bf16 v[14:17], v[26:29], v[114:117], 0
	v_mfma_f32_16x16x32_bf16 v[210:213], v[30:33], v[118:121], v[14:17]
	s_setprio 0
	s_barrier
	s_add_i32 s83, 0, 0x18000
	s_add_i32 s85, 0, 0x1c000
	v_add_u32_e32 v146, s83, v153
	v_add_u32_e32 v147, s85, v153
	s_nop 0
	ds_read_b128 v[14:17], v146
	ds_read_b128 v[18:21], v146 offset:1024
	ds_read_b128 v[26:29], v146 offset:2048
	ds_read_b128 v[214:217], v146 offset:3072
	ds_read_b128 v[218:221], v147
	ds_read_b128 v[222:225], v147 offset:1024
	ds_read_b128 v[226:229], v147 offset:2048
	ds_read_b128 v[230:233], v147 offset:3072
	s_add_u32 s56, s54, 0x80100
	s_addc_u32 s57, s55, 0
	s_mov_b32 m0, s62
	v_lshl_add_u64 v[50:51], s[56:57], 0, v[130:131]
	ds_read_b128 v[22:25], v152 offset:32768
	ds_read_b128 v[30:33], v152 offset:33792
	ds_read_b128 v[62:65], v152 offset:34816
	ds_read_b128 v[234:237], v152 offset:35840
	ds_read_b128 v[238:241], v152 offset:36864
	ds_read_b128 v[242:245], v152 offset:37888
	ds_read_b128 v[246:249], v152 offset:38912
	ds_read_b128 v[250:253], v152 offset:39936
	global_load_lds_dwordx4 v[50:51], off
	v_lshl_add_u64 v[50:51], s[56:57], 0, v[134:135]
	s_mov_b32 m0, s63
	s_nop 0
	global_load_lds_dwordx4 v[50:51], off
	s_waitcnt vmcnt(8)
	s_waitcnt lgkmcnt(0)
	s_setprio 1
	s_barrier
	v_mfma_f32_16x16x32_bf16 v[50:53], v[14:17], v[22:25], v[66:69]
	v_mfma_f32_16x16x32_bf16 v[122:125], v[18:21], v[30:33], v[50:53]
	v_mfma_f32_16x16x32_bf16 v[50:53], v[26:29], v[22:25], v[126:129]
	v_mfma_f32_16x16x32_bf16 v[114:117], v[214:217], v[30:33], v[50:53]
	v_mfma_f32_16x16x32_bf16 v[50:53], v[14:17], v[62:65], v[74:77]
	v_mfma_f32_16x16x32_bf16 v[106:109], v[18:21], v[234:237], v[50:53]
	v_mfma_f32_16x16x32_bf16 v[50:53], v[26:29], v[62:65], v[78:81]
	v_mfma_f32_16x16x32_bf16 v[98:101], v[214:217], v[234:237], v[50:53]
	v_mfma_f32_16x16x32_bf16 v[50:53], v[14:17], v[238:241], v[82:85]
	v_mfma_f32_16x16x32_bf16 v[90:93], v[18:21], v[242:245], v[50:53]
	v_mfma_f32_16x16x32_bf16 v[50:53], v[26:29], v[238:241], v[86:89]
	v_mfma_f32_16x16x32_bf16 v[82:85], v[214:217], v[242:245], v[50:53]
	v_mfma_f32_16x16x32_bf16 v[50:53], v[14:17], v[246:249], v[94:97]
	v_mfma_f32_16x16x32_bf16 v[58:61], v[18:21], v[250:253], v[50:53]
	v_mfma_f32_16x16x32_bf16 v[50:53], v[26:29], v[246:249], v[102:105]
	v_mfma_f32_16x16x32_bf16 v[50:53], v[214:217], v[250:253], v[50:53]
	v_mfma_f32_16x16x32_bf16 v[66:69], v[218:221], v[22:25], v[110:113]
	v_mfma_f32_16x16x32_bf16 v[22:25], v[226:229], v[22:25], v[34:37]
	v_mfma_f32_16x16x32_bf16 v[118:121], v[230:233], v[30:33], v[22:25]
	v_mfma_f32_16x16x32_bf16 v[22:25], v[218:221], v[62:65], v[38:41]
	v_mfma_f32_16x16x32_bf16 v[110:113], v[222:225], v[234:237], v[22:25]
	v_mfma_f32_16x16x32_bf16 v[22:25], v[226:229], v[62:65], v[42:45]
	v_mfma_f32_16x16x32_bf16 v[102:105], v[230:233], v[234:237], v[22:25]
	v_mfma_f32_16x16x32_bf16 v[22:25], v[218:221], v[238:241], v[46:49]
	v_mfma_f32_16x16x32_bf16 v[94:97], v[222:225], v[242:245], v[22:25]
	v_mfma_f32_16x16x32_bf16 v[22:25], v[226:229], v[238:241], v[54:57]
	v_mfma_f32_16x16x32_bf16 v[86:89], v[230:233], v[242:245], v[22:25]
	v_mfma_f32_16x16x32_bf16 v[22:25], v[218:221], v[246:249], v[154:157]
	v_mfma_f32_16x16x32_bf16 v[62:65], v[222:225], v[250:253], v[22:25]
	v_mfma_f32_16x16x32_bf16 v[22:25], v[226:229], v[246:249], v[158:161]
	v_mfma_f32_16x16x32_bf16 v[126:129], v[222:225], v[30:33], v[66:69]
	v_mfma_f32_16x16x32_bf16 v[54:57], v[230:233], v[250:253], v[22:25]
	s_setprio 0
	s_barrier
	s_add_i32 s83, s83, s60
	s_add_i32 s84, s83, 0x2000
	s_nop 1
	v_lshl_add_u64 v[22:23], v[142:143], 0, s[30:31]
	s_mov_b32 m0, s83
	s_add_u32 s56, s52, 0x80180
	ds_read_b128 v[34:37], v152 offset:49152
	ds_read_b128 v[42:45], v152 offset:50176
	ds_read_b128 v[154:157], v152 offset:51200
	ds_read_b128 v[158:161], v152 offset:52224
	ds_read_b128 v[234:237], v152 offset:53248
	ds_read_b128 v[238:241], v152 offset:54272
	ds_read_b128 v[242:245], v152 offset:55296
	ds_read_b128 v[246:249], v152 offset:56320
	global_load_lds_dwordx4 v[22:23], off
	v_lshl_add_u64 v[22:23], v[144:145], 0, s[30:31]
	s_mov_b32 m0, s84
	s_addc_u32 s57, s53, 0
	s_add_i32 s85, s85, s60
	global_load_lds_dwordx4 v[22:23], off
	v_lshl_add_u64 v[22:23], s[56:57], 0, v[132:133]
	s_mov_b32 m0, s85
	s_add_i32 s86, s85, 0x2000
	global_load_lds_dwordx4 v[22:23], off
	v_lshl_add_u64 v[22:23], s[56:57], 0, v[136:137]
	s_mov_b32 m0, s86
	s_nop 0
	global_load_lds_dwordx4 v[22:23], off
	v_lshl_add_u64 v[22:23], v[148:149], 0, s[30:31]
	s_mov_b32 m0, s65
	s_nop 0
	global_load_lds_dwordx4 v[22:23], off
	v_lshl_add_u64 v[22:23], v[70:71], 0, s[30:31]
	s_mov_b32 m0, s66
	s_nop 0
	global_load_lds_dwordx4 v[22:23], off
	s_waitcnt vmcnt(8)
	s_waitcnt lgkmcnt(0)
	s_setprio 1
	s_barrier
	v_mfma_f32_16x16x32_bf16 v[22:25], v[14:17], v[34:37], v[162:165]
	v_mfma_f32_16x16x32_bf16 v[78:81], v[18:21], v[42:45], v[22:25]
	v_mfma_f32_16x16x32_bf16 v[22:25], v[26:29], v[34:37], v[166:169]
	v_mfma_f32_16x16x32_bf16 v[70:73], v[214:217], v[42:45], v[22:25]
	v_mfma_f32_16x16x32_bf16 v[22:25], v[14:17], v[154:157], v[170:173]
	v_mfma_f32_16x16x32_bf16 v[46:49], v[18:21], v[158:161], v[22:25]
	v_mfma_f32_16x16x32_bf16 v[22:25], v[26:29], v[154:157], v[174:177]
	v_mfma_f32_16x16x32_bf16 v[38:41], v[214:217], v[158:161], v[22:25]
	v_mfma_f32_16x16x32_bf16 v[22:25], v[14:17], v[234:237], v[178:181]
	v_mfma_f32_16x16x32_bf16 v[2:5], v[14:17], v[242:245], v[2:5]
	v_mfma_f32_16x16x32_bf16 v[30:33], v[18:21], v[238:241], v[22:25]
	v_mfma_f32_16x16x32_bf16 v[22:25], v[26:29], v[234:237], v[182:185]
	v_mfma_f32_16x16x32_bf16 v[14:17], v[18:21], v[246:249], v[2:5]
	v_mfma_f32_16x16x32_bf16 v[2:5], v[26:29], v[242:245], v[6:9]
	v_mfma_f32_16x16x32_bf16 v[22:25], v[214:217], v[238:241], v[22:25]
	v_mfma_f32_16x16x32_bf16 v[6:9], v[214:217], v[246:249], v[2:5]
	v_mfma_f32_16x16x32_bf16 v[2:5], v[218:221], v[34:37], v[10:13]
	v_mfma_f32_16x16x32_bf16 v[74:77], v[222:225], v[42:45], v[2:5]
	v_mfma_f32_16x16x32_bf16 v[2:5], v[226:229], v[34:37], v[186:189]
	v_mfma_f32_16x16x32_bf16 v[66:69], v[230:233], v[42:45], v[2:5]
	v_mfma_f32_16x16x32_bf16 v[2:5], v[218:221], v[154:157], v[190:193]
	v_mfma_f32_16x16x32_bf16 v[42:45], v[222:225], v[158:161], v[2:5]
	v_mfma_f32_16x16x32_bf16 v[2:5], v[226:229], v[154:157], v[194:197]
	v_mfma_f32_16x16x32_bf16 v[34:37], v[230:233], v[158:161], v[2:5]
	v_mfma_f32_16x16x32_bf16 v[2:5], v[218:221], v[234:237], v[198:201]
	v_mfma_f32_16x16x32_bf16 v[26:29], v[222:225], v[238:241], v[2:5]
	v_mfma_f32_16x16x32_bf16 v[2:5], v[226:229], v[234:237], v[202:205]
	v_mfma_f32_16x16x32_bf16 v[18:21], v[230:233], v[238:241], v[2:5]
	v_mfma_f32_16x16x32_bf16 v[2:5], v[218:221], v[242:245], v[206:209]
	v_mfma_f32_16x16x32_bf16 v[10:13], v[222:225], v[246:249], v[2:5]
	v_mfma_f32_16x16x32_bf16 v[2:5], v[226:229], v[242:245], v[210:213]
	v_mfma_f32_16x16x32_bf16 v[2:5], v[230:233], v[246:249], v[2:5]
	s_setprio 0
	s_barrier
	s_add_u32 s87, s52, 0x200
	s_addc_u32 s88, s53, 0
	s_add_u32 s52, s54, 0x80180
	s_addc_u32 s53, s55, 0
	s_mov_b32 s89, 0
	.p2align	6

.LBB0_770:
	s_ashr_i32 s49, s48, 31
	s_lshl_b64 s[8:9], s[48:49], 19
	s_add_u32 s50, s24, s8
	ds_read_b128 v[2:5], v188
	ds_read_b128 v[6:9], v188 offset:1024
	ds_read_b128 v[10:13], v188 offset:2048
	ds_read_b128 v[14:17], v188 offset:3072
	ds_read_b128 v[18:21], v189
	ds_read_b128 v[22:25], v189 offset:1024
	ds_read_b128 v[26:29], v189 offset:2048
	ds_read_b128 v[30:33], v189 offset:3072
	s_addc_u32 s51, s25, s9
	s_ashr_i32 s47, s46, 31
	s_lshl_b64 s[8:9], s[46:47], 19
	s_add_u32 s52, s26, s8
	s_addc_u32 s53, s27, s9
	s_and_b64 s[8:9], s[4:5], exec
	s_cselect_b32 s47, s51, s59
	s_cselect_b32 s49, s50, s58
	s_cselect_b32 s74, s53, s57
	s_cselect_b32 s75, s52, s56
	s_add_u32 s8, s58, 0x40080
	s_addc_u32 s9, s59, 0
	s_add_i32 s76, s55, 0xc000
	v_lshl_add_u64 v[34:35], s[8:9], 0, v[162:163]
	s_mov_b32 m0, s76
	s_add_i32 s77, s55, 0xe000
	ds_read_b128 v[38:41], v190
	ds_read_b128 v[42:45], v190 offset:1024
	ds_read_b128 v[46:49], v190 offset:2048
	ds_read_b128 v[50:53], v190 offset:3072
	ds_read_b128 v[54:57], v190 offset:4096
	ds_read_b128 v[58:61], v190 offset:5120
	ds_read_b128 v[62:65], v190 offset:6144
	ds_read_b128 v[66:69], v190 offset:7168
	global_load_lds_dwordx4 v[34:35], off
	v_lshl_add_u64 v[34:35], s[8:9], 0, v[166:167]
	s_mov_b32 m0, s77
	s_nop 0
	global_load_lds_dwordx4 v[34:35], off
	s_waitcnt vmcnt(24)
	s_waitcnt lgkmcnt(0)
	s_setprio 1
	s_barrier
	s_mov_b32 s8, 0
	s_mov_b32 s10, s8
	s_mov_b32 s11, s8
	s_mov_b32 s9, s8
	v_mov_b64_e32 v[36:37], s[10:11]
	v_mov_b64_e32 v[156:157], s[10:11]
	v_mov_b64_e32 v[160:161], s[10:11]
	v_mov_b64_e32 v[144:145], s[10:11]
	v_mov_b64_e32 v[140:141], s[10:11]
	v_mov_b64_e32 v[128:129], s[10:11]
	v_mov_b64_e32 v[124:125], s[10:11]
	v_mov_b64_e32 v[112:113], s[10:11]
	v_mov_b64_e32 v[108:109], s[10:11]
	v_mov_b64_e32 v[34:35], s[8:9]
	v_mov_b64_e32 v[154:155], s[8:9]
	v_mov_b64_e32 v[158:159], s[8:9]
	v_mov_b64_e32 v[142:143], s[8:9]
	v_mov_b64_e32 v[138:139], s[8:9]
	v_mov_b64_e32 v[126:127], s[8:9]
	v_mov_b64_e32 v[122:123], s[8:9]
	v_mov_b64_e32 v[110:111], s[8:9]
	v_mov_b64_e32 v[106:107], s[8:9]
	s_waitcnt lgkmcnt(0)
	v_mfma_f32_16x16x128_f8f6f4 v[154:157], v[2:9], v[38:45], v[154:157]
	v_mfma_f32_16x16x128_f8f6f4 v[158:161], v[10:17], v[38:45], v[158:161]
	v_mfma_f32_16x16x128_f8f6f4 v[142:145], v[2:9], v[46:53], v[142:145]
	v_mfma_f32_16x16x128_f8f6f4 v[138:141], v[10:17], v[46:53], v[138:141]
	v_mfma_f32_16x16x128_f8f6f4 v[126:129], v[2:9], v[54:61], v[126:129]
	v_mfma_f32_16x16x128_f8f6f4 v[122:125], v[10:17], v[54:61], v[122:125]
	v_mfma_f32_16x16x128_f8f6f4 v[110:113], v[2:9], v[62:69], v[110:113]
	v_mfma_f32_16x16x128_f8f6f4 v[106:109], v[10:17], v[62:69], v[106:109]
	v_mov_b64_e32 v[148:149], s[10:11]
	v_mov_b64_e32 v[152:153], s[10:11]
	v_mov_b64_e32 v[136:137], s[10:11]
	v_mov_b64_e32 v[132:133], s[10:11]
	v_mov_b64_e32 v[120:121], s[10:11]
	v_mov_b64_e32 v[116:117], s[10:11]
	v_mov_b64_e32 v[96:97], s[10:11]
	v_mov_b64_e32 v[92:93], s[10:11]
	v_mov_b64_e32 v[146:147], s[8:9]
	v_mov_b64_e32 v[150:151], s[8:9]
	v_mov_b64_e32 v[134:135], s[8:9]
	v_mov_b64_e32 v[130:131], s[8:9]
	v_mov_b64_e32 v[118:119], s[8:9]
	v_mov_b64_e32 v[114:115], s[8:9]
	v_mov_b64_e32 v[94:95], s[8:9]
	v_mov_b64_e32 v[90:91], s[8:9]
	v_mfma_f32_16x16x128_f8f6f4 v[146:149], v[18:25], v[38:45], v[146:149]
	v_mfma_f32_16x16x128_f8f6f4 v[150:153], v[26:33], v[38:45], v[150:153]
	v_mfma_f32_16x16x128_f8f6f4 v[134:137], v[18:25], v[46:53], v[134:137]
	v_mfma_f32_16x16x128_f8f6f4 v[130:133], v[26:33], v[46:53], v[130:133]
	v_mfma_f32_16x16x128_f8f6f4 v[118:121], v[18:25], v[54:61], v[118:121]
	v_mfma_f32_16x16x128_f8f6f4 v[114:117], v[26:33], v[54:61], v[114:117]
	v_mfma_f32_16x16x128_f8f6f4 v[94:97], v[18:25], v[62:69], v[94:97]
	v_mfma_f32_16x16x128_f8f6f4 v[90:93], v[26:33], v[62:69], v[90:93]
	s_setprio 0
	s_barrier
	s_add_i32 s9, s67, s37
	v_lshl_add_u64 v[178:179], s[56:57], 0, v[164:165]
	s_add_i32 s78, s9, 0x2000
	v_lshl_add_u64 v[38:39], v[178:179], 0, s[30:31]
	s_mov_b32 m0, s9
	v_lshl_add_u64 v[180:181], s[56:57], 0, v[168:169]
	s_add_u32 s10, s56, 0x40100
	ds_read_b128 v[50:53], v190 offset:16384
	ds_read_b128 v[54:57], v190 offset:17408
	ds_read_b128 v[192:195], v190 offset:18432
	ds_read_b128 v[196:199], v190 offset:19456
	ds_read_b128 v[200:203], v190 offset:20480
	ds_read_b128 v[204:207], v190 offset:21504
	ds_read_b128 v[208:211], v190 offset:22528
	ds_read_b128 v[212:215], v190 offset:23552
	global_load_lds_dwordx4 v[38:39], off
	v_lshl_add_u64 v[38:39], v[180:181], 0, s[30:31]
	s_mov_b32 m0, s78
	s_addc_u32 s11, s57, 0
	s_add_i32 s79, s68, s37
	global_load_lds_dwordx4 v[38:39], off
	v_lshl_add_u64 v[38:39], s[10:11], 0, v[164:165]
	s_mov_b32 m0, s79
	s_add_i32 s80, s79, 0x2000
	global_load_lds_dwordx4 v[38:39], off
	v_lshl_add_u64 v[38:39], s[10:11], 0, v[168:169]
	s_mov_b32 m0, s80
	v_lshl_add_u64 v[182:183], s[58:59], 0, v[162:163]
	global_load_lds_dwordx4 v[38:39], off
	v_lshl_add_u64 v[38:39], v[182:183], 0, s[30:31]
	s_mov_b32 m0, s55
	v_lshl_add_u64 v[184:185], s[58:59], 0, v[166:167]
	global_load_lds_dwordx4 v[38:39], off
	v_lshl_add_u64 v[38:39], v[184:185], 0, s[30:31]
	s_mov_b32 m0, s60
	s_nop 0
	global_load_lds_dwordx4 v[38:39], off
	s_waitcnt vmcnt(24)
	s_waitcnt lgkmcnt(0)
	s_setprio 1
	s_barrier
	v_mov_b64_e32 v[104:105], v[36:37]
	v_mov_b64_e32 v[100:101], v[36:37]
	v_mov_b64_e32 v[80:81], v[36:37]
	v_mov_b64_e32 v[76:77], v[36:37]
	v_mov_b64_e32 v[64:65], v[36:37]
	v_mov_b64_e32 v[60:61], v[36:37]
	v_mov_b64_e32 v[48:49], v[36:37]
	v_mov_b64_e32 v[44:45], v[36:37]
	v_mov_b64_e32 v[102:103], v[34:35]
	v_mov_b64_e32 v[98:99], v[34:35]
	v_mov_b64_e32 v[78:79], v[34:35]
	v_mov_b64_e32 v[74:75], v[34:35]
	v_mov_b64_e32 v[62:63], v[34:35]
	v_mov_b64_e32 v[58:59], v[34:35]
	v_mov_b64_e32 v[46:47], v[34:35]
	v_mov_b64_e32 v[42:43], v[34:35]
	s_waitcnt lgkmcnt(0)
	v_mfma_f32_16x16x128_f8f6f4 v[102:105], v[2:9], v[50:57], v[102:105]
	v_mfma_f32_16x16x128_f8f6f4 v[98:101], v[10:17], v[50:57], v[98:101]
	v_mfma_f32_16x16x128_f8f6f4 v[78:81], v[2:9], v[192:199], v[78:81]
	v_mfma_f32_16x16x128_f8f6f4 v[74:77], v[10:17], v[192:199], v[74:77]
	v_mfma_f32_16x16x128_f8f6f4 v[62:65], v[2:9], v[200:207], v[62:65]
	v_mfma_f32_16x16x128_f8f6f4 v[58:61], v[10:17], v[200:207], v[58:61]
	v_mfma_f32_16x16x128_f8f6f4 v[46:49], v[2:9], v[208:215], v[46:49]
	v_mfma_f32_16x16x128_f8f6f4 v[42:45], v[10:17], v[208:215], v[42:45]
	v_mov_b64_e32 v[88:89], v[36:37]
	v_mov_b64_e32 v[84:85], v[36:37]
	v_mov_b64_e32 v[86:87], v[34:35]
	v_mov_b64_e32 v[82:83], v[34:35]
	v_mfma_f32_16x16x128_f8f6f4 v[86:89], v[18:25], v[50:57], v[86:89]
	v_mfma_f32_16x16x128_f8f6f4 v[82:85], v[26:33], v[50:57], v[82:85]
	v_mov_b64_e32 v[72:73], v[36:37]
	v_mov_b64_e32 v[68:69], v[36:37]
	v_mov_b64_e32 v[56:57], v[36:37]
	v_mov_b64_e32 v[52:53], v[36:37]
	v_mov_b64_e32 v[40:41], v[36:37]
	v_mov_b64_e32 v[70:71], v[34:35]
	v_mov_b64_e32 v[66:67], v[34:35]
	v_mov_b64_e32 v[54:55], v[34:35]
	v_mov_b64_e32 v[50:51], v[34:35]
	v_mov_b64_e32 v[38:39], v[34:35]
	v_mfma_f32_16x16x128_f8f6f4 v[70:73], v[18:25], v[192:199], v[70:73]
	v_mfma_f32_16x16x128_f8f6f4 v[66:69], v[26:33], v[192:199], v[66:69]
	v_mfma_f32_16x16x128_f8f6f4 v[54:57], v[18:25], v[200:207], v[54:57]
	v_mfma_f32_16x16x128_f8f6f4 v[50:53], v[26:33], v[200:207], v[50:53]
	v_mfma_f32_16x16x128_f8f6f4 v[38:41], v[18:25], v[208:215], v[38:41]
	v_mfma_f32_16x16x128_f8f6f4 v[34:37], v[26:33], v[208:215], v[34:37]
	s_setprio 0
	s_barrier
	s_add_i32 s81, 0, 0x18000
	s_add_i32 s83, 0, 0x1c000
	v_add_u32_e32 v191, s81, v186
	v_add_u32_e32 v192, s83, v186
	ds_read_b128 v[18:21], v191
	ds_read_b128 v[22:25], v191 offset:1024
	ds_read_b128 v[26:29], v191 offset:2048
	ds_read_b128 v[30:33], v191 offset:3072
	ds_read_b128 v[2:5], v192
	ds_read_b128 v[6:9], v192 offset:1024
	ds_read_b128 v[10:13], v192 offset:2048
	ds_read_b128 v[14:17], v192 offset:3072
	s_add_u32 s10, s58, 0x40100
	s_addc_u32 s11, s59, 0
	s_mov_b32 m0, s61
	v_lshl_add_u64 v[226:227], s[10:11], 0, v[162:163]
	ds_read_b128 v[194:197], v190 offset:32768
	ds_read_b128 v[198:201], v190 offset:33792
	ds_read_b128 v[202:205], v190 offset:34816
	ds_read_b128 v[206:209], v190 offset:35840
	ds_read_b128 v[210:213], v190 offset:36864
	ds_read_b128 v[214:217], v190 offset:37888
	ds_read_b128 v[218:221], v190 offset:38912
	ds_read_b128 v[222:225], v190 offset:39936
	global_load_lds_dwordx4 v[226:227], off
	v_lshl_add_u64 v[226:227], s[10:11], 0, v[166:167]
	s_mov_b32 m0, s62
	s_nop 0
	global_load_lds_dwordx4 v[226:227], off
	s_waitcnt vmcnt(8)
	s_waitcnt lgkmcnt(0)
	s_setprio 1
	s_barrier
	v_mfma_f32_16x16x128_f8f6f4 v[154:157], v[18:25], v[194:201], v[154:157]
	v_mfma_f32_16x16x128_f8f6f4 v[158:161], v[26:33], v[194:201], v[158:161]
	v_mfma_f32_16x16x128_f8f6f4 v[142:145], v[18:25], v[202:209], v[142:145]
	v_mfma_f32_16x16x128_f8f6f4 v[138:141], v[26:33], v[202:209], v[138:141]
	v_mfma_f32_16x16x128_f8f6f4 v[126:129], v[18:25], v[210:217], v[126:129]
	v_mfma_f32_16x16x128_f8f6f4 v[122:125], v[26:33], v[210:217], v[122:125]
	v_mfma_f32_16x16x128_f8f6f4 v[110:113], v[18:25], v[218:225], v[110:113]
	v_mfma_f32_16x16x128_f8f6f4 v[106:109], v[26:33], v[218:225], v[106:109]
	v_mfma_f32_16x16x128_f8f6f4 v[146:149], v[2:9], v[194:201], v[146:149]
	v_mfma_f32_16x16x128_f8f6f4 v[150:153], v[10:17], v[194:201], v[150:153]
	v_mfma_f32_16x16x128_f8f6f4 v[134:137], v[2:9], v[202:209], v[134:137]
	v_mfma_f32_16x16x128_f8f6f4 v[130:133], v[10:17], v[202:209], v[130:133]
	v_mfma_f32_16x16x128_f8f6f4 v[118:121], v[2:9], v[210:217], v[118:121]
	v_mfma_f32_16x16x128_f8f6f4 v[114:117], v[10:17], v[210:217], v[114:117]
	v_mfma_f32_16x16x128_f8f6f4 v[94:97], v[2:9], v[218:225], v[94:97]
	v_mfma_f32_16x16x128_f8f6f4 v[90:93], v[10:17], v[218:225], v[90:93]
	s_setprio 0
	s_barrier
	s_add_i32 s81, s81, s37
	s_add_i32 s82, s81, 0x2000
	v_lshl_add_u64 v[178:179], v[178:179], 0, s[34:35]
	s_mov_b32 m0, s81
	s_add_u32 s10, s56, 0x40180
	ds_read_b128 v[194:197], v190 offset:49152
	ds_read_b128 v[198:201], v190 offset:50176
	ds_read_b128 v[202:205], v190 offset:51200
	ds_read_b128 v[206:209], v190 offset:52224
	ds_read_b128 v[210:213], v190 offset:53248
	ds_read_b128 v[214:217], v190 offset:54272
	ds_read_b128 v[218:221], v190 offset:55296
	ds_read_b128 v[222:225], v190 offset:56320
	global_load_lds_dwordx4 v[178:179], off
	v_lshl_add_u64 v[178:179], v[180:181], 0, s[34:35]
	s_mov_b32 m0, s82
	s_addc_u32 s11, s57, 0
	s_add_i32 s83, s83, s37
	global_load_lds_dwordx4 v[178:179], off
	v_lshl_add_u64 v[178:179], s[10:11], 0, v[164:165]
	s_mov_b32 m0, s83
	s_add_i32 s84, s83, 0x2000
	global_load_lds_dwordx4 v[178:179], off
	v_lshl_add_u64 v[178:179], s[10:11], 0, v[168:169]
	s_mov_b32 m0, s84
	s_nop 0
	global_load_lds_dwordx4 v[178:179], off
	v_lshl_add_u64 v[178:179], v[182:183], 0, s[34:35]
	s_mov_b32 m0, s64
	s_nop 0
	global_load_lds_dwordx4 v[178:179], off
	v_lshl_add_u64 v[178:179], v[184:185], 0, s[34:35]
	s_mov_b32 m0, s65
	s_nop 0
	global_load_lds_dwordx4 v[178:179], off
	s_waitcnt vmcnt(8)
	s_waitcnt lgkmcnt(0)
	s_setprio 1
	s_barrier
	v_mfma_f32_16x16x128_f8f6f4 v[102:105], v[18:25], v[194:201], v[102:105]
	v_mfma_f32_16x16x128_f8f6f4 v[98:101], v[26:33], v[194:201], v[98:101]
	v_mfma_f32_16x16x128_f8f6f4 v[78:81], v[18:25], v[202:209], v[78:81]
	v_mfma_f32_16x16x128_f8f6f4 v[74:77], v[26:33], v[202:209], v[74:77]
	v_mfma_f32_16x16x128_f8f6f4 v[62:65], v[18:25], v[210:217], v[62:65]
	v_mfma_f32_16x16x128_f8f6f4 v[58:61], v[26:33], v[210:217], v[58:61]
	v_mfma_f32_16x16x128_f8f6f4 v[46:49], v[18:25], v[218:225], v[46:49]
	v_mfma_f32_16x16x128_f8f6f4 v[42:45], v[26:33], v[218:225], v[42:45]
	v_mfma_f32_16x16x128_f8f6f4 v[86:89], v[2:9], v[194:201], v[86:89]
	v_mfma_f32_16x16x128_f8f6f4 v[82:85], v[10:17], v[194:201], v[82:85]
	v_mfma_f32_16x16x128_f8f6f4 v[70:73], v[2:9], v[202:209], v[70:73]
	v_mfma_f32_16x16x128_f8f6f4 v[66:69], v[10:17], v[202:209], v[66:69]
	v_mfma_f32_16x16x128_f8f6f4 v[54:57], v[2:9], v[210:217], v[54:57]
	v_mfma_f32_16x16x128_f8f6f4 v[50:53], v[10:17], v[210:217], v[50:53]
	v_mfma_f32_16x16x128_f8f6f4 v[38:41], v[2:9], v[218:225], v[38:41]
	v_mfma_f32_16x16x128_f8f6f4 v[34:37], v[10:17], v[218:225], v[34:37]
	s_setprio 0
	s_barrier
	s_add_u32 s85, s56, 0x200
	s_addc_u32 s86, s57, 0
	s_add_u32 s10, s58, 0x40180
	s_addc_u32 s11, s59, 0
	.p2align	6

.LBB0_902:
	s_ashr_i32 s49, s48, 31
	ds_read_b128 v[2:5], v188
	ds_read_b128 v[6:9], v188 offset:1024
	ds_read_b128 v[10:13], v188 offset:2048
	ds_read_b128 v[14:17], v188 offset:3072
	ds_read_b128 v[18:21], v189
	ds_read_b128 v[22:25], v189 offset:1024
	ds_read_b128 v[26:29], v189 offset:2048
	ds_read_b128 v[30:33], v189 offset:3072
	s_lshl_b64 s[8:9], s[48:49], 20
	s_add_u32 s50, s19, s8
	s_addc_u32 s51, s24, s9
	s_and_b64 s[8:9], s[4:5], exec
	s_cselect_b32 s49, s51, s59
	s_cselect_b32 s74, s50, s58
	s_ashr_i32 s47, s46, 31
	s_lshl_b64 s[8:9], s[46:47], 20
	s_add_u32 s52, s25, s8
	s_addc_u32 s53, s26, s9
	s_and_b64 s[8:9], s[4:5], exec
	s_cselect_b32 s47, s53, s57
	s_cselect_b32 s75, s52, s56
	s_add_u32 s8, s58, 0x80080
	s_addc_u32 s9, s59, 0
	s_add_i32 s76, s55, 0xc000
	v_lshl_add_u64 v[34:35], s[8:9], 0, v[168:169]
	s_mov_b32 m0, s76
	s_add_i32 s77, s55, 0xe000
	ds_read_b128 v[38:41], v190
	ds_read_b128 v[42:45], v190 offset:1024
	ds_read_b128 v[46:49], v190 offset:2048
	ds_read_b128 v[50:53], v190 offset:3072
	ds_read_b128 v[54:57], v190 offset:4096
	ds_read_b128 v[58:61], v190 offset:5120
	ds_read_b128 v[62:65], v190 offset:6144
	ds_read_b128 v[66:69], v190 offset:7168
	global_load_lds_dwordx4 v[34:35], off
	v_lshl_add_u64 v[34:35], s[8:9], 0, v[164:165]
	s_mov_b32 m0, s77
	s_nop 0
	global_load_lds_dwordx4 v[34:35], off
	s_waitcnt vmcnt(24)
	s_waitcnt lgkmcnt(0)
	s_setprio 1
	s_barrier
	s_mov_b32 s8, 0
	s_mov_b32 s10, s8
	s_mov_b32 s11, s8
	s_mov_b32 s9, s8
	v_mov_b64_e32 v[36:37], s[10:11]
	v_mov_b64_e32 v[160:161], s[10:11]
	v_mov_b64_e32 v[156:157], s[10:11]
	v_mov_b64_e32 v[144:145], s[10:11]
	v_mov_b64_e32 v[140:141], s[10:11]
	v_mov_b64_e32 v[128:129], s[10:11]
	v_mov_b64_e32 v[120:121], s[10:11]
	v_mov_b64_e32 v[92:93], s[10:11]
	v_mov_b64_e32 v[84:85], s[10:11]
	v_mov_b64_e32 v[34:35], s[8:9]
	v_mov_b64_e32 v[158:159], s[8:9]
	v_mov_b64_e32 v[154:155], s[8:9]
	v_mov_b64_e32 v[142:143], s[8:9]
	v_mov_b64_e32 v[138:139], s[8:9]
	v_mov_b64_e32 v[126:127], s[8:9]
	v_mov_b64_e32 v[118:119], s[8:9]
	v_mov_b64_e32 v[90:91], s[8:9]
	v_mov_b64_e32 v[82:83], s[8:9]
	s_waitcnt lgkmcnt(0)
	v_mfma_f32_16x16x128_f8f6f4 v[158:161], v[2:9], v[38:45], v[158:161]
	v_mfma_f32_16x16x128_f8f6f4 v[154:157], v[10:17], v[38:45], v[154:157]
	v_mfma_f32_16x16x128_f8f6f4 v[142:145], v[2:9], v[46:53], v[142:145]
	v_mfma_f32_16x16x128_f8f6f4 v[138:141], v[10:17], v[46:53], v[138:141]
	v_mfma_f32_16x16x128_f8f6f4 v[126:129], v[2:9], v[54:61], v[126:129]
	v_mfma_f32_16x16x128_f8f6f4 v[118:121], v[10:17], v[54:61], v[118:121]
	v_mfma_f32_16x16x128_f8f6f4 v[90:93], v[2:9], v[62:69], v[90:93]
	v_mfma_f32_16x16x128_f8f6f4 v[82:85], v[10:17], v[62:69], v[82:85]
	v_mov_b64_e32 v[152:153], s[10:11]
	v_mov_b64_e32 v[148:149], s[10:11]
	v_mov_b64_e32 v[136:137], s[10:11]
	v_mov_b64_e32 v[132:133], s[10:11]
	v_mov_b64_e32 v[112:113], s[10:11]
	v_mov_b64_e32 v[108:109], s[10:11]
	v_mov_b64_e32 v[80:81], s[10:11]
	v_mov_b64_e32 v[76:77], s[10:11]
	v_mov_b64_e32 v[150:151], s[8:9]
	v_mov_b64_e32 v[146:147], s[8:9]
	v_mov_b64_e32 v[134:135], s[8:9]
	v_mov_b64_e32 v[130:131], s[8:9]
	v_mov_b64_e32 v[110:111], s[8:9]
	v_mov_b64_e32 v[106:107], s[8:9]
	v_mov_b64_e32 v[78:79], s[8:9]
	v_mov_b64_e32 v[74:75], s[8:9]
	v_mfma_f32_16x16x128_f8f6f4 v[150:153], v[18:25], v[38:45], v[150:153]
	v_mfma_f32_16x16x128_f8f6f4 v[146:149], v[26:33], v[38:45], v[146:149]
	v_mfma_f32_16x16x128_f8f6f4 v[134:137], v[18:25], v[46:53], v[134:137]
	v_mfma_f32_16x16x128_f8f6f4 v[130:133], v[26:33], v[46:53], v[130:133]
	v_mfma_f32_16x16x128_f8f6f4 v[110:113], v[18:25], v[54:61], v[110:113]
	v_mfma_f32_16x16x128_f8f6f4 v[106:109], v[26:33], v[54:61], v[106:109]
	v_mfma_f32_16x16x128_f8f6f4 v[78:81], v[18:25], v[62:69], v[78:81]
	v_mfma_f32_16x16x128_f8f6f4 v[74:77], v[26:33], v[62:69], v[74:77]
	s_setprio 0
	s_barrier
	s_add_i32 s9, s67, s27
	v_lshl_add_u64 v[178:179], s[56:57], 0, v[166:167]
	s_add_i32 s78, s9, 0x2000
	v_lshl_add_u64 v[38:39], v[178:179], 0, s[34:35]
	s_mov_b32 m0, s9
	v_lshl_add_u64 v[180:181], s[56:57], 0, v[162:163]
	s_add_u32 s10, s56, 0x80100
	ds_read_b128 v[50:53], v190 offset:16384
	ds_read_b128 v[54:57], v190 offset:17408
	ds_read_b128 v[192:195], v190 offset:18432
	ds_read_b128 v[196:199], v190 offset:19456
	ds_read_b128 v[200:203], v190 offset:20480
	ds_read_b128 v[204:207], v190 offset:21504
	ds_read_b128 v[208:211], v190 offset:22528
	ds_read_b128 v[212:215], v190 offset:23552
	global_load_lds_dwordx4 v[38:39], off
	v_lshl_add_u64 v[38:39], v[180:181], 0, s[34:35]
	s_mov_b32 m0, s78
	s_addc_u32 s11, s57, 0
	s_add_i32 s79, s68, s27
	global_load_lds_dwordx4 v[38:39], off
	v_lshl_add_u64 v[38:39], s[10:11], 0, v[166:167]
	s_mov_b32 m0, s79
	s_add_i32 s80, s79, 0x2000
	global_load_lds_dwordx4 v[38:39], off
	v_lshl_add_u64 v[38:39], s[10:11], 0, v[162:163]
	s_mov_b32 m0, s80
	v_lshl_add_u64 v[182:183], s[58:59], 0, v[168:169]
	global_load_lds_dwordx4 v[38:39], off
	v_lshl_add_u64 v[38:39], v[182:183], 0, s[34:35]
	s_mov_b32 m0, s55
	v_lshl_add_u64 v[184:185], s[58:59], 0, v[164:165]
	global_load_lds_dwordx4 v[38:39], off
	v_lshl_add_u64 v[38:39], v[184:185], 0, s[34:35]
	s_mov_b32 m0, s60
	s_nop 0
	global_load_lds_dwordx4 v[38:39], off
	s_waitcnt vmcnt(24)
	s_waitcnt lgkmcnt(0)
	s_setprio 1
	s_barrier
	v_mov_b64_e32 v[124:125], v[36:37]
	v_mov_b64_e32 v[116:117], v[36:37]
	v_mov_b64_e32 v[96:97], v[36:37]
	v_mov_b64_e32 v[88:89], v[36:37]
	v_mov_b64_e32 v[64:65], v[36:37]
	v_mov_b64_e32 v[60:61], v[36:37]
	v_mov_b64_e32 v[48:49], v[36:37]
	v_mov_b64_e32 v[44:45], v[36:37]
	v_mov_b64_e32 v[122:123], v[34:35]
	v_mov_b64_e32 v[114:115], v[34:35]
	v_mov_b64_e32 v[94:95], v[34:35]
	v_mov_b64_e32 v[86:87], v[34:35]
	v_mov_b64_e32 v[62:63], v[34:35]
	v_mov_b64_e32 v[58:59], v[34:35]
	v_mov_b64_e32 v[46:47], v[34:35]
	v_mov_b64_e32 v[42:43], v[34:35]
	s_waitcnt lgkmcnt(0)
	v_mfma_f32_16x16x128_f8f6f4 v[122:125], v[2:9], v[50:57], v[122:125]
	v_mfma_f32_16x16x128_f8f6f4 v[114:117], v[10:17], v[50:57], v[114:117]
	v_mfma_f32_16x16x128_f8f6f4 v[94:97], v[2:9], v[192:199], v[94:97]
	v_mfma_f32_16x16x128_f8f6f4 v[86:89], v[10:17], v[192:199], v[86:89]
	v_mfma_f32_16x16x128_f8f6f4 v[62:65], v[2:9], v[200:207], v[62:65]
	v_mfma_f32_16x16x128_f8f6f4 v[58:61], v[10:17], v[200:207], v[58:61]
	v_mfma_f32_16x16x128_f8f6f4 v[46:49], v[2:9], v[208:215], v[46:49]
	v_mfma_f32_16x16x128_f8f6f4 v[42:45], v[10:17], v[208:215], v[42:45]
	v_mov_b64_e32 v[104:105], v[36:37]
	v_mov_b64_e32 v[100:101], v[36:37]
	v_mov_b64_e32 v[102:103], v[34:35]
	v_mov_b64_e32 v[98:99], v[34:35]
	v_mfma_f32_16x16x128_f8f6f4 v[102:105], v[18:25], v[50:57], v[102:105]
	v_mfma_f32_16x16x128_f8f6f4 v[98:101], v[26:33], v[50:57], v[98:101]
	v_mov_b64_e32 v[72:73], v[36:37]
	v_mov_b64_e32 v[68:69], v[36:37]
	v_mov_b64_e32 v[56:57], v[36:37]
	v_mov_b64_e32 v[52:53], v[36:37]
	v_mov_b64_e32 v[40:41], v[36:37]
	v_mov_b64_e32 v[70:71], v[34:35]
	v_mov_b64_e32 v[66:67], v[34:35]
	v_mov_b64_e32 v[54:55], v[34:35]
	v_mov_b64_e32 v[50:51], v[34:35]
	v_mov_b64_e32 v[38:39], v[34:35]
	v_mfma_f32_16x16x128_f8f6f4 v[70:73], v[18:25], v[192:199], v[70:73]
	v_mfma_f32_16x16x128_f8f6f4 v[66:69], v[26:33], v[192:199], v[66:69]
	v_mfma_f32_16x16x128_f8f6f4 v[54:57], v[18:25], v[200:207], v[54:57]
	v_mfma_f32_16x16x128_f8f6f4 v[50:53], v[26:33], v[200:207], v[50:53]
	v_mfma_f32_16x16x128_f8f6f4 v[38:41], v[18:25], v[208:215], v[38:41]
	v_mfma_f32_16x16x128_f8f6f4 v[34:37], v[26:33], v[208:215], v[34:37]
	s_setprio 0
	s_barrier
	s_add_i32 s81, 0, 0x18000
	s_add_i32 s83, 0, 0x1c000
	v_add_u32_e32 v191, s81, v186
	v_add_u32_e32 v192, s83, v186
	ds_read_b128 v[18:21], v191
	ds_read_b128 v[22:25], v191 offset:1024
	ds_read_b128 v[26:29], v191 offset:2048
	ds_read_b128 v[30:33], v191 offset:3072
	ds_read_b128 v[2:5], v192
	ds_read_b128 v[6:9], v192 offset:1024
	ds_read_b128 v[10:13], v192 offset:2048
	ds_read_b128 v[14:17], v192 offset:3072
	s_add_u32 s10, s58, 0x80100
	s_addc_u32 s11, s59, 0
	s_mov_b32 m0, s61
	v_lshl_add_u64 v[226:227], s[10:11], 0, v[168:169]
	ds_read_b128 v[194:197], v190 offset:32768
	ds_read_b128 v[198:201], v190 offset:33792
	ds_read_b128 v[202:205], v190 offset:34816
	ds_read_b128 v[206:209], v190 offset:35840
	ds_read_b128 v[210:213], v190 offset:36864
	ds_read_b128 v[214:217], v190 offset:37888
	ds_read_b128 v[218:221], v190 offset:38912
	ds_read_b128 v[222:225], v190 offset:39936
	global_load_lds_dwordx4 v[226:227], off
	v_lshl_add_u64 v[226:227], s[10:11], 0, v[164:165]
	s_mov_b32 m0, s62
	s_nop 0
	global_load_lds_dwordx4 v[226:227], off
	s_waitcnt vmcnt(8)
	s_waitcnt lgkmcnt(0)
	s_setprio 1
	s_barrier
	v_mfma_f32_16x16x128_f8f6f4 v[158:161], v[18:25], v[194:201], v[158:161]
	v_mfma_f32_16x16x128_f8f6f4 v[154:157], v[26:33], v[194:201], v[154:157]
	v_mfma_f32_16x16x128_f8f6f4 v[142:145], v[18:25], v[202:209], v[142:145]
	v_mfma_f32_16x16x128_f8f6f4 v[138:141], v[26:33], v[202:209], v[138:141]
	v_mfma_f32_16x16x128_f8f6f4 v[126:129], v[18:25], v[210:217], v[126:129]
	v_mfma_f32_16x16x128_f8f6f4 v[118:121], v[26:33], v[210:217], v[118:121]
	v_mfma_f32_16x16x128_f8f6f4 v[90:93], v[18:25], v[218:225], v[90:93]
	v_mfma_f32_16x16x128_f8f6f4 v[82:85], v[26:33], v[218:225], v[82:85]
	v_mfma_f32_16x16x128_f8f6f4 v[150:153], v[2:9], v[194:201], v[150:153]
	v_mfma_f32_16x16x128_f8f6f4 v[146:149], v[10:17], v[194:201], v[146:149]
	v_mfma_f32_16x16x128_f8f6f4 v[134:137], v[2:9], v[202:209], v[134:137]
	v_mfma_f32_16x16x128_f8f6f4 v[130:133], v[10:17], v[202:209], v[130:133]
	v_mfma_f32_16x16x128_f8f6f4 v[110:113], v[2:9], v[210:217], v[110:113]
	v_mfma_f32_16x16x128_f8f6f4 v[106:109], v[10:17], v[210:217], v[106:109]
	v_mfma_f32_16x16x128_f8f6f4 v[78:81], v[2:9], v[218:225], v[78:81]
	v_mfma_f32_16x16x128_f8f6f4 v[74:77], v[10:17], v[218:225], v[74:77]
	s_setprio 0
	s_barrier
	s_add_i32 s81, s81, s27
	s_add_i32 s82, s81, 0x2000
	v_lshl_add_u64 v[178:179], v[178:179], 0, s[36:37]
	s_mov_b32 m0, s81
	s_add_u32 s10, s56, 0x80180
	ds_read_b128 v[194:197], v190 offset:49152
	ds_read_b128 v[198:201], v190 offset:50176
	ds_read_b128 v[202:205], v190 offset:51200
	ds_read_b128 v[206:209], v190 offset:52224
	ds_read_b128 v[210:213], v190 offset:53248
	ds_read_b128 v[214:217], v190 offset:54272
	ds_read_b128 v[218:221], v190 offset:55296
	ds_read_b128 v[222:225], v190 offset:56320
	global_load_lds_dwordx4 v[178:179], off
	v_lshl_add_u64 v[178:179], v[180:181], 0, s[36:37]
	s_mov_b32 m0, s82
	s_addc_u32 s11, s57, 0
	s_add_i32 s83, s83, s27
	global_load_lds_dwordx4 v[178:179], off
	v_lshl_add_u64 v[178:179], s[10:11], 0, v[166:167]
	s_mov_b32 m0, s83
	s_add_i32 s84, s83, 0x2000
	global_load_lds_dwordx4 v[178:179], off
	v_lshl_add_u64 v[178:179], s[10:11], 0, v[162:163]
	s_mov_b32 m0, s84
	s_nop 0
	global_load_lds_dwordx4 v[178:179], off
	v_lshl_add_u64 v[178:179], v[182:183], 0, s[36:37]
	s_mov_b32 m0, s63
	s_nop 0
	global_load_lds_dwordx4 v[178:179], off
	v_lshl_add_u64 v[178:179], v[184:185], 0, s[36:37]
	s_mov_b32 m0, s64
	s_nop 0
	global_load_lds_dwordx4 v[178:179], off
	s_waitcnt vmcnt(8)
	s_waitcnt lgkmcnt(0)
	s_setprio 1
	s_barrier
	v_mfma_f32_16x16x128_f8f6f4 v[122:125], v[18:25], v[194:201], v[122:125]
	v_mfma_f32_16x16x128_f8f6f4 v[114:117], v[26:33], v[194:201], v[114:117]
	v_mfma_f32_16x16x128_f8f6f4 v[94:97], v[18:25], v[202:209], v[94:97]
	v_mfma_f32_16x16x128_f8f6f4 v[86:89], v[26:33], v[202:209], v[86:89]
	v_mfma_f32_16x16x128_f8f6f4 v[62:65], v[18:25], v[210:217], v[62:65]
	v_mfma_f32_16x16x128_f8f6f4 v[58:61], v[26:33], v[210:217], v[58:61]
	v_mfma_f32_16x16x128_f8f6f4 v[46:49], v[18:25], v[218:225], v[46:49]
	v_mfma_f32_16x16x128_f8f6f4 v[42:45], v[26:33], v[218:225], v[42:45]
	v_mfma_f32_16x16x128_f8f6f4 v[102:105], v[2:9], v[194:201], v[102:105]
	v_mfma_f32_16x16x128_f8f6f4 v[98:101], v[10:17], v[194:201], v[98:101]
	v_mfma_f32_16x16x128_f8f6f4 v[70:73], v[2:9], v[202:209], v[70:73]
	v_mfma_f32_16x16x128_f8f6f4 v[66:69], v[10:17], v[202:209], v[66:69]
	v_mfma_f32_16x16x128_f8f6f4 v[54:57], v[2:9], v[210:217], v[54:57]
	v_mfma_f32_16x16x128_f8f6f4 v[50:53], v[10:17], v[210:217], v[50:53]
	v_mfma_f32_16x16x128_f8f6f4 v[38:41], v[2:9], v[218:225], v[38:41]
	v_mfma_f32_16x16x128_f8f6f4 v[34:37], v[10:17], v[218:225], v[34:37]
	s_setprio 0
	s_barrier
	s_add_u32 s85, s56, 0x200
	s_addc_u32 s86, s57, 0
	s_add_u32 s10, s58, 0x80180
	s_addc_u32 s11, s59, 0
	.p2align	6

.LBB0_1033:
	s_ashr_i32 s49, s48, 31
	ds_read_b128 v[2:5], v188
	ds_read_b128 v[6:9], v188 offset:1024
	ds_read_b128 v[10:13], v188 offset:2048
	ds_read_b128 v[14:17], v188 offset:3072
	ds_read_b128 v[18:21], v189
	ds_read_b128 v[22:25], v189 offset:1024
	ds_read_b128 v[26:29], v189 offset:2048
	ds_read_b128 v[30:33], v189 offset:3072
	s_lshl_b64 s[8:9], s[48:49], 18
	s_add_u32 s50, s19, s8
	s_addc_u32 s51, s24, s9
	s_and_b64 s[8:9], s[4:5], exec
	s_cselect_b32 s49, s51, s59
	s_cselect_b32 s75, s50, s58
	s_ashr_i32 s47, s46, 31
	s_lshl_b64 s[8:9], s[46:47], 18
	s_add_u32 s52, s25, s8
	s_addc_u32 s53, s26, s9
	s_and_b64 s[8:9], s[4:5], exec
	s_cselect_b32 s47, s53, s57
	s_cselect_b32 s76, s52, s56
	s_add_u32 s8, s58, 0x20080
	s_addc_u32 s9, s59, 0
	s_add_i32 s77, s55, 0xc000
	v_lshl_add_u64 v[34:35], s[8:9], 0, v[168:169]
	s_mov_b32 m0, s77
	s_add_i32 s78, s55, 0xe000
	ds_read_b128 v[38:41], v190
	ds_read_b128 v[42:45], v190 offset:1024
	ds_read_b128 v[46:49], v190 offset:2048
	ds_read_b128 v[50:53], v190 offset:3072
	ds_read_b128 v[54:57], v190 offset:4096
	ds_read_b128 v[58:61], v190 offset:5120
	ds_read_b128 v[62:65], v190 offset:6144
	ds_read_b128 v[66:69], v190 offset:7168
	global_load_lds_dwordx4 v[34:35], off
	v_lshl_add_u64 v[34:35], s[8:9], 0, v[164:165]
	s_mov_b32 m0, s78
	s_nop 0
	global_load_lds_dwordx4 v[34:35], off
	s_waitcnt vmcnt(24)
	s_waitcnt lgkmcnt(0)
	s_setprio 1
	s_barrier
	s_mov_b32 s8, 0
	s_mov_b32 s10, s8
	s_mov_b32 s11, s8
	s_mov_b32 s9, s8
	v_mov_b64_e32 v[36:37], s[10:11]
	v_mov_b64_e32 v[160:161], s[10:11]
	v_mov_b64_e32 v[156:157], s[10:11]
	v_mov_b64_e32 v[144:145], s[10:11]
	v_mov_b64_e32 v[140:141], s[10:11]
	v_mov_b64_e32 v[128:129], s[10:11]
	v_mov_b64_e32 v[120:121], s[10:11]
	v_mov_b64_e32 v[92:93], s[10:11]
	v_mov_b64_e32 v[84:85], s[10:11]
	v_mov_b64_e32 v[34:35], s[8:9]
	v_mov_b64_e32 v[158:159], s[8:9]
	v_mov_b64_e32 v[154:155], s[8:9]
	v_mov_b64_e32 v[142:143], s[8:9]
	v_mov_b64_e32 v[138:139], s[8:9]
	v_mov_b64_e32 v[126:127], s[8:9]
	v_mov_b64_e32 v[118:119], s[8:9]
	v_mov_b64_e32 v[90:91], s[8:9]
	v_mov_b64_e32 v[82:83], s[8:9]
	s_waitcnt lgkmcnt(0)
	v_mfma_f32_16x16x128_f8f6f4 v[158:161], v[2:9], v[38:45], v[158:161]
	v_mfma_f32_16x16x128_f8f6f4 v[154:157], v[10:17], v[38:45], v[154:157]
	v_mfma_f32_16x16x128_f8f6f4 v[142:145], v[2:9], v[46:53], v[142:145]
	v_mfma_f32_16x16x128_f8f6f4 v[138:141], v[10:17], v[46:53], v[138:141]
	v_mfma_f32_16x16x128_f8f6f4 v[126:129], v[2:9], v[54:61], v[126:129]
	v_mfma_f32_16x16x128_f8f6f4 v[118:121], v[10:17], v[54:61], v[118:121]
	v_mfma_f32_16x16x128_f8f6f4 v[90:93], v[2:9], v[62:69], v[90:93]
	v_mfma_f32_16x16x128_f8f6f4 v[82:85], v[10:17], v[62:69], v[82:85]
	v_mov_b64_e32 v[152:153], s[10:11]
	v_mov_b64_e32 v[148:149], s[10:11]
	v_mov_b64_e32 v[136:137], s[10:11]
	v_mov_b64_e32 v[132:133], s[10:11]
	v_mov_b64_e32 v[112:113], s[10:11]
	v_mov_b64_e32 v[108:109], s[10:11]
	v_mov_b64_e32 v[80:81], s[10:11]
	v_mov_b64_e32 v[76:77], s[10:11]
	v_mov_b64_e32 v[150:151], s[8:9]
	v_mov_b64_e32 v[146:147], s[8:9]
	v_mov_b64_e32 v[134:135], s[8:9]
	v_mov_b64_e32 v[130:131], s[8:9]
	v_mov_b64_e32 v[110:111], s[8:9]
	v_mov_b64_e32 v[106:107], s[8:9]
	v_mov_b64_e32 v[78:79], s[8:9]
	v_mov_b64_e32 v[74:75], s[8:9]
	v_mfma_f32_16x16x128_f8f6f4 v[150:153], v[18:25], v[38:45], v[150:153]
	v_mfma_f32_16x16x128_f8f6f4 v[146:149], v[26:33], v[38:45], v[146:149]
	v_mfma_f32_16x16x128_f8f6f4 v[134:137], v[18:25], v[46:53], v[134:137]
	v_mfma_f32_16x16x128_f8f6f4 v[130:133], v[26:33], v[46:53], v[130:133]
	v_mfma_f32_16x16x128_f8f6f4 v[110:113], v[18:25], v[54:61], v[110:113]
	v_mfma_f32_16x16x128_f8f6f4 v[106:109], v[26:33], v[54:61], v[106:109]
	v_mfma_f32_16x16x128_f8f6f4 v[78:81], v[18:25], v[62:69], v[78:81]
	v_mfma_f32_16x16x128_f8f6f4 v[74:77], v[26:33], v[62:69], v[74:77]
	s_setprio 0
	s_barrier
	s_add_i32 s9, s68, s27
	v_lshl_add_u64 v[178:179], s[56:57], 0, v[166:167]
	s_add_i32 s79, s9, 0x2000
	v_lshl_add_u64 v[38:39], v[178:179], 0, s[30:31]
	s_mov_b32 m0, s9
	v_lshl_add_u64 v[180:181], s[56:57], 0, v[162:163]
	s_add_u32 s10, s56, 0x20100
	ds_read_b128 v[50:53], v190 offset:16384
	ds_read_b128 v[54:57], v190 offset:17408
	ds_read_b128 v[192:195], v190 offset:18432
	ds_read_b128 v[196:199], v190 offset:19456
	ds_read_b128 v[200:203], v190 offset:20480
	ds_read_b128 v[204:207], v190 offset:21504
	ds_read_b128 v[208:211], v190 offset:22528
	ds_read_b128 v[212:215], v190 offset:23552
	global_load_lds_dwordx4 v[38:39], off
	v_lshl_add_u64 v[38:39], v[180:181], 0, s[30:31]
	s_mov_b32 m0, s79
	s_addc_u32 s11, s57, 0
	s_add_i32 s80, s69, s27
	global_load_lds_dwordx4 v[38:39], off
	v_lshl_add_u64 v[38:39], s[10:11], 0, v[166:167]
	s_mov_b32 m0, s80
	s_add_i32 s81, s80, 0x2000
	global_load_lds_dwordx4 v[38:39], off
	v_lshl_add_u64 v[38:39], s[10:11], 0, v[162:163]
	s_mov_b32 m0, s81
	v_lshl_add_u64 v[182:183], s[58:59], 0, v[168:169]
	global_load_lds_dwordx4 v[38:39], off
	v_lshl_add_u64 v[38:39], v[182:183], 0, s[30:31]
	s_mov_b32 m0, s55
	v_lshl_add_u64 v[184:185], s[58:59], 0, v[164:165]
	global_load_lds_dwordx4 v[38:39], off
	v_lshl_add_u64 v[38:39], v[184:185], 0, s[30:31]
	s_mov_b32 m0, s61
	s_nop 0
	global_load_lds_dwordx4 v[38:39], off
	s_waitcnt vmcnt(24)
	s_waitcnt lgkmcnt(0)
	s_setprio 1
	s_barrier
	v_mov_b64_e32 v[124:125], v[36:37]
	v_mov_b64_e32 v[116:117], v[36:37]
	v_mov_b64_e32 v[96:97], v[36:37]
	v_mov_b64_e32 v[88:89], v[36:37]
	v_mov_b64_e32 v[64:65], v[36:37]
	v_mov_b64_e32 v[60:61], v[36:37]
	v_mov_b64_e32 v[48:49], v[36:37]
	v_mov_b64_e32 v[44:45], v[36:37]
	v_mov_b64_e32 v[122:123], v[34:35]
	v_mov_b64_e32 v[114:115], v[34:35]
	v_mov_b64_e32 v[94:95], v[34:35]
	v_mov_b64_e32 v[86:87], v[34:35]
	v_mov_b64_e32 v[62:63], v[34:35]
	v_mov_b64_e32 v[58:59], v[34:35]
	v_mov_b64_e32 v[46:47], v[34:35]
	v_mov_b64_e32 v[42:43], v[34:35]
	s_waitcnt lgkmcnt(0)
	v_mfma_f32_16x16x128_f8f6f4 v[122:125], v[2:9], v[50:57], v[122:125]
	v_mfma_f32_16x16x128_f8f6f4 v[114:117], v[10:17], v[50:57], v[114:117]
	v_mfma_f32_16x16x128_f8f6f4 v[94:97], v[2:9], v[192:199], v[94:97]
	v_mfma_f32_16x16x128_f8f6f4 v[86:89], v[10:17], v[192:199], v[86:89]
	v_mfma_f32_16x16x128_f8f6f4 v[62:65], v[2:9], v[200:207], v[62:65]
	v_mfma_f32_16x16x128_f8f6f4 v[58:61], v[10:17], v[200:207], v[58:61]
	v_mfma_f32_16x16x128_f8f6f4 v[46:49], v[2:9], v[208:215], v[46:49]
	v_mfma_f32_16x16x128_f8f6f4 v[42:45], v[10:17], v[208:215], v[42:45]
	v_mov_b64_e32 v[104:105], v[36:37]
	v_mov_b64_e32 v[100:101], v[36:37]
	v_mov_b64_e32 v[102:103], v[34:35]
	v_mov_b64_e32 v[98:99], v[34:35]
	v_mfma_f32_16x16x128_f8f6f4 v[102:105], v[18:25], v[50:57], v[102:105]
	v_mfma_f32_16x16x128_f8f6f4 v[98:101], v[26:33], v[50:57], v[98:101]
	v_mov_b64_e32 v[72:73], v[36:37]
	v_mov_b64_e32 v[68:69], v[36:37]
	v_mov_b64_e32 v[56:57], v[36:37]
	v_mov_b64_e32 v[52:53], v[36:37]
	v_mov_b64_e32 v[40:41], v[36:37]
	v_mov_b64_e32 v[70:71], v[34:35]
	v_mov_b64_e32 v[66:67], v[34:35]
	v_mov_b64_e32 v[54:55], v[34:35]
	v_mov_b64_e32 v[50:51], v[34:35]
	v_mov_b64_e32 v[38:39], v[34:35]
	v_mfma_f32_16x16x128_f8f6f4 v[70:73], v[18:25], v[192:199], v[70:73]
	v_mfma_f32_16x16x128_f8f6f4 v[66:69], v[26:33], v[192:199], v[66:69]
	v_mfma_f32_16x16x128_f8f6f4 v[54:57], v[18:25], v[200:207], v[54:57]
	v_mfma_f32_16x16x128_f8f6f4 v[50:53], v[26:33], v[200:207], v[50:53]
	v_mfma_f32_16x16x128_f8f6f4 v[38:41], v[18:25], v[208:215], v[38:41]
	v_mfma_f32_16x16x128_f8f6f4 v[34:37], v[26:33], v[208:215], v[34:37]
	s_setprio 0
	s_barrier
	s_add_i32 s82, 0, 0x18000
	s_add_i32 s84, 0, 0x1c000
	v_add_u32_e32 v191, s82, v186
	v_add_u32_e32 v192, s84, v186
	ds_read_b128 v[18:21], v191
	ds_read_b128 v[22:25], v191 offset:1024
	ds_read_b128 v[26:29], v191 offset:2048
	ds_read_b128 v[30:33], v191 offset:3072
	ds_read_b128 v[2:5], v192
	ds_read_b128 v[6:9], v192 offset:1024
	ds_read_b128 v[10:13], v192 offset:2048
	ds_read_b128 v[14:17], v192 offset:3072
	s_add_u32 s10, s58, 0x20100
	s_addc_u32 s11, s59, 0
	s_mov_b32 m0, s62
	v_lshl_add_u64 v[226:227], s[10:11], 0, v[168:169]
	ds_read_b128 v[194:197], v190 offset:32768
	ds_read_b128 v[198:201], v190 offset:33792
	ds_read_b128 v[202:205], v190 offset:34816
	ds_read_b128 v[206:209], v190 offset:35840
	ds_read_b128 v[210:213], v190 offset:36864
	ds_read_b128 v[214:217], v190 offset:37888
	ds_read_b128 v[218:221], v190 offset:38912
	ds_read_b128 v[222:225], v190 offset:39936
	global_load_lds_dwordx4 v[226:227], off
	v_lshl_add_u64 v[226:227], s[10:11], 0, v[164:165]
	s_mov_b32 m0, s63
	s_nop 0
	global_load_lds_dwordx4 v[226:227], off
	s_waitcnt vmcnt(8)
	s_waitcnt lgkmcnt(0)
	s_setprio 1
	s_barrier
	v_mfma_f32_16x16x128_f8f6f4 v[158:161], v[18:25], v[194:201], v[158:161]
	v_mfma_f32_16x16x128_f8f6f4 v[154:157], v[26:33], v[194:201], v[154:157]
	v_mfma_f32_16x16x128_f8f6f4 v[142:145], v[18:25], v[202:209], v[142:145]
	v_mfma_f32_16x16x128_f8f6f4 v[138:141], v[26:33], v[202:209], v[138:141]
	v_mfma_f32_16x16x128_f8f6f4 v[126:129], v[18:25], v[210:217], v[126:129]
	v_mfma_f32_16x16x128_f8f6f4 v[118:121], v[26:33], v[210:217], v[118:121]
	v_mfma_f32_16x16x128_f8f6f4 v[90:93], v[18:25], v[218:225], v[90:93]
	v_mfma_f32_16x16x128_f8f6f4 v[82:85], v[26:33], v[218:225], v[82:85]
	v_mfma_f32_16x16x128_f8f6f4 v[150:153], v[2:9], v[194:201], v[150:153]
	v_mfma_f32_16x16x128_f8f6f4 v[146:149], v[10:17], v[194:201], v[146:149]
	v_mfma_f32_16x16x128_f8f6f4 v[134:137], v[2:9], v[202:209], v[134:137]
	v_mfma_f32_16x16x128_f8f6f4 v[130:133], v[10:17], v[202:209], v[130:133]
	v_mfma_f32_16x16x128_f8f6f4 v[110:113], v[2:9], v[210:217], v[110:113]
	v_mfma_f32_16x16x128_f8f6f4 v[106:109], v[10:17], v[210:217], v[106:109]
	v_mfma_f32_16x16x128_f8f6f4 v[78:81], v[2:9], v[218:225], v[78:81]
	v_mfma_f32_16x16x128_f8f6f4 v[74:77], v[10:17], v[218:225], v[74:77]
	s_setprio 0
	s_barrier
	s_add_i32 s82, s82, s27
	s_add_i32 s83, s82, 0x2000
	v_lshl_add_u64 v[178:179], v[178:179], 0, s[34:35]
	s_mov_b32 m0, s82
	s_add_u32 s10, s56, 0x20180
	ds_read_b128 v[194:197], v190 offset:49152
	ds_read_b128 v[198:201], v190 offset:50176
	ds_read_b128 v[202:205], v190 offset:51200
	ds_read_b128 v[206:209], v190 offset:52224
	ds_read_b128 v[210:213], v190 offset:53248
	ds_read_b128 v[214:217], v190 offset:54272
	ds_read_b128 v[218:221], v190 offset:55296
	ds_read_b128 v[222:225], v190 offset:56320
	global_load_lds_dwordx4 v[178:179], off
	v_lshl_add_u64 v[178:179], v[180:181], 0, s[34:35]
	s_mov_b32 m0, s83
	s_addc_u32 s11, s57, 0
	s_add_i32 s84, s84, s27
	global_load_lds_dwordx4 v[178:179], off
	v_lshl_add_u64 v[178:179], s[10:11], 0, v[166:167]
	s_mov_b32 m0, s84
	s_add_i32 s85, s84, 0x2000
	global_load_lds_dwordx4 v[178:179], off
	v_lshl_add_u64 v[178:179], s[10:11], 0, v[162:163]
	s_mov_b32 m0, s85
	s_nop 0
	global_load_lds_dwordx4 v[178:179], off
	v_lshl_add_u64 v[178:179], v[182:183], 0, s[34:35]
	s_mov_b32 m0, s64
	s_nop 0
	global_load_lds_dwordx4 v[178:179], off
	v_lshl_add_u64 v[178:179], v[184:185], 0, s[34:35]
	s_mov_b32 m0, s65
	s_nop 0
	global_load_lds_dwordx4 v[178:179], off
	s_waitcnt vmcnt(8)
	s_waitcnt lgkmcnt(0)
	s_setprio 1
	s_barrier
	v_mfma_f32_16x16x128_f8f6f4 v[122:125], v[18:25], v[194:201], v[122:125]
	v_mfma_f32_16x16x128_f8f6f4 v[114:117], v[26:33], v[194:201], v[114:117]
	v_mfma_f32_16x16x128_f8f6f4 v[94:97], v[18:25], v[202:209], v[94:97]
	v_mfma_f32_16x16x128_f8f6f4 v[86:89], v[26:33], v[202:209], v[86:89]
	v_mfma_f32_16x16x128_f8f6f4 v[62:65], v[18:25], v[210:217], v[62:65]
	v_mfma_f32_16x16x128_f8f6f4 v[58:61], v[26:33], v[210:217], v[58:61]
	v_mfma_f32_16x16x128_f8f6f4 v[46:49], v[18:25], v[218:225], v[46:49]
	v_mfma_f32_16x16x128_f8f6f4 v[42:45], v[26:33], v[218:225], v[42:45]
	v_mfma_f32_16x16x128_f8f6f4 v[102:105], v[2:9], v[194:201], v[102:105]
	v_mfma_f32_16x16x128_f8f6f4 v[98:101], v[10:17], v[194:201], v[98:101]
	v_mfma_f32_16x16x128_f8f6f4 v[70:73], v[2:9], v[202:209], v[70:73]
	v_mfma_f32_16x16x128_f8f6f4 v[66:69], v[10:17], v[202:209], v[66:69]
	v_mfma_f32_16x16x128_f8f6f4 v[54:57], v[2:9], v[210:217], v[54:57]
	v_mfma_f32_16x16x128_f8f6f4 v[50:53], v[10:17], v[210:217], v[50:53]
	v_mfma_f32_16x16x128_f8f6f4 v[38:41], v[2:9], v[218:225], v[38:41]
	v_mfma_f32_16x16x128_f8f6f4 v[34:37], v[10:17], v[218:225], v[34:37]
	s_setprio 0
	s_barrier
	s_add_u32 s86, s56, 0x200
	s_addc_u32 s87, s57, 0
	s_add_u32 s10, s58, 0x20180
	s_addc_u32 s11, s59, 0
	.p2align	6

.LBB0_1173:
	s_ashr_i32 s43, s42, 31
	ds_read_b128 v[2:5], v150
	ds_read_b128 v[6:9], v150 offset:1024
	ds_read_b128 v[10:13], v150 offset:2048
	ds_read_b128 v[14:17], v150 offset:3072
	ds_read_b128 v[18:21], v151
	ds_read_b128 v[22:25], v151 offset:1024
	ds_read_b128 v[26:29], v151 offset:2048
	ds_read_b128 v[30:33], v151 offset:3072
	s_lshl_b64 s[44:45], s[42:43], 21
	s_add_u32 s44, s24, s44
	s_addc_u32 s45, s25, s45
	s_and_b64 s[46:47], s[4:5], exec
	s_cselect_b32 s43, s45, s53
	s_cselect_b32 s71, s44, s52
	s_ashr_i32 s41, s40, 31
	s_lshl_b64 s[46:47], s[40:41], 21
	s_add_u32 s46, s26, s46
	s_addc_u32 s47, s27, s47
	s_and_b64 s[54:55], s[4:5], exec
	s_cselect_b32 s41, s47, s51
	s_cselect_b32 s72, s46, s50
	s_add_u32 s54, s52, 0x100080
	s_addc_u32 s55, s53, 0
	s_add_i32 s73, s49, 0xc000
	v_lshl_add_u64 v[66:67], s[54:55], 0, v[130:131]
	s_mov_b32 m0, s73
	s_add_i32 s74, s49, 0xe000
	ds_read_b128 v[34:37], v152
	ds_read_b128 v[38:41], v152 offset:1024
	ds_read_b128 v[42:45], v152 offset:2048
	ds_read_b128 v[46:49], v152 offset:3072
	ds_read_b128 v[50:53], v152 offset:4096
	ds_read_b128 v[54:57], v152 offset:5120
	ds_read_b128 v[58:61], v152 offset:6144
	ds_read_b128 v[62:65], v152 offset:7168
	global_load_lds_dwordx4 v[66:67], off
	v_lshl_add_u64 v[66:67], s[54:55], 0, v[134:135]
	s_mov_b32 m0, s74
	s_nop 0
	global_load_lds_dwordx4 v[66:67], off
	s_waitcnt vmcnt(24)
	s_waitcnt lgkmcnt(0)
	s_setprio 1
	s_barrier
	v_mfma_f32_16x16x32_bf16 v[90:93], v[2:5], v[58:61], 0
	v_mfma_f32_16x16x32_bf16 v[66:69], v[2:5], v[34:37], 0
	v_mfma_f32_16x16x32_bf16 v[70:73], v[10:13], v[34:37], 0
	v_mfma_f32_16x16x32_bf16 v[74:77], v[2:5], v[42:45], 0
	v_mfma_f32_16x16x32_bf16 v[78:81], v[10:13], v[42:45], 0
	v_mfma_f32_16x16x32_bf16 v[82:85], v[2:5], v[50:53], 0
	v_mfma_f32_16x16x32_bf16 v[86:89], v[10:13], v[50:53], 0
	v_mfma_f32_16x16x32_bf16 v[94:97], v[6:9], v[62:65], v[90:93]
	v_mfma_f32_16x16x32_bf16 v[90:93], v[10:13], v[58:61], 0
	v_mfma_f32_16x16x32_bf16 v[66:69], v[6:9], v[38:41], v[66:69]
	v_mfma_f32_16x16x32_bf16 v[126:129], v[14:17], v[38:41], v[70:73]
	v_mfma_f32_16x16x32_bf16 v[74:77], v[6:9], v[46:49], v[74:77]
	v_mfma_f32_16x16x32_bf16 v[78:81], v[14:17], v[46:49], v[78:81]
	v_mfma_f32_16x16x32_bf16 v[82:85], v[6:9], v[54:57], v[82:85]
	v_mfma_f32_16x16x32_bf16 v[86:89], v[14:17], v[54:57], v[86:89]
	v_mfma_f32_16x16x32_bf16 v[102:105], v[14:17], v[62:65], v[90:93]
	v_mfma_f32_16x16x32_bf16 v[90:93], v[18:21], v[34:37], 0
	v_mfma_f32_16x16x32_bf16 v[34:37], v[26:29], v[34:37], 0
	v_mfma_f32_16x16x32_bf16 v[110:113], v[22:25], v[38:41], v[90:93]
	v_mfma_f32_16x16x32_bf16 v[34:37], v[30:33], v[38:41], v[34:37]
	v_mfma_f32_16x16x32_bf16 v[38:41], v[18:21], v[42:45], 0
	v_mfma_f32_16x16x32_bf16 v[42:45], v[26:29], v[42:45], 0
	v_mfma_f32_16x16x32_bf16 v[38:41], v[22:25], v[46:49], v[38:41]
	v_mfma_f32_16x16x32_bf16 v[42:45], v[30:33], v[46:49], v[42:45]
	v_mfma_f32_16x16x32_bf16 v[46:49], v[18:21], v[50:53], 0
	v_mfma_f32_16x16x32_bf16 v[50:53], v[26:29], v[50:53], 0
	v_mfma_f32_16x16x32_bf16 v[46:49], v[22:25], v[54:57], v[46:49]
	v_mfma_f32_16x16x32_bf16 v[54:57], v[30:33], v[54:57], v[50:53]
	v_mfma_f32_16x16x32_bf16 v[50:53], v[18:21], v[58:61], 0
	v_mfma_f32_16x16x32_bf16 v[154:157], v[22:25], v[62:65], v[50:53]
	v_mfma_f32_16x16x32_bf16 v[50:53], v[26:29], v[58:61], 0
	v_mfma_f32_16x16x32_bf16 v[158:161], v[30:33], v[62:65], v[50:53]
	s_setprio 0
	s_barrier
	s_add_i32 s75, s64, s56
	v_lshl_add_u64 v[142:143], s[50:51], 0, v[132:133]
	s_add_i32 s76, s75, 0x2000
	v_lshl_add_u64 v[122:123], v[142:143], 0, s[14:15]
	s_mov_b32 m0, s75
	v_lshl_add_u64 v[144:145], s[50:51], 0, v[136:137]
	s_add_u32 s54, s50, 0x100100
	ds_read_b128 v[50:53], v152 offset:16384
	ds_read_b128 v[58:61], v152 offset:17408
	ds_read_b128 v[62:65], v152 offset:18432
	ds_read_b128 v[90:93], v152 offset:19456
	ds_read_b128 v[98:101], v152 offset:20480
	ds_read_b128 v[106:109], v152 offset:21504
	ds_read_b128 v[114:117], v152 offset:22528
	ds_read_b128 v[118:121], v152 offset:23552
	global_load_lds_dwordx4 v[122:123], off
	v_lshl_add_u64 v[122:123], v[144:145], 0, s[14:15]
	s_mov_b32 m0, s76
	s_addc_u32 s55, s51, 0
	s_add_i32 s77, s65, s56
	global_load_lds_dwordx4 v[122:123], off
	v_lshl_add_u64 v[122:123], s[54:55], 0, v[132:133]
	s_mov_b32 m0, s77
	s_add_i32 s78, s77, 0x2000
	global_load_lds_dwordx4 v[122:123], off
	v_lshl_add_u64 v[122:123], s[54:55], 0, v[136:137]
	s_mov_b32 m0, s78
	v_lshl_add_u64 v[148:149], s[52:53], 0, v[130:131]
	global_load_lds_dwordx4 v[122:123], off
	v_lshl_add_u64 v[122:123], v[148:149], 0, s[14:15]
	s_mov_b32 m0, s49
	v_lshl_add_u64 v[70:71], s[52:53], 0, v[134:135]
	global_load_lds_dwordx4 v[122:123], off
	v_lshl_add_u64 v[72:73], v[70:71], 0, s[14:15]
	s_mov_b32 m0, s57
	s_nop 0
	global_load_lds_dwordx4 v[72:73], off
	s_waitcnt vmcnt(24)
	s_waitcnt lgkmcnt(0)
	s_setprio 1
	s_barrier
	v_mfma_f32_16x16x32_bf16 v[122:125], v[2:5], v[50:53], 0
	v_mfma_f32_16x16x32_bf16 v[162:165], v[6:9], v[58:61], v[122:125]
	v_mfma_f32_16x16x32_bf16 v[122:125], v[10:13], v[50:53], 0
	v_mfma_f32_16x16x32_bf16 v[166:169], v[14:17], v[58:61], v[122:125]
	v_mfma_f32_16x16x32_bf16 v[122:125], v[2:5], v[62:65], 0
	v_mfma_f32_16x16x32_bf16 v[170:173], v[6:9], v[90:93], v[122:125]
	v_mfma_f32_16x16x32_bf16 v[122:125], v[10:13], v[62:65], 0
	v_mfma_f32_16x16x32_bf16 v[174:177], v[14:17], v[90:93], v[122:125]
	v_mfma_f32_16x16x32_bf16 v[122:125], v[2:5], v[98:101], 0
	v_mfma_f32_16x16x32_bf16 v[2:5], v[2:5], v[114:117], 0
	v_mfma_f32_16x16x32_bf16 v[178:181], v[6:9], v[106:109], v[122:125]
	v_mfma_f32_16x16x32_bf16 v[2:5], v[6:9], v[118:121], v[2:5]
	v_mfma_f32_16x16x32_bf16 v[6:9], v[10:13], v[114:117], 0
	v_mfma_f32_16x16x32_bf16 v[122:125], v[10:13], v[98:101], 0
	v_mfma_f32_16x16x32_bf16 v[6:9], v[14:17], v[118:121], v[6:9]
	v_mfma_f32_16x16x32_bf16 v[182:185], v[14:17], v[106:109], v[122:125]
	v_mfma_f32_16x16x32_bf16 v[14:17], v[26:29], v[50:53], 0
	v_mfma_f32_16x16x32_bf16 v[186:189], v[30:33], v[58:61], v[14:17]
	v_mfma_f32_16x16x32_bf16 v[14:17], v[18:21], v[62:65], 0
	v_mfma_f32_16x16x32_bf16 v[190:193], v[22:25], v[90:93], v[14:17]
	v_mfma_f32_16x16x32_bf16 v[14:17], v[26:29], v[62:65], 0
	v_mfma_f32_16x16x32_bf16 v[194:197], v[30:33], v[90:93], v[14:17]
	v_mfma_f32_16x16x32_bf16 v[14:17], v[18:21], v[98:101], 0
	v_mfma_f32_16x16x32_bf16 v[198:201], v[22:25], v[106:109], v[14:17]
	v_mfma_f32_16x16x32_bf16 v[14:17], v[26:29], v[98:101], 0
	v_mfma_f32_16x16x32_bf16 v[10:13], v[18:21], v[50:53], 0
	v_mfma_f32_16x16x32_bf16 v[202:205], v[30:33], v[106:109], v[14:17]
	v_mfma_f32_16x16x32_bf16 v[14:17], v[18:21], v[114:117], 0
	v_mfma_f32_16x16x32_bf16 v[10:13], v[22:25], v[58:61], v[10:13]
	v_mfma_f32_16x16x32_bf16 v[206:209], v[22:25], v[118:121], v[14:17]
	v_mfma_f32_16x16x32_bf16 v[14:17], v[26:29], v[114:117], 0
	v_mfma_f32_16x16x32_bf16 v[210:213], v[30:33], v[118:121], v[14:17]
	s_setprio 0
	s_barrier
	s_add_i32 s79, 0, 0x18000
	s_add_i32 s81, 0, 0x1c000
	v_add_u32_e32 v146, s79, v153
	v_add_u32_e32 v147, s81, v153
	s_nop 0
	ds_read_b128 v[14:17], v146
	ds_read_b128 v[18:21], v146 offset:1024
	ds_read_b128 v[26:29], v146 offset:2048
	ds_read_b128 v[214:217], v146 offset:3072
	ds_read_b128 v[218:221], v147
	ds_read_b128 v[222:225], v147 offset:1024
	ds_read_b128 v[226:229], v147 offset:2048
	ds_read_b128 v[230:233], v147 offset:3072
	s_add_u32 s54, s52, 0x100100
	s_addc_u32 s55, s53, 0
	s_mov_b32 m0, s58
	v_lshl_add_u64 v[50:51], s[54:55], 0, v[130:131]
	ds_read_b128 v[22:25], v152 offset:32768
	ds_read_b128 v[30:33], v152 offset:33792
	ds_read_b128 v[62:65], v152 offset:34816
	ds_read_b128 v[234:237], v152 offset:35840
	ds_read_b128 v[238:241], v152 offset:36864
	ds_read_b128 v[242:245], v152 offset:37888
	ds_read_b128 v[246:249], v152 offset:38912
	ds_read_b128 v[250:253], v152 offset:39936
	global_load_lds_dwordx4 v[50:51], off
	v_lshl_add_u64 v[50:51], s[54:55], 0, v[134:135]
	s_mov_b32 m0, s59
	s_nop 0
	global_load_lds_dwordx4 v[50:51], off
	s_waitcnt vmcnt(8)
	s_waitcnt lgkmcnt(0)
	s_setprio 1
	s_barrier
	v_mfma_f32_16x16x32_bf16 v[50:53], v[14:17], v[22:25], v[66:69]
	v_mfma_f32_16x16x32_bf16 v[122:125], v[18:21], v[30:33], v[50:53]
	v_mfma_f32_16x16x32_bf16 v[50:53], v[26:29], v[22:25], v[126:129]
	v_mfma_f32_16x16x32_bf16 v[114:117], v[214:217], v[30:33], v[50:53]
	v_mfma_f32_16x16x32_bf16 v[50:53], v[14:17], v[62:65], v[74:77]
	v_mfma_f32_16x16x32_bf16 v[106:109], v[18:21], v[234:237], v[50:53]
	v_mfma_f32_16x16x32_bf16 v[50:53], v[26:29], v[62:65], v[78:81]
	v_mfma_f32_16x16x32_bf16 v[98:101], v[214:217], v[234:237], v[50:53]
	v_mfma_f32_16x16x32_bf16 v[50:53], v[14:17], v[238:241], v[82:85]
	v_mfma_f32_16x16x32_bf16 v[90:93], v[18:21], v[242:245], v[50:53]
	v_mfma_f32_16x16x32_bf16 v[50:53], v[26:29], v[238:241], v[86:89]
	v_mfma_f32_16x16x32_bf16 v[82:85], v[214:217], v[242:245], v[50:53]
	v_mfma_f32_16x16x32_bf16 v[50:53], v[14:17], v[246:249], v[94:97]
	v_mfma_f32_16x16x32_bf16 v[58:61], v[18:21], v[250:253], v[50:53]
	v_mfma_f32_16x16x32_bf16 v[50:53], v[26:29], v[246:249], v[102:105]
	v_mfma_f32_16x16x32_bf16 v[50:53], v[214:217], v[250:253], v[50:53]
	v_mfma_f32_16x16x32_bf16 v[66:69], v[218:221], v[22:25], v[110:113]
	v_mfma_f32_16x16x32_bf16 v[22:25], v[226:229], v[22:25], v[34:37]
	v_mfma_f32_16x16x32_bf16 v[118:121], v[230:233], v[30:33], v[22:25]
	v_mfma_f32_16x16x32_bf16 v[22:25], v[218:221], v[62:65], v[38:41]
	v_mfma_f32_16x16x32_bf16 v[110:113], v[222:225], v[234:237], v[22:25]
	v_mfma_f32_16x16x32_bf16 v[22:25], v[226:229], v[62:65], v[42:45]
	v_mfma_f32_16x16x32_bf16 v[102:105], v[230:233], v[234:237], v[22:25]
	v_mfma_f32_16x16x32_bf16 v[22:25], v[218:221], v[238:241], v[46:49]
	v_mfma_f32_16x16x32_bf16 v[94:97], v[222:225], v[242:245], v[22:25]
	v_mfma_f32_16x16x32_bf16 v[22:25], v[226:229], v[238:241], v[54:57]
	v_mfma_f32_16x16x32_bf16 v[86:89], v[230:233], v[242:245], v[22:25]
	v_mfma_f32_16x16x32_bf16 v[22:25], v[218:221], v[246:249], v[154:157]
	v_mfma_f32_16x16x32_bf16 v[62:65], v[222:225], v[250:253], v[22:25]
	v_mfma_f32_16x16x32_bf16 v[22:25], v[226:229], v[246:249], v[158:161]
	v_mfma_f32_16x16x32_bf16 v[126:129], v[222:225], v[30:33], v[66:69]
	v_mfma_f32_16x16x32_bf16 v[54:57], v[230:233], v[250:253], v[22:25]
	s_setprio 0
	s_barrier
	s_add_i32 s79, s79, s56
	s_add_i32 s80, s79, 0x2000
	s_nop 1
	v_lshl_add_u64 v[22:23], v[142:143], 0, s[16:17]
	s_mov_b32 m0, s79
	s_add_u32 s54, s50, 0x100180
	ds_read_b128 v[34:37], v152 offset:49152
	ds_read_b128 v[42:45], v152 offset:50176
	ds_read_b128 v[154:157], v152 offset:51200
	ds_read_b128 v[158:161], v152 offset:52224
	ds_read_b128 v[234:237], v152 offset:53248
	ds_read_b128 v[238:241], v152 offset:54272
	ds_read_b128 v[242:245], v152 offset:55296
	ds_read_b128 v[246:249], v152 offset:56320
	global_load_lds_dwordx4 v[22:23], off
	v_lshl_add_u64 v[22:23], v[144:145], 0, s[16:17]
	s_mov_b32 m0, s80
	s_addc_u32 s55, s51, 0
	s_add_i32 s81, s81, s56
	global_load_lds_dwordx4 v[22:23], off
	v_lshl_add_u64 v[22:23], s[54:55], 0, v[132:133]
	s_mov_b32 m0, s81
	s_add_i32 s82, s81, 0x2000
	global_load_lds_dwordx4 v[22:23], off
	v_lshl_add_u64 v[22:23], s[54:55], 0, v[136:137]
	s_mov_b32 m0, s82
	s_nop 0
	global_load_lds_dwordx4 v[22:23], off
	v_lshl_add_u64 v[22:23], v[148:149], 0, s[16:17]
	s_mov_b32 m0, s61
	s_nop 0
	global_load_lds_dwordx4 v[22:23], off
	v_lshl_add_u64 v[22:23], v[70:71], 0, s[16:17]
	s_mov_b32 m0, s62
	s_nop 0
	global_load_lds_dwordx4 v[22:23], off
	s_waitcnt vmcnt(8)
	s_waitcnt lgkmcnt(0)
	s_setprio 1
	s_barrier
	v_mfma_f32_16x16x32_bf16 v[22:25], v[14:17], v[34:37], v[162:165]
	v_mfma_f32_16x16x32_bf16 v[78:81], v[18:21], v[42:45], v[22:25]
	v_mfma_f32_16x16x32_bf16 v[22:25], v[26:29], v[34:37], v[166:169]
	v_mfma_f32_16x16x32_bf16 v[70:73], v[214:217], v[42:45], v[22:25]
	v_mfma_f32_16x16x32_bf16 v[22:25], v[14:17], v[154:157], v[170:173]
	v_mfma_f32_16x16x32_bf16 v[46:49], v[18:21], v[158:161], v[22:25]
	v_mfma_f32_16x16x32_bf16 v[22:25], v[26:29], v[154:157], v[174:177]
	v_mfma_f32_16x16x32_bf16 v[38:41], v[214:217], v[158:161], v[22:25]
	v_mfma_f32_16x16x32_bf16 v[22:25], v[14:17], v[234:237], v[178:181]
	v_mfma_f32_16x16x32_bf16 v[2:5], v[14:17], v[242:245], v[2:5]
	v_mfma_f32_16x16x32_bf16 v[30:33], v[18:21], v[238:241], v[22:25]
	v_mfma_f32_16x16x32_bf16 v[22:25], v[26:29], v[234:237], v[182:185]
	v_mfma_f32_16x16x32_bf16 v[14:17], v[18:21], v[246:249], v[2:5]
	v_mfma_f32_16x16x32_bf16 v[2:5], v[26:29], v[242:245], v[6:9]
	v_mfma_f32_16x16x32_bf16 v[22:25], v[214:217], v[238:241], v[22:25]
	v_mfma_f32_16x16x32_bf16 v[6:9], v[214:217], v[246:249], v[2:5]
	v_mfma_f32_16x16x32_bf16 v[2:5], v[218:221], v[34:37], v[10:13]
	v_mfma_f32_16x16x32_bf16 v[74:77], v[222:225], v[42:45], v[2:5]
	v_mfma_f32_16x16x32_bf16 v[2:5], v[226:229], v[34:37], v[186:189]
	v_mfma_f32_16x16x32_bf16 v[66:69], v[230:233], v[42:45], v[2:5]
	v_mfma_f32_16x16x32_bf16 v[2:5], v[218:221], v[154:157], v[190:193]
	v_mfma_f32_16x16x32_bf16 v[42:45], v[222:225], v[158:161], v[2:5]
	v_mfma_f32_16x16x32_bf16 v[2:5], v[226:229], v[154:157], v[194:197]
	v_mfma_f32_16x16x32_bf16 v[34:37], v[230:233], v[158:161], v[2:5]
	v_mfma_f32_16x16x32_bf16 v[2:5], v[218:221], v[234:237], v[198:201]
	v_mfma_f32_16x16x32_bf16 v[26:29], v[222:225], v[238:241], v[2:5]
	v_mfma_f32_16x16x32_bf16 v[2:5], v[226:229], v[234:237], v[202:205]
	v_mfma_f32_16x16x32_bf16 v[18:21], v[230:233], v[238:241], v[2:5]
	v_mfma_f32_16x16x32_bf16 v[2:5], v[218:221], v[242:245], v[206:209]
	v_mfma_f32_16x16x32_bf16 v[10:13], v[222:225], v[246:249], v[2:5]
	v_mfma_f32_16x16x32_bf16 v[2:5], v[226:229], v[242:245], v[210:213]
	v_mfma_f32_16x16x32_bf16 v[2:5], v[230:233], v[246:249], v[2:5]
	s_setprio 0
	s_barrier
	s_add_u32 s83, s50, 0x200
	s_addc_u32 s84, s51, 0
	s_add_u32 s50, s52, 0x100180
	s_addc_u32 s51, s53, 0
	s_mov_b32 s85, 0
	.p2align	6

.LBB0_1327:
	s_ashr_i32 s43, s42, 31
	ds_read_b128 v[2:5], v150
	ds_read_b128 v[6:9], v150 offset:1024
	ds_read_b128 v[10:13], v150 offset:2048
	ds_read_b128 v[14:17], v150 offset:3072
	ds_read_b128 v[18:21], v151
	ds_read_b128 v[22:25], v151 offset:1024
	ds_read_b128 v[26:29], v151 offset:2048
	ds_read_b128 v[30:33], v151 offset:3072
	s_lshl_b64 s[44:45], s[42:43], 21
	s_add_u32 s44, s24, s44
	s_addc_u32 s45, s25, s45
	s_and_b64 s[46:47], s[4:5], exec
	s_cselect_b32 s43, s45, s53
	s_cselect_b32 s71, s44, s52
	s_ashr_i32 s41, s40, 31
	s_lshl_b64 s[46:47], s[40:41], 21
	s_add_u32 s46, s26, s46
	s_addc_u32 s47, s27, s47
	s_and_b64 s[54:55], s[4:5], exec
	s_cselect_b32 s41, s47, s51
	s_cselect_b32 s72, s46, s50
	s_add_u32 s54, s52, 0x100080
	s_addc_u32 s55, s53, 0
	s_add_i32 s73, s49, 0xc000
	v_lshl_add_u64 v[66:67], s[54:55], 0, v[130:131]
	s_mov_b32 m0, s73
	s_add_i32 s74, s49, 0xe000
	ds_read_b128 v[34:37], v152
	ds_read_b128 v[38:41], v152 offset:1024
	ds_read_b128 v[42:45], v152 offset:2048
	ds_read_b128 v[46:49], v152 offset:3072
	ds_read_b128 v[50:53], v152 offset:4096
	ds_read_b128 v[54:57], v152 offset:5120
	ds_read_b128 v[58:61], v152 offset:6144
	ds_read_b128 v[62:65], v152 offset:7168
	global_load_lds_dwordx4 v[66:67], off
	v_lshl_add_u64 v[66:67], s[54:55], 0, v[134:135]
	s_mov_b32 m0, s74
	s_nop 0
	global_load_lds_dwordx4 v[66:67], off
	s_waitcnt vmcnt(24)
	s_waitcnt lgkmcnt(0)
	s_setprio 1
	s_barrier
	v_mfma_f32_16x16x32_bf16 v[90:93], v[2:5], v[58:61], 0
	v_mfma_f32_16x16x32_bf16 v[66:69], v[2:5], v[34:37], 0
	v_mfma_f32_16x16x32_bf16 v[70:73], v[10:13], v[34:37], 0
	v_mfma_f32_16x16x32_bf16 v[74:77], v[2:5], v[42:45], 0
	v_mfma_f32_16x16x32_bf16 v[78:81], v[10:13], v[42:45], 0
	v_mfma_f32_16x16x32_bf16 v[82:85], v[2:5], v[50:53], 0
	v_mfma_f32_16x16x32_bf16 v[86:89], v[10:13], v[50:53], 0
	v_mfma_f32_16x16x32_bf16 v[94:97], v[6:9], v[62:65], v[90:93]
	v_mfma_f32_16x16x32_bf16 v[90:93], v[10:13], v[58:61], 0
	v_mfma_f32_16x16x32_bf16 v[66:69], v[6:9], v[38:41], v[66:69]
	v_mfma_f32_16x16x32_bf16 v[126:129], v[14:17], v[38:41], v[70:73]
	v_mfma_f32_16x16x32_bf16 v[74:77], v[6:9], v[46:49], v[74:77]
	v_mfma_f32_16x16x32_bf16 v[78:81], v[14:17], v[46:49], v[78:81]
	v_mfma_f32_16x16x32_bf16 v[82:85], v[6:9], v[54:57], v[82:85]
	v_mfma_f32_16x16x32_bf16 v[86:89], v[14:17], v[54:57], v[86:89]
	v_mfma_f32_16x16x32_bf16 v[102:105], v[14:17], v[62:65], v[90:93]
	v_mfma_f32_16x16x32_bf16 v[90:93], v[18:21], v[34:37], 0
	v_mfma_f32_16x16x32_bf16 v[34:37], v[26:29], v[34:37], 0
	v_mfma_f32_16x16x32_bf16 v[110:113], v[22:25], v[38:41], v[90:93]
	v_mfma_f32_16x16x32_bf16 v[34:37], v[30:33], v[38:41], v[34:37]
	v_mfma_f32_16x16x32_bf16 v[38:41], v[18:21], v[42:45], 0
	v_mfma_f32_16x16x32_bf16 v[42:45], v[26:29], v[42:45], 0
	v_mfma_f32_16x16x32_bf16 v[38:41], v[22:25], v[46:49], v[38:41]
	v_mfma_f32_16x16x32_bf16 v[42:45], v[30:33], v[46:49], v[42:45]
	v_mfma_f32_16x16x32_bf16 v[46:49], v[18:21], v[50:53], 0
	v_mfma_f32_16x16x32_bf16 v[50:53], v[26:29], v[50:53], 0
	v_mfma_f32_16x16x32_bf16 v[46:49], v[22:25], v[54:57], v[46:49]
	v_mfma_f32_16x16x32_bf16 v[54:57], v[30:33], v[54:57], v[50:53]
	v_mfma_f32_16x16x32_bf16 v[50:53], v[18:21], v[58:61], 0
	v_mfma_f32_16x16x32_bf16 v[154:157], v[22:25], v[62:65], v[50:53]
	v_mfma_f32_16x16x32_bf16 v[50:53], v[26:29], v[58:61], 0
	v_mfma_f32_16x16x32_bf16 v[158:161], v[30:33], v[62:65], v[50:53]
	s_setprio 0
	s_barrier
	s_add_i32 s75, s64, s56
	v_lshl_add_u64 v[142:143], s[50:51], 0, v[132:133]
	s_add_i32 s76, s75, 0x2000
	v_lshl_add_u64 v[122:123], v[142:143], 0, s[16:17]
	s_mov_b32 m0, s75
	v_lshl_add_u64 v[144:145], s[50:51], 0, v[136:137]
	s_add_u32 s54, s50, 0x100100
	ds_read_b128 v[50:53], v152 offset:16384
	ds_read_b128 v[58:61], v152 offset:17408
	ds_read_b128 v[62:65], v152 offset:18432
	ds_read_b128 v[90:93], v152 offset:19456
	ds_read_b128 v[98:101], v152 offset:20480
	ds_read_b128 v[106:109], v152 offset:21504
	ds_read_b128 v[114:117], v152 offset:22528
	ds_read_b128 v[118:121], v152 offset:23552
	global_load_lds_dwordx4 v[122:123], off
	v_lshl_add_u64 v[122:123], v[144:145], 0, s[16:17]
	s_mov_b32 m0, s76
	s_addc_u32 s55, s51, 0
	s_add_i32 s77, s65, s56
	global_load_lds_dwordx4 v[122:123], off
	v_lshl_add_u64 v[122:123], s[54:55], 0, v[132:133]
	s_mov_b32 m0, s77
	s_add_i32 s78, s77, 0x2000
	global_load_lds_dwordx4 v[122:123], off
	v_lshl_add_u64 v[122:123], s[54:55], 0, v[136:137]
	s_mov_b32 m0, s78
	v_lshl_add_u64 v[148:149], s[52:53], 0, v[130:131]
	global_load_lds_dwordx4 v[122:123], off
	v_lshl_add_u64 v[122:123], v[148:149], 0, s[16:17]
	s_mov_b32 m0, s49
	v_lshl_add_u64 v[70:71], s[52:53], 0, v[134:135]
	global_load_lds_dwordx4 v[122:123], off
	v_lshl_add_u64 v[72:73], v[70:71], 0, s[16:17]
	s_mov_b32 m0, s57
	s_nop 0
	global_load_lds_dwordx4 v[72:73], off
	s_waitcnt vmcnt(24)
	s_waitcnt lgkmcnt(0)
	s_setprio 1
	s_barrier
	v_mfma_f32_16x16x32_bf16 v[122:125], v[2:5], v[50:53], 0
	v_mfma_f32_16x16x32_bf16 v[162:165], v[6:9], v[58:61], v[122:125]
	v_mfma_f32_16x16x32_bf16 v[122:125], v[10:13], v[50:53], 0
	v_mfma_f32_16x16x32_bf16 v[166:169], v[14:17], v[58:61], v[122:125]
	v_mfma_f32_16x16x32_bf16 v[122:125], v[2:5], v[62:65], 0
	v_mfma_f32_16x16x32_bf16 v[170:173], v[6:9], v[90:93], v[122:125]
	v_mfma_f32_16x16x32_bf16 v[122:125], v[10:13], v[62:65], 0
	v_mfma_f32_16x16x32_bf16 v[174:177], v[14:17], v[90:93], v[122:125]
	v_mfma_f32_16x16x32_bf16 v[122:125], v[2:5], v[98:101], 0
	v_mfma_f32_16x16x32_bf16 v[2:5], v[2:5], v[114:117], 0
	v_mfma_f32_16x16x32_bf16 v[178:181], v[6:9], v[106:109], v[122:125]
	v_mfma_f32_16x16x32_bf16 v[2:5], v[6:9], v[118:121], v[2:5]
	v_mfma_f32_16x16x32_bf16 v[6:9], v[10:13], v[114:117], 0
	v_mfma_f32_16x16x32_bf16 v[122:125], v[10:13], v[98:101], 0
	v_mfma_f32_16x16x32_bf16 v[6:9], v[14:17], v[118:121], v[6:9]
	v_mfma_f32_16x16x32_bf16 v[182:185], v[14:17], v[106:109], v[122:125]
	v_mfma_f32_16x16x32_bf16 v[14:17], v[26:29], v[50:53], 0
	v_mfma_f32_16x16x32_bf16 v[186:189], v[30:33], v[58:61], v[14:17]
	v_mfma_f32_16x16x32_bf16 v[14:17], v[18:21], v[62:65], 0
	v_mfma_f32_16x16x32_bf16 v[190:193], v[22:25], v[90:93], v[14:17]
	v_mfma_f32_16x16x32_bf16 v[14:17], v[26:29], v[62:65], 0
	v_mfma_f32_16x16x32_bf16 v[194:197], v[30:33], v[90:93], v[14:17]
	v_mfma_f32_16x16x32_bf16 v[14:17], v[18:21], v[98:101], 0
	v_mfma_f32_16x16x32_bf16 v[198:201], v[22:25], v[106:109], v[14:17]
	v_mfma_f32_16x16x32_bf16 v[14:17], v[26:29], v[98:101], 0
	v_mfma_f32_16x16x32_bf16 v[10:13], v[18:21], v[50:53], 0
	v_mfma_f32_16x16x32_bf16 v[202:205], v[30:33], v[106:109], v[14:17]
	v_mfma_f32_16x16x32_bf16 v[14:17], v[18:21], v[114:117], 0
	v_mfma_f32_16x16x32_bf16 v[10:13], v[22:25], v[58:61], v[10:13]
	v_mfma_f32_16x16x32_bf16 v[206:209], v[22:25], v[118:121], v[14:17]
	v_mfma_f32_16x16x32_bf16 v[14:17], v[26:29], v[114:117], 0
	v_mfma_f32_16x16x32_bf16 v[210:213], v[30:33], v[118:121], v[14:17]
	s_setprio 0
	s_barrier
	s_add_i32 s79, 0, 0x18000
	s_add_i32 s81, 0, 0x1c000
	v_add_u32_e32 v146, s79, v153
	v_add_u32_e32 v147, s81, v153
	s_nop 0
	ds_read_b128 v[14:17], v146
	ds_read_b128 v[18:21], v146 offset:1024
	ds_read_b128 v[26:29], v146 offset:2048
	ds_read_b128 v[214:217], v146 offset:3072
	ds_read_b128 v[218:221], v147
	ds_read_b128 v[222:225], v147 offset:1024
	ds_read_b128 v[226:229], v147 offset:2048
	ds_read_b128 v[230:233], v147 offset:3072
	s_add_u32 s54, s52, 0x100100
	s_addc_u32 s55, s53, 0
	s_mov_b32 m0, s58
	v_lshl_add_u64 v[50:51], s[54:55], 0, v[130:131]
	ds_read_b128 v[22:25], v152 offset:32768
	ds_read_b128 v[30:33], v152 offset:33792
	ds_read_b128 v[62:65], v152 offset:34816
	ds_read_b128 v[234:237], v152 offset:35840
	ds_read_b128 v[238:241], v152 offset:36864
	ds_read_b128 v[242:245], v152 offset:37888
	ds_read_b128 v[246:249], v152 offset:38912
	ds_read_b128 v[250:253], v152 offset:39936
	global_load_lds_dwordx4 v[50:51], off
	v_lshl_add_u64 v[50:51], s[54:55], 0, v[134:135]
	s_mov_b32 m0, s59
	s_nop 0
	global_load_lds_dwordx4 v[50:51], off
	s_waitcnt vmcnt(8)
	s_waitcnt lgkmcnt(0)
	s_setprio 1
	s_barrier
	v_mfma_f32_16x16x32_bf16 v[50:53], v[14:17], v[22:25], v[66:69]
	v_mfma_f32_16x16x32_bf16 v[122:125], v[18:21], v[30:33], v[50:53]
	v_mfma_f32_16x16x32_bf16 v[50:53], v[26:29], v[22:25], v[126:129]
	v_mfma_f32_16x16x32_bf16 v[114:117], v[214:217], v[30:33], v[50:53]
	v_mfma_f32_16x16x32_bf16 v[50:53], v[14:17], v[62:65], v[74:77]
	v_mfma_f32_16x16x32_bf16 v[106:109], v[18:21], v[234:237], v[50:53]
	v_mfma_f32_16x16x32_bf16 v[50:53], v[26:29], v[62:65], v[78:81]
	v_mfma_f32_16x16x32_bf16 v[98:101], v[214:217], v[234:237], v[50:53]
	v_mfma_f32_16x16x32_bf16 v[50:53], v[14:17], v[238:241], v[82:85]
	v_mfma_f32_16x16x32_bf16 v[90:93], v[18:21], v[242:245], v[50:53]
	v_mfma_f32_16x16x32_bf16 v[50:53], v[26:29], v[238:241], v[86:89]
	v_mfma_f32_16x16x32_bf16 v[82:85], v[214:217], v[242:245], v[50:53]
	v_mfma_f32_16x16x32_bf16 v[50:53], v[14:17], v[246:249], v[94:97]
	v_mfma_f32_16x16x32_bf16 v[58:61], v[18:21], v[250:253], v[50:53]
	v_mfma_f32_16x16x32_bf16 v[50:53], v[26:29], v[246:249], v[102:105]
	v_mfma_f32_16x16x32_bf16 v[50:53], v[214:217], v[250:253], v[50:53]
	v_mfma_f32_16x16x32_bf16 v[66:69], v[218:221], v[22:25], v[110:113]
	v_mfma_f32_16x16x32_bf16 v[22:25], v[226:229], v[22:25], v[34:37]
	v_mfma_f32_16x16x32_bf16 v[118:121], v[230:233], v[30:33], v[22:25]
	v_mfma_f32_16x16x32_bf16 v[22:25], v[218:221], v[62:65], v[38:41]
	v_mfma_f32_16x16x32_bf16 v[110:113], v[222:225], v[234:237], v[22:25]
	v_mfma_f32_16x16x32_bf16 v[22:25], v[226:229], v[62:65], v[42:45]
	v_mfma_f32_16x16x32_bf16 v[102:105], v[230:233], v[234:237], v[22:25]
	v_mfma_f32_16x16x32_bf16 v[22:25], v[218:221], v[238:241], v[46:49]
	v_mfma_f32_16x16x32_bf16 v[94:97], v[222:225], v[242:245], v[22:25]
	v_mfma_f32_16x16x32_bf16 v[22:25], v[226:229], v[238:241], v[54:57]
	v_mfma_f32_16x16x32_bf16 v[86:89], v[230:233], v[242:245], v[22:25]
	v_mfma_f32_16x16x32_bf16 v[22:25], v[218:221], v[246:249], v[154:157]
	v_mfma_f32_16x16x32_bf16 v[62:65], v[222:225], v[250:253], v[22:25]
	v_mfma_f32_16x16x32_bf16 v[22:25], v[226:229], v[246:249], v[158:161]
	v_mfma_f32_16x16x32_bf16 v[126:129], v[222:225], v[30:33], v[66:69]
	v_mfma_f32_16x16x32_bf16 v[54:57], v[230:233], v[250:253], v[22:25]
	s_setprio 0
	s_barrier
	s_add_i32 s79, s79, s56
	s_add_i32 s80, s79, 0x2000
	s_nop 1
	v_lshl_add_u64 v[22:23], v[142:143], 0, s[30:31]
	s_mov_b32 m0, s79
	s_add_u32 s54, s50, 0x100180
	ds_read_b128 v[34:37], v152 offset:49152
	ds_read_b128 v[42:45], v152 offset:50176
	ds_read_b128 v[154:157], v152 offset:51200
	ds_read_b128 v[158:161], v152 offset:52224
	ds_read_b128 v[234:237], v152 offset:53248
	ds_read_b128 v[238:241], v152 offset:54272
	ds_read_b128 v[242:245], v152 offset:55296
	ds_read_b128 v[246:249], v152 offset:56320
	global_load_lds_dwordx4 v[22:23], off
	v_lshl_add_u64 v[22:23], v[144:145], 0, s[30:31]
	s_mov_b32 m0, s80
	s_addc_u32 s55, s51, 0
	s_add_i32 s81, s81, s56
	global_load_lds_dwordx4 v[22:23], off
	v_lshl_add_u64 v[22:23], s[54:55], 0, v[132:133]
	s_mov_b32 m0, s81
	s_add_i32 s82, s81, 0x2000
	global_load_lds_dwordx4 v[22:23], off
	v_lshl_add_u64 v[22:23], s[54:55], 0, v[136:137]
	s_mov_b32 m0, s82
	s_nop 0
	global_load_lds_dwordx4 v[22:23], off
	v_lshl_add_u64 v[22:23], v[148:149], 0, s[30:31]
	s_mov_b32 m0, s61
	s_nop 0
	global_load_lds_dwordx4 v[22:23], off
	v_lshl_add_u64 v[22:23], v[70:71], 0, s[30:31]
	s_mov_b32 m0, s62
	s_nop 0
	global_load_lds_dwordx4 v[22:23], off
	s_waitcnt vmcnt(8)
	s_waitcnt lgkmcnt(0)
	s_setprio 1
	s_barrier
	v_mfma_f32_16x16x32_bf16 v[22:25], v[14:17], v[34:37], v[162:165]
	v_mfma_f32_16x16x32_bf16 v[78:81], v[18:21], v[42:45], v[22:25]
	v_mfma_f32_16x16x32_bf16 v[22:25], v[26:29], v[34:37], v[166:169]
	v_mfma_f32_16x16x32_bf16 v[70:73], v[214:217], v[42:45], v[22:25]
	v_mfma_f32_16x16x32_bf16 v[22:25], v[14:17], v[154:157], v[170:173]
	v_mfma_f32_16x16x32_bf16 v[46:49], v[18:21], v[158:161], v[22:25]
	v_mfma_f32_16x16x32_bf16 v[22:25], v[26:29], v[154:157], v[174:177]
	v_mfma_f32_16x16x32_bf16 v[38:41], v[214:217], v[158:161], v[22:25]
	v_mfma_f32_16x16x32_bf16 v[22:25], v[14:17], v[234:237], v[178:181]
	v_mfma_f32_16x16x32_bf16 v[2:5], v[14:17], v[242:245], v[2:5]
	v_mfma_f32_16x16x32_bf16 v[30:33], v[18:21], v[238:241], v[22:25]
	v_mfma_f32_16x16x32_bf16 v[22:25], v[26:29], v[234:237], v[182:185]
	v_mfma_f32_16x16x32_bf16 v[14:17], v[18:21], v[246:249], v[2:5]
	v_mfma_f32_16x16x32_bf16 v[2:5], v[26:29], v[242:245], v[6:9]
	v_mfma_f32_16x16x32_bf16 v[22:25], v[214:217], v[238:241], v[22:25]
	v_mfma_f32_16x16x32_bf16 v[6:9], v[214:217], v[246:249], v[2:5]
	v_mfma_f32_16x16x32_bf16 v[2:5], v[218:221], v[34:37], v[10:13]
	v_mfma_f32_16x16x32_bf16 v[74:77], v[222:225], v[42:45], v[2:5]
	v_mfma_f32_16x16x32_bf16 v[2:5], v[226:229], v[34:37], v[186:189]
	v_mfma_f32_16x16x32_bf16 v[66:69], v[230:233], v[42:45], v[2:5]
	v_mfma_f32_16x16x32_bf16 v[2:5], v[218:221], v[154:157], v[190:193]
	v_mfma_f32_16x16x32_bf16 v[42:45], v[222:225], v[158:161], v[2:5]
	v_mfma_f32_16x16x32_bf16 v[2:5], v[226:229], v[154:157], v[194:197]
	v_mfma_f32_16x16x32_bf16 v[34:37], v[230:233], v[158:161], v[2:5]
	v_mfma_f32_16x16x32_bf16 v[2:5], v[218:221], v[234:237], v[198:201]
	v_mfma_f32_16x16x32_bf16 v[26:29], v[222:225], v[238:241], v[2:5]
	v_mfma_f32_16x16x32_bf16 v[2:5], v[226:229], v[234:237], v[202:205]
	v_mfma_f32_16x16x32_bf16 v[18:21], v[230:233], v[238:241], v[2:5]
	v_mfma_f32_16x16x32_bf16 v[2:5], v[218:221], v[242:245], v[206:209]
	v_mfma_f32_16x16x32_bf16 v[10:13], v[222:225], v[246:249], v[2:5]
	v_mfma_f32_16x16x32_bf16 v[2:5], v[226:229], v[242:245], v[210:213]
	v_mfma_f32_16x16x32_bf16 v[2:5], v[230:233], v[246:249], v[2:5]
	s_setprio 0
	s_barrier
	s_add_u32 s83, s50, 0x200
	s_addc_u32 s84, s51, 0
	s_add_u32 s50, s52, 0x100180
	s_addc_u32 s51, s53, 0
	s_mov_b32 s85, 0
	.p2align	6

.LBB0_1459:
	s_ashr_i32 s49, s48, 31
	ds_read_b128 v[2:5], v188
	ds_read_b128 v[6:9], v188 offset:1024
	ds_read_b128 v[10:13], v188 offset:2048
	ds_read_b128 v[14:17], v188 offset:3072
	ds_read_b128 v[18:21], v189
	ds_read_b128 v[22:25], v189 offset:1024
	ds_read_b128 v[26:29], v189 offset:2048
	ds_read_b128 v[30:33], v189 offset:3072
	s_lshl_b64 s[8:9], s[48:49], 20
	s_add_u32 s50, s19, s8
	s_addc_u32 s51, s24, s9
	s_and_b64 s[8:9], s[4:5], exec
	s_cselect_b32 s49, s51, s59
	s_cselect_b32 s74, s50, s58
	s_ashr_i32 s47, s46, 31
	s_lshl_b64 s[8:9], s[46:47], 20
	s_add_u32 s52, s25, s8
	s_addc_u32 s53, s26, s9
	s_and_b64 s[8:9], s[4:5], exec
	s_cselect_b32 s47, s53, s57
	s_cselect_b32 s75, s52, s56
	s_add_u32 s8, s58, 0x80080
	s_addc_u32 s9, s59, 0
	s_add_i32 s76, s55, 0xc000
	v_lshl_add_u64 v[34:35], s[8:9], 0, v[168:169]
	s_mov_b32 m0, s76
	s_add_i32 s77, s55, 0xe000
	ds_read_b128 v[38:41], v190
	ds_read_b128 v[42:45], v190 offset:1024
	ds_read_b128 v[46:49], v190 offset:2048
	ds_read_b128 v[50:53], v190 offset:3072
	ds_read_b128 v[54:57], v190 offset:4096
	ds_read_b128 v[58:61], v190 offset:5120
	ds_read_b128 v[62:65], v190 offset:6144
	ds_read_b128 v[66:69], v190 offset:7168
	global_load_lds_dwordx4 v[34:35], off
	v_lshl_add_u64 v[34:35], s[8:9], 0, v[164:165]
	s_mov_b32 m0, s77
	s_nop 0
	global_load_lds_dwordx4 v[34:35], off
	s_waitcnt vmcnt(24)
	s_waitcnt lgkmcnt(0)
	s_setprio 1
	s_barrier
	s_mov_b32 s8, 0
	s_mov_b32 s10, s8
	s_mov_b32 s11, s8
	s_mov_b32 s9, s8
	v_mov_b64_e32 v[36:37], s[10:11]
	v_mov_b64_e32 v[160:161], s[10:11]
	v_mov_b64_e32 v[156:157], s[10:11]
	v_mov_b64_e32 v[144:145], s[10:11]
	v_mov_b64_e32 v[140:141], s[10:11]
	v_mov_b64_e32 v[128:129], s[10:11]
	v_mov_b64_e32 v[120:121], s[10:11]
	v_mov_b64_e32 v[92:93], s[10:11]
	v_mov_b64_e32 v[84:85], s[10:11]
	v_mov_b64_e32 v[34:35], s[8:9]
	v_mov_b64_e32 v[158:159], s[8:9]
	v_mov_b64_e32 v[154:155], s[8:9]
	v_mov_b64_e32 v[142:143], s[8:9]
	v_mov_b64_e32 v[138:139], s[8:9]
	v_mov_b64_e32 v[126:127], s[8:9]
	v_mov_b64_e32 v[118:119], s[8:9]
	v_mov_b64_e32 v[90:91], s[8:9]
	v_mov_b64_e32 v[82:83], s[8:9]
	s_waitcnt lgkmcnt(0)
	v_mfma_f32_16x16x128_f8f6f4 v[158:161], v[2:9], v[38:45], v[158:161]
	v_mfma_f32_16x16x128_f8f6f4 v[154:157], v[10:17], v[38:45], v[154:157]
	v_mfma_f32_16x16x128_f8f6f4 v[142:145], v[2:9], v[46:53], v[142:145]
	v_mfma_f32_16x16x128_f8f6f4 v[138:141], v[10:17], v[46:53], v[138:141]
	v_mfma_f32_16x16x128_f8f6f4 v[126:129], v[2:9], v[54:61], v[126:129]
	v_mfma_f32_16x16x128_f8f6f4 v[118:121], v[10:17], v[54:61], v[118:121]
	v_mfma_f32_16x16x128_f8f6f4 v[90:93], v[2:9], v[62:69], v[90:93]
	v_mfma_f32_16x16x128_f8f6f4 v[82:85], v[10:17], v[62:69], v[82:85]
	v_mov_b64_e32 v[152:153], s[10:11]
	v_mov_b64_e32 v[148:149], s[10:11]
	v_mov_b64_e32 v[136:137], s[10:11]
	v_mov_b64_e32 v[132:133], s[10:11]
	v_mov_b64_e32 v[112:113], s[10:11]
	v_mov_b64_e32 v[108:109], s[10:11]
	v_mov_b64_e32 v[80:81], s[10:11]
	v_mov_b64_e32 v[76:77], s[10:11]
	v_mov_b64_e32 v[150:151], s[8:9]
	v_mov_b64_e32 v[146:147], s[8:9]
	v_mov_b64_e32 v[134:135], s[8:9]
	v_mov_b64_e32 v[130:131], s[8:9]
	v_mov_b64_e32 v[110:111], s[8:9]
	v_mov_b64_e32 v[106:107], s[8:9]
	v_mov_b64_e32 v[78:79], s[8:9]
	v_mov_b64_e32 v[74:75], s[8:9]
	v_mfma_f32_16x16x128_f8f6f4 v[150:153], v[18:25], v[38:45], v[150:153]
	v_mfma_f32_16x16x128_f8f6f4 v[146:149], v[26:33], v[38:45], v[146:149]
	v_mfma_f32_16x16x128_f8f6f4 v[134:137], v[18:25], v[46:53], v[134:137]
	v_mfma_f32_16x16x128_f8f6f4 v[130:133], v[26:33], v[46:53], v[130:133]
	v_mfma_f32_16x16x128_f8f6f4 v[110:113], v[18:25], v[54:61], v[110:113]
	v_mfma_f32_16x16x128_f8f6f4 v[106:109], v[26:33], v[54:61], v[106:109]
	v_mfma_f32_16x16x128_f8f6f4 v[78:81], v[18:25], v[62:69], v[78:81]
	v_mfma_f32_16x16x128_f8f6f4 v[74:77], v[26:33], v[62:69], v[74:77]
	s_setprio 0
	s_barrier
	s_add_i32 s9, s67, s27
	v_lshl_add_u64 v[178:179], s[56:57], 0, v[166:167]
	s_add_i32 s78, s9, 0x2000
	v_lshl_add_u64 v[38:39], v[178:179], 0, s[34:35]
	s_mov_b32 m0, s9
	v_lshl_add_u64 v[180:181], s[56:57], 0, v[162:163]
	s_add_u32 s10, s56, 0x80100
	ds_read_b128 v[50:53], v190 offset:16384
	ds_read_b128 v[54:57], v190 offset:17408
	ds_read_b128 v[192:195], v190 offset:18432
	ds_read_b128 v[196:199], v190 offset:19456
	ds_read_b128 v[200:203], v190 offset:20480
	ds_read_b128 v[204:207], v190 offset:21504
	ds_read_b128 v[208:211], v190 offset:22528
	ds_read_b128 v[212:215], v190 offset:23552
	global_load_lds_dwordx4 v[38:39], off
	v_lshl_add_u64 v[38:39], v[180:181], 0, s[34:35]
	s_mov_b32 m0, s78
	s_addc_u32 s11, s57, 0
	s_add_i32 s79, s68, s27
	global_load_lds_dwordx4 v[38:39], off
	v_lshl_add_u64 v[38:39], s[10:11], 0, v[166:167]
	s_mov_b32 m0, s79
	s_add_i32 s80, s79, 0x2000
	global_load_lds_dwordx4 v[38:39], off
	v_lshl_add_u64 v[38:39], s[10:11], 0, v[162:163]
	s_mov_b32 m0, s80
	v_lshl_add_u64 v[182:183], s[58:59], 0, v[168:169]
	global_load_lds_dwordx4 v[38:39], off
	v_lshl_add_u64 v[38:39], v[182:183], 0, s[34:35]
	s_mov_b32 m0, s55
	v_lshl_add_u64 v[184:185], s[58:59], 0, v[164:165]
	global_load_lds_dwordx4 v[38:39], off
	v_lshl_add_u64 v[38:39], v[184:185], 0, s[34:35]
	s_mov_b32 m0, s60
	s_nop 0
	global_load_lds_dwordx4 v[38:39], off
	s_waitcnt vmcnt(24)
	s_waitcnt lgkmcnt(0)
	s_setprio 1
	s_barrier
	v_mov_b64_e32 v[124:125], v[36:37]
	v_mov_b64_e32 v[116:117], v[36:37]
	v_mov_b64_e32 v[96:97], v[36:37]
	v_mov_b64_e32 v[88:89], v[36:37]
	v_mov_b64_e32 v[64:65], v[36:37]
	v_mov_b64_e32 v[60:61], v[36:37]
	v_mov_b64_e32 v[48:49], v[36:37]
	v_mov_b64_e32 v[44:45], v[36:37]
	v_mov_b64_e32 v[122:123], v[34:35]
	v_mov_b64_e32 v[114:115], v[34:35]
	v_mov_b64_e32 v[94:95], v[34:35]
	v_mov_b64_e32 v[86:87], v[34:35]
	v_mov_b64_e32 v[62:63], v[34:35]
	v_mov_b64_e32 v[58:59], v[34:35]
	v_mov_b64_e32 v[46:47], v[34:35]
	v_mov_b64_e32 v[42:43], v[34:35]
	s_waitcnt lgkmcnt(0)
	v_mfma_f32_16x16x128_f8f6f4 v[122:125], v[2:9], v[50:57], v[122:125]
	v_mfma_f32_16x16x128_f8f6f4 v[114:117], v[10:17], v[50:57], v[114:117]
	v_mfma_f32_16x16x128_f8f6f4 v[94:97], v[2:9], v[192:199], v[94:97]
	v_mfma_f32_16x16x128_f8f6f4 v[86:89], v[10:17], v[192:199], v[86:89]
	v_mfma_f32_16x16x128_f8f6f4 v[62:65], v[2:9], v[200:207], v[62:65]
	v_mfma_f32_16x16x128_f8f6f4 v[58:61], v[10:17], v[200:207], v[58:61]
	v_mfma_f32_16x16x128_f8f6f4 v[46:49], v[2:9], v[208:215], v[46:49]
	v_mfma_f32_16x16x128_f8f6f4 v[42:45], v[10:17], v[208:215], v[42:45]
	v_mov_b64_e32 v[104:105], v[36:37]
	v_mov_b64_e32 v[100:101], v[36:37]
	v_mov_b64_e32 v[102:103], v[34:35]
	v_mov_b64_e32 v[98:99], v[34:35]
	v_mfma_f32_16x16x128_f8f6f4 v[102:105], v[18:25], v[50:57], v[102:105]
	v_mfma_f32_16x16x128_f8f6f4 v[98:101], v[26:33], v[50:57], v[98:101]
	v_mov_b64_e32 v[72:73], v[36:37]
	v_mov_b64_e32 v[68:69], v[36:37]
	v_mov_b64_e32 v[56:57], v[36:37]
	v_mov_b64_e32 v[52:53], v[36:37]
	v_mov_b64_e32 v[40:41], v[36:37]
	v_mov_b64_e32 v[70:71], v[34:35]
	v_mov_b64_e32 v[66:67], v[34:35]
	v_mov_b64_e32 v[54:55], v[34:35]
	v_mov_b64_e32 v[50:51], v[34:35]
	v_mov_b64_e32 v[38:39], v[34:35]
	v_mfma_f32_16x16x128_f8f6f4 v[70:73], v[18:25], v[192:199], v[70:73]
	v_mfma_f32_16x16x128_f8f6f4 v[66:69], v[26:33], v[192:199], v[66:69]
	v_mfma_f32_16x16x128_f8f6f4 v[54:57], v[18:25], v[200:207], v[54:57]
	v_mfma_f32_16x16x128_f8f6f4 v[50:53], v[26:33], v[200:207], v[50:53]
	v_mfma_f32_16x16x128_f8f6f4 v[38:41], v[18:25], v[208:215], v[38:41]
	v_mfma_f32_16x16x128_f8f6f4 v[34:37], v[26:33], v[208:215], v[34:37]
	s_setprio 0
	s_barrier
	s_add_i32 s81, 0, 0x18000
	s_add_i32 s83, 0, 0x1c000
	v_add_u32_e32 v191, s81, v186
	v_add_u32_e32 v192, s83, v186
	ds_read_b128 v[18:21], v191
	ds_read_b128 v[22:25], v191 offset:1024
	ds_read_b128 v[26:29], v191 offset:2048
	ds_read_b128 v[30:33], v191 offset:3072
	ds_read_b128 v[2:5], v192
	ds_read_b128 v[6:9], v192 offset:1024
	ds_read_b128 v[10:13], v192 offset:2048
	ds_read_b128 v[14:17], v192 offset:3072
	s_add_u32 s10, s58, 0x80100
	s_addc_u32 s11, s59, 0
	s_mov_b32 m0, s61
	v_lshl_add_u64 v[226:227], s[10:11], 0, v[168:169]
	ds_read_b128 v[194:197], v190 offset:32768
	ds_read_b128 v[198:201], v190 offset:33792
	ds_read_b128 v[202:205], v190 offset:34816
	ds_read_b128 v[206:209], v190 offset:35840
	ds_read_b128 v[210:213], v190 offset:36864
	ds_read_b128 v[214:217], v190 offset:37888
	ds_read_b128 v[218:221], v190 offset:38912
	ds_read_b128 v[222:225], v190 offset:39936
	global_load_lds_dwordx4 v[226:227], off
	v_lshl_add_u64 v[226:227], s[10:11], 0, v[164:165]
	s_mov_b32 m0, s62
	s_nop 0
	global_load_lds_dwordx4 v[226:227], off
	s_waitcnt vmcnt(8)
	s_waitcnt lgkmcnt(0)
	s_setprio 1
	s_barrier
	v_mfma_f32_16x16x128_f8f6f4 v[158:161], v[18:25], v[194:201], v[158:161]
	v_mfma_f32_16x16x128_f8f6f4 v[154:157], v[26:33], v[194:201], v[154:157]
	v_mfma_f32_16x16x128_f8f6f4 v[142:145], v[18:25], v[202:209], v[142:145]
	v_mfma_f32_16x16x128_f8f6f4 v[138:141], v[26:33], v[202:209], v[138:141]
	v_mfma_f32_16x16x128_f8f6f4 v[126:129], v[18:25], v[210:217], v[126:129]
	v_mfma_f32_16x16x128_f8f6f4 v[118:121], v[26:33], v[210:217], v[118:121]
	v_mfma_f32_16x16x128_f8f6f4 v[90:93], v[18:25], v[218:225], v[90:93]
	v_mfma_f32_16x16x128_f8f6f4 v[82:85], v[26:33], v[218:225], v[82:85]
	v_mfma_f32_16x16x128_f8f6f4 v[150:153], v[2:9], v[194:201], v[150:153]
	v_mfma_f32_16x16x128_f8f6f4 v[146:149], v[10:17], v[194:201], v[146:149]
	v_mfma_f32_16x16x128_f8f6f4 v[134:137], v[2:9], v[202:209], v[134:137]
	v_mfma_f32_16x16x128_f8f6f4 v[130:133], v[10:17], v[202:209], v[130:133]
	v_mfma_f32_16x16x128_f8f6f4 v[110:113], v[2:9], v[210:217], v[110:113]
	v_mfma_f32_16x16x128_f8f6f4 v[106:109], v[10:17], v[210:217], v[106:109]
	v_mfma_f32_16x16x128_f8f6f4 v[78:81], v[2:9], v[218:225], v[78:81]
	v_mfma_f32_16x16x128_f8f6f4 v[74:77], v[10:17], v[218:225], v[74:77]
	s_setprio 0
	s_barrier
	s_add_i32 s81, s81, s27
	s_add_i32 s82, s81, 0x2000
	v_lshl_add_u64 v[178:179], v[178:179], 0, s[36:37]
	s_mov_b32 m0, s81
	s_add_u32 s10, s56, 0x80180
	ds_read_b128 v[194:197], v190 offset:49152
	ds_read_b128 v[198:201], v190 offset:50176
	ds_read_b128 v[202:205], v190 offset:51200
	ds_read_b128 v[206:209], v190 offset:52224
	ds_read_b128 v[210:213], v190 offset:53248
	ds_read_b128 v[214:217], v190 offset:54272
	ds_read_b128 v[218:221], v190 offset:55296
	ds_read_b128 v[222:225], v190 offset:56320
	global_load_lds_dwordx4 v[178:179], off
	v_lshl_add_u64 v[178:179], v[180:181], 0, s[36:37]
	s_mov_b32 m0, s82
	s_addc_u32 s11, s57, 0
	s_add_i32 s83, s83, s27
	global_load_lds_dwordx4 v[178:179], off
	v_lshl_add_u64 v[178:179], s[10:11], 0, v[166:167]
	s_mov_b32 m0, s83
	s_add_i32 s84, s83, 0x2000
	global_load_lds_dwordx4 v[178:179], off
	v_lshl_add_u64 v[178:179], s[10:11], 0, v[162:163]
	s_mov_b32 m0, s84
	s_nop 0
	global_load_lds_dwordx4 v[178:179], off
	v_lshl_add_u64 v[178:179], v[182:183], 0, s[36:37]
	s_mov_b32 m0, s64
	s_nop 0
	global_load_lds_dwordx4 v[178:179], off
	v_lshl_add_u64 v[178:179], v[184:185], 0, s[36:37]
	s_mov_b32 m0, s65
	s_nop 0
	global_load_lds_dwordx4 v[178:179], off
	s_waitcnt vmcnt(8)
	s_waitcnt lgkmcnt(0)
	s_setprio 1
	s_barrier
	v_mfma_f32_16x16x128_f8f6f4 v[122:125], v[18:25], v[194:201], v[122:125]
	v_mfma_f32_16x16x128_f8f6f4 v[114:117], v[26:33], v[194:201], v[114:117]
	v_mfma_f32_16x16x128_f8f6f4 v[94:97], v[18:25], v[202:209], v[94:97]
	v_mfma_f32_16x16x128_f8f6f4 v[86:89], v[26:33], v[202:209], v[86:89]
	v_mfma_f32_16x16x128_f8f6f4 v[62:65], v[18:25], v[210:217], v[62:65]
	v_mfma_f32_16x16x128_f8f6f4 v[58:61], v[26:33], v[210:217], v[58:61]
	v_mfma_f32_16x16x128_f8f6f4 v[46:49], v[18:25], v[218:225], v[46:49]
	v_mfma_f32_16x16x128_f8f6f4 v[42:45], v[26:33], v[218:225], v[42:45]
	v_mfma_f32_16x16x128_f8f6f4 v[102:105], v[2:9], v[194:201], v[102:105]
	v_mfma_f32_16x16x128_f8f6f4 v[98:101], v[10:17], v[194:201], v[98:101]
	v_mfma_f32_16x16x128_f8f6f4 v[70:73], v[2:9], v[202:209], v[70:73]
	v_mfma_f32_16x16x128_f8f6f4 v[66:69], v[10:17], v[202:209], v[66:69]
	v_mfma_f32_16x16x128_f8f6f4 v[54:57], v[2:9], v[210:217], v[54:57]
	v_mfma_f32_16x16x128_f8f6f4 v[50:53], v[10:17], v[210:217], v[50:53]
	v_mfma_f32_16x16x128_f8f6f4 v[38:41], v[2:9], v[218:225], v[38:41]
	v_mfma_f32_16x16x128_f8f6f4 v[34:37], v[10:17], v[218:225], v[34:37]
	s_setprio 0
	s_barrier
	s_add_u32 s85, s56, 0x200
	s_addc_u32 s86, s57, 0
	s_add_u32 s10, s58, 0x80180
	s_addc_u32 s11, s59, 0
	.p2align	6

.LBB0_1590:
	s_ashr_i32 s49, s48, 31
	ds_read_b128 v[2:5], v188
	ds_read_b128 v[6:9], v188 offset:1024
	ds_read_b128 v[10:13], v188 offset:2048
	ds_read_b128 v[14:17], v188 offset:3072
	ds_read_b128 v[18:21], v189
	ds_read_b128 v[22:25], v189 offset:1024
	ds_read_b128 v[26:29], v189 offset:2048
	ds_read_b128 v[30:33], v189 offset:3072
	s_lshl_b64 s[8:9], s[48:49], 18
	s_add_u32 s50, s18, s8
	s_addc_u32 s51, s19, s9
	s_and_b64 s[8:9], s[4:5], exec
	s_cselect_b32 s49, s51, s59
	s_cselect_b32 s74, s50, s58
	s_ashr_i32 s47, s46, 31
	s_lshl_b64 s[8:9], s[46:47], 18
	s_add_u32 s52, s24, s8
	s_addc_u32 s53, s25, s9
	s_and_b64 s[8:9], s[4:5], exec
	s_cselect_b32 s47, s53, s57
	s_cselect_b32 s75, s52, s56
	s_add_u32 s8, s58, 0x20080
	s_addc_u32 s9, s59, 0
	s_add_i32 s76, s55, 0xc000
	v_lshl_add_u64 v[34:35], s[8:9], 0, v[168:169]
	s_mov_b32 m0, s76
	s_add_i32 s77, s55, 0xe000
	ds_read_b128 v[38:41], v190
	ds_read_b128 v[42:45], v190 offset:1024
	ds_read_b128 v[46:49], v190 offset:2048
	ds_read_b128 v[50:53], v190 offset:3072
	ds_read_b128 v[54:57], v190 offset:4096
	ds_read_b128 v[58:61], v190 offset:5120
	ds_read_b128 v[62:65], v190 offset:6144
	ds_read_b128 v[66:69], v190 offset:7168
	global_load_lds_dwordx4 v[34:35], off
	v_lshl_add_u64 v[34:35], s[8:9], 0, v[164:165]
	s_mov_b32 m0, s77
	s_nop 0
	global_load_lds_dwordx4 v[34:35], off
	s_waitcnt vmcnt(24)
	s_waitcnt lgkmcnt(0)
	s_setprio 1
	s_barrier
	s_mov_b32 s8, 0
	s_mov_b32 s10, s8
	s_mov_b32 s11, s8
	s_mov_b32 s9, s8
	v_mov_b64_e32 v[36:37], s[10:11]
	v_mov_b64_e32 v[160:161], s[10:11]
	v_mov_b64_e32 v[156:157], s[10:11]
	v_mov_b64_e32 v[144:145], s[10:11]
	v_mov_b64_e32 v[140:141], s[10:11]
	v_mov_b64_e32 v[128:129], s[10:11]
	v_mov_b64_e32 v[120:121], s[10:11]
	v_mov_b64_e32 v[92:93], s[10:11]
	v_mov_b64_e32 v[84:85], s[10:11]
	v_mov_b64_e32 v[34:35], s[8:9]
	v_mov_b64_e32 v[158:159], s[8:9]
	v_mov_b64_e32 v[154:155], s[8:9]
	v_mov_b64_e32 v[142:143], s[8:9]
	v_mov_b64_e32 v[138:139], s[8:9]
	v_mov_b64_e32 v[126:127], s[8:9]
	v_mov_b64_e32 v[118:119], s[8:9]
	v_mov_b64_e32 v[90:91], s[8:9]
	v_mov_b64_e32 v[82:83], s[8:9]
	s_waitcnt lgkmcnt(0)
	v_mfma_f32_16x16x128_f8f6f4 v[158:161], v[2:9], v[38:45], v[158:161]
	v_mfma_f32_16x16x128_f8f6f4 v[154:157], v[10:17], v[38:45], v[154:157]
	v_mfma_f32_16x16x128_f8f6f4 v[142:145], v[2:9], v[46:53], v[142:145]
	v_mfma_f32_16x16x128_f8f6f4 v[138:141], v[10:17], v[46:53], v[138:141]
	v_mfma_f32_16x16x128_f8f6f4 v[126:129], v[2:9], v[54:61], v[126:129]
	v_mfma_f32_16x16x128_f8f6f4 v[118:121], v[10:17], v[54:61], v[118:121]
	v_mfma_f32_16x16x128_f8f6f4 v[90:93], v[2:9], v[62:69], v[90:93]
	v_mfma_f32_16x16x128_f8f6f4 v[82:85], v[10:17], v[62:69], v[82:85]
	v_mov_b64_e32 v[152:153], s[10:11]
	v_mov_b64_e32 v[148:149], s[10:11]
	v_mov_b64_e32 v[136:137], s[10:11]
	v_mov_b64_e32 v[132:133], s[10:11]
	v_mov_b64_e32 v[112:113], s[10:11]
	v_mov_b64_e32 v[108:109], s[10:11]
	v_mov_b64_e32 v[80:81], s[10:11]
	v_mov_b64_e32 v[76:77], s[10:11]
	v_mov_b64_e32 v[150:151], s[8:9]
	v_mov_b64_e32 v[146:147], s[8:9]
	v_mov_b64_e32 v[134:135], s[8:9]
	v_mov_b64_e32 v[130:131], s[8:9]
	v_mov_b64_e32 v[110:111], s[8:9]
	v_mov_b64_e32 v[106:107], s[8:9]
	v_mov_b64_e32 v[78:79], s[8:9]
	v_mov_b64_e32 v[74:75], s[8:9]
	v_mfma_f32_16x16x128_f8f6f4 v[150:153], v[18:25], v[38:45], v[150:153]
	v_mfma_f32_16x16x128_f8f6f4 v[146:149], v[26:33], v[38:45], v[146:149]
	v_mfma_f32_16x16x128_f8f6f4 v[134:137], v[18:25], v[46:53], v[134:137]
	v_mfma_f32_16x16x128_f8f6f4 v[130:133], v[26:33], v[46:53], v[130:133]
	v_mfma_f32_16x16x128_f8f6f4 v[110:113], v[18:25], v[54:61], v[110:113]
	v_mfma_f32_16x16x128_f8f6f4 v[106:109], v[26:33], v[54:61], v[106:109]
	v_mfma_f32_16x16x128_f8f6f4 v[78:81], v[18:25], v[62:69], v[78:81]
	v_mfma_f32_16x16x128_f8f6f4 v[74:77], v[26:33], v[62:69], v[74:77]
	s_setprio 0
	s_barrier
	s_add_i32 s9, s67, s26
	v_lshl_add_u64 v[178:179], s[56:57], 0, v[166:167]
	s_add_i32 s78, s9, 0x2000
	v_lshl_add_u64 v[38:39], v[178:179], 0, s[30:31]
	s_mov_b32 m0, s9
	v_lshl_add_u64 v[180:181], s[56:57], 0, v[162:163]
	s_add_u32 s10, s56, 0x20100
	ds_read_b128 v[50:53], v190 offset:16384
	ds_read_b128 v[54:57], v190 offset:17408
	ds_read_b128 v[192:195], v190 offset:18432
	ds_read_b128 v[196:199], v190 offset:19456
	ds_read_b128 v[200:203], v190 offset:20480
	ds_read_b128 v[204:207], v190 offset:21504
	ds_read_b128 v[208:211], v190 offset:22528
	ds_read_b128 v[212:215], v190 offset:23552
	global_load_lds_dwordx4 v[38:39], off
	v_lshl_add_u64 v[38:39], v[180:181], 0, s[30:31]
	s_mov_b32 m0, s78
	s_addc_u32 s11, s57, 0
	s_add_i32 s79, s68, s26
	global_load_lds_dwordx4 v[38:39], off
	v_lshl_add_u64 v[38:39], s[10:11], 0, v[166:167]
	s_mov_b32 m0, s79
	s_add_i32 s80, s79, 0x2000
	global_load_lds_dwordx4 v[38:39], off
	v_lshl_add_u64 v[38:39], s[10:11], 0, v[162:163]
	s_mov_b32 m0, s80
	v_lshl_add_u64 v[182:183], s[58:59], 0, v[168:169]
	global_load_lds_dwordx4 v[38:39], off
	v_lshl_add_u64 v[38:39], v[182:183], 0, s[30:31]
	s_mov_b32 m0, s55
	v_lshl_add_u64 v[184:185], s[58:59], 0, v[164:165]
	global_load_lds_dwordx4 v[38:39], off
	v_lshl_add_u64 v[38:39], v[184:185], 0, s[30:31]
	s_mov_b32 m0, s60
	s_nop 0
	global_load_lds_dwordx4 v[38:39], off
	s_waitcnt vmcnt(24)
	s_waitcnt lgkmcnt(0)
	s_setprio 1
	s_barrier
	v_mov_b64_e32 v[124:125], v[36:37]
	v_mov_b64_e32 v[116:117], v[36:37]
	v_mov_b64_e32 v[96:97], v[36:37]
	v_mov_b64_e32 v[88:89], v[36:37]
	v_mov_b64_e32 v[64:65], v[36:37]
	v_mov_b64_e32 v[60:61], v[36:37]
	v_mov_b64_e32 v[48:49], v[36:37]
	v_mov_b64_e32 v[44:45], v[36:37]
	v_mov_b64_e32 v[122:123], v[34:35]
	v_mov_b64_e32 v[114:115], v[34:35]
	v_mov_b64_e32 v[94:95], v[34:35]
	v_mov_b64_e32 v[86:87], v[34:35]
	v_mov_b64_e32 v[62:63], v[34:35]
	v_mov_b64_e32 v[58:59], v[34:35]
	v_mov_b64_e32 v[46:47], v[34:35]
	v_mov_b64_e32 v[42:43], v[34:35]
	s_waitcnt lgkmcnt(0)
	v_mfma_f32_16x16x128_f8f6f4 v[122:125], v[2:9], v[50:57], v[122:125]
	v_mfma_f32_16x16x128_f8f6f4 v[114:117], v[10:17], v[50:57], v[114:117]
	v_mfma_f32_16x16x128_f8f6f4 v[94:97], v[2:9], v[192:199], v[94:97]
	v_mfma_f32_16x16x128_f8f6f4 v[86:89], v[10:17], v[192:199], v[86:89]
	v_mfma_f32_16x16x128_f8f6f4 v[62:65], v[2:9], v[200:207], v[62:65]
	v_mfma_f32_16x16x128_f8f6f4 v[58:61], v[10:17], v[200:207], v[58:61]
	v_mfma_f32_16x16x128_f8f6f4 v[46:49], v[2:9], v[208:215], v[46:49]
	v_mfma_f32_16x16x128_f8f6f4 v[42:45], v[10:17], v[208:215], v[42:45]
	v_mov_b64_e32 v[104:105], v[36:37]
	v_mov_b64_e32 v[100:101], v[36:37]
	v_mov_b64_e32 v[102:103], v[34:35]
	v_mov_b64_e32 v[98:99], v[34:35]
	v_mfma_f32_16x16x128_f8f6f4 v[102:105], v[18:25], v[50:57], v[102:105]
	v_mfma_f32_16x16x128_f8f6f4 v[98:101], v[26:33], v[50:57], v[98:101]
	v_mov_b64_e32 v[72:73], v[36:37]
	v_mov_b64_e32 v[68:69], v[36:37]
	v_mov_b64_e32 v[56:57], v[36:37]
	v_mov_b64_e32 v[52:53], v[36:37]
	v_mov_b64_e32 v[40:41], v[36:37]
	v_mov_b64_e32 v[70:71], v[34:35]
	v_mov_b64_e32 v[66:67], v[34:35]
	v_mov_b64_e32 v[54:55], v[34:35]
	v_mov_b64_e32 v[50:51], v[34:35]
	v_mov_b64_e32 v[38:39], v[34:35]
	v_mfma_f32_16x16x128_f8f6f4 v[70:73], v[18:25], v[192:199], v[70:73]
	v_mfma_f32_16x16x128_f8f6f4 v[66:69], v[26:33], v[192:199], v[66:69]
	v_mfma_f32_16x16x128_f8f6f4 v[54:57], v[18:25], v[200:207], v[54:57]
	v_mfma_f32_16x16x128_f8f6f4 v[50:53], v[26:33], v[200:207], v[50:53]
	v_mfma_f32_16x16x128_f8f6f4 v[38:41], v[18:25], v[208:215], v[38:41]
	v_mfma_f32_16x16x128_f8f6f4 v[34:37], v[26:33], v[208:215], v[34:37]
	s_setprio 0
	s_barrier
	s_add_i32 s81, 0, 0x18000
	s_add_i32 s83, 0, 0x1c000
	v_add_u32_e32 v191, s81, v186
	v_add_u32_e32 v192, s83, v186
	ds_read_b128 v[18:21], v191
	ds_read_b128 v[22:25], v191 offset:1024
	ds_read_b128 v[26:29], v191 offset:2048
	ds_read_b128 v[30:33], v191 offset:3072
	ds_read_b128 v[2:5], v192
	ds_read_b128 v[6:9], v192 offset:1024
	ds_read_b128 v[10:13], v192 offset:2048
	ds_read_b128 v[14:17], v192 offset:3072
	s_add_u32 s10, s58, 0x20100
	s_addc_u32 s11, s59, 0
	s_mov_b32 m0, s61
	v_lshl_add_u64 v[226:227], s[10:11], 0, v[168:169]
	ds_read_b128 v[194:197], v190 offset:32768
	ds_read_b128 v[198:201], v190 offset:33792
	ds_read_b128 v[202:205], v190 offset:34816
	ds_read_b128 v[206:209], v190 offset:35840
	ds_read_b128 v[210:213], v190 offset:36864
	ds_read_b128 v[214:217], v190 offset:37888
	ds_read_b128 v[218:221], v190 offset:38912
	ds_read_b128 v[222:225], v190 offset:39936
	global_load_lds_dwordx4 v[226:227], off
	v_lshl_add_u64 v[226:227], s[10:11], 0, v[164:165]
	s_mov_b32 m0, s62
	s_nop 0
	global_load_lds_dwordx4 v[226:227], off
	s_waitcnt vmcnt(8)
	s_waitcnt lgkmcnt(0)
	s_setprio 1
	s_barrier
	v_mfma_f32_16x16x128_f8f6f4 v[158:161], v[18:25], v[194:201], v[158:161]
	v_mfma_f32_16x16x128_f8f6f4 v[154:157], v[26:33], v[194:201], v[154:157]
	v_mfma_f32_16x16x128_f8f6f4 v[142:145], v[18:25], v[202:209], v[142:145]
	v_mfma_f32_16x16x128_f8f6f4 v[138:141], v[26:33], v[202:209], v[138:141]
	v_mfma_f32_16x16x128_f8f6f4 v[126:129], v[18:25], v[210:217], v[126:129]
	v_mfma_f32_16x16x128_f8f6f4 v[118:121], v[26:33], v[210:217], v[118:121]
	v_mfma_f32_16x16x128_f8f6f4 v[90:93], v[18:25], v[218:225], v[90:93]
	v_mfma_f32_16x16x128_f8f6f4 v[82:85], v[26:33], v[218:225], v[82:85]
	v_mfma_f32_16x16x128_f8f6f4 v[150:153], v[2:9], v[194:201], v[150:153]
	v_mfma_f32_16x16x128_f8f6f4 v[146:149], v[10:17], v[194:201], v[146:149]
	v_mfma_f32_16x16x128_f8f6f4 v[134:137], v[2:9], v[202:209], v[134:137]
	v_mfma_f32_16x16x128_f8f6f4 v[130:133], v[10:17], v[202:209], v[130:133]
	v_mfma_f32_16x16x128_f8f6f4 v[110:113], v[2:9], v[210:217], v[110:113]
	v_mfma_f32_16x16x128_f8f6f4 v[106:109], v[10:17], v[210:217], v[106:109]
	v_mfma_f32_16x16x128_f8f6f4 v[78:81], v[2:9], v[218:225], v[78:81]
	v_mfma_f32_16x16x128_f8f6f4 v[74:77], v[10:17], v[218:225], v[74:77]
	s_setprio 0
	s_barrier
	s_add_i32 s81, s81, s26
	s_add_i32 s82, s81, 0x2000
	v_lshl_add_u64 v[178:179], v[178:179], 0, s[34:35]
	s_mov_b32 m0, s81
	s_add_u32 s10, s56, 0x20180
	ds_read_b128 v[194:197], v190 offset:49152
	ds_read_b128 v[198:201], v190 offset:50176
	ds_read_b128 v[202:205], v190 offset:51200
	ds_read_b128 v[206:209], v190 offset:52224
	ds_read_b128 v[210:213], v190 offset:53248
	ds_read_b128 v[214:217], v190 offset:54272
	ds_read_b128 v[218:221], v190 offset:55296
	ds_read_b128 v[222:225], v190 offset:56320
	global_load_lds_dwordx4 v[178:179], off
	v_lshl_add_u64 v[178:179], v[180:181], 0, s[34:35]
	s_mov_b32 m0, s82
	s_addc_u32 s11, s57, 0
	s_add_i32 s83, s83, s26
	global_load_lds_dwordx4 v[178:179], off
	v_lshl_add_u64 v[178:179], s[10:11], 0, v[166:167]
	s_mov_b32 m0, s83
	s_add_i32 s84, s83, 0x2000
	global_load_lds_dwordx4 v[178:179], off
	v_lshl_add_u64 v[178:179], s[10:11], 0, v[162:163]
	s_mov_b32 m0, s84
	s_nop 0
	global_load_lds_dwordx4 v[178:179], off
	v_lshl_add_u64 v[178:179], v[182:183], 0, s[34:35]
	s_mov_b32 m0, s64
	s_nop 0
	global_load_lds_dwordx4 v[178:179], off
	v_lshl_add_u64 v[178:179], v[184:185], 0, s[34:35]
	s_mov_b32 m0, s65
	s_nop 0
	global_load_lds_dwordx4 v[178:179], off
	s_waitcnt vmcnt(8)
	s_waitcnt lgkmcnt(0)
	s_setprio 1
	s_barrier
	v_mfma_f32_16x16x128_f8f6f4 v[122:125], v[18:25], v[194:201], v[122:125]
	v_mfma_f32_16x16x128_f8f6f4 v[114:117], v[26:33], v[194:201], v[114:117]
	v_mfma_f32_16x16x128_f8f6f4 v[94:97], v[18:25], v[202:209], v[94:97]
	v_mfma_f32_16x16x128_f8f6f4 v[86:89], v[26:33], v[202:209], v[86:89]
	v_mfma_f32_16x16x128_f8f6f4 v[62:65], v[18:25], v[210:217], v[62:65]
	v_mfma_f32_16x16x128_f8f6f4 v[58:61], v[26:33], v[210:217], v[58:61]
	v_mfma_f32_16x16x128_f8f6f4 v[46:49], v[18:25], v[218:225], v[46:49]
	v_mfma_f32_16x16x128_f8f6f4 v[42:45], v[26:33], v[218:225], v[42:45]
	v_mfma_f32_16x16x128_f8f6f4 v[102:105], v[2:9], v[194:201], v[102:105]
	v_mfma_f32_16x16x128_f8f6f4 v[98:101], v[10:17], v[194:201], v[98:101]
	v_mfma_f32_16x16x128_f8f6f4 v[70:73], v[2:9], v[202:209], v[70:73]
	v_mfma_f32_16x16x128_f8f6f4 v[66:69], v[10:17], v[202:209], v[66:69]
	v_mfma_f32_16x16x128_f8f6f4 v[54:57], v[2:9], v[210:217], v[54:57]
	v_mfma_f32_16x16x128_f8f6f4 v[50:53], v[10:17], v[210:217], v[50:53]
	v_mfma_f32_16x16x128_f8f6f4 v[38:41], v[2:9], v[218:225], v[38:41]
	v_mfma_f32_16x16x128_f8f6f4 v[34:37], v[10:17], v[218:225], v[34:37]
	s_setprio 0
	s_barrier
	s_add_u32 s85, s56, 0x200
	s_addc_u32 s86, s57, 0
	s_add_u32 s10, s58, 0x20180
	s_addc_u32 s11, s59, 0
	.p2align	6
